# combo + m0 write hoisted above address add (drops s_nop 0 before 77 LDS-DMA loads)
# baseline (speedup 1.0000x reference)
.LBB0_80:
	s_add_u32 s2, s14, 0x100
	v_mov_b32_e32 v0, 0
	s_addc_u32 s8, s15, 0
	s_mov_b32 s9, -2
	v_mov_b32_e32 v1, v0
	v_mov_b32_e32 v2, v0
	v_mov_b32_e32 v3, v0
	v_mov_b32_e32 v6, v0
	s_waitcnt lgkmcnt(0)
	v_mov_b32_e32 v7, v0
	v_mov_b32_e32 v8, v0
	v_mov_b32_e32 v9, v0
	v_mov_b32_e32 v18, v0
	v_mov_b32_e32 v19, v0
	v_mov_b32_e32 v20, v0
	v_mov_b32_e32 v21, v0
	v_mov_b32_e32 v22, v0
	v_mov_b32_e32 v23, v0
	v_mov_b32_e32 v24, v0
	v_mov_b32_e32 v25, v0
	v_mov_b32_e32 v34, v0
	v_mov_b32_e32 v35, v0
	v_mov_b32_e32 v36, v0
	v_mov_b32_e32 v37, v0
	v_mov_b32_e32 v38, v0
	v_mov_b32_e32 v39, v0
	v_mov_b32_e32 v40, v0
	v_mov_b32_e32 v41, v0
	v_mov_b32_e32 v50, v0
	v_mov_b32_e32 v51, v0
	v_mov_b32_e32 v52, v0
	v_mov_b32_e32 v53, v0
	v_mov_b32_e32 v54, v0
	v_mov_b32_e32 v55, v0
	v_mov_b32_e32 v56, v0
	v_mov_b32_e32 v57, v0
	v_mov_b32_e32 v10, v0
	v_mov_b32_e32 v11, v0
	v_mov_b32_e32 v12, v0
	v_mov_b32_e32 v13, v0
	v_mov_b32_e32 v14, v0
	v_mov_b32_e32 v15, v0
	v_mov_b32_e32 v16, v0
	v_mov_b32_e32 v17, v0
	v_mov_b32_e32 v26, v0
	v_mov_b32_e32 v27, v0
	v_mov_b32_e32 v28, v0
	v_mov_b32_e32 v29, v0
	v_mov_b32_e32 v30, v0
	v_mov_b32_e32 v31, v0
	v_mov_b32_e32 v32, v0
	v_mov_b32_e32 v33, v0
	v_mov_b32_e32 v42, v0
	v_mov_b32_e32 v43, v0
	v_mov_b32_e32 v44, v0
	v_mov_b32_e32 v45, v0
	v_mov_b32_e32 v46, v0
	v_mov_b32_e32 v47, v0
	v_mov_b32_e32 v48, v0
	v_mov_b32_e32 v49, v0
	v_mov_b32_e32 v58, v0
	v_mov_b32_e32 v59, v0
	v_mov_b32_e32 v60, v0
	v_mov_b32_e32 v61, v0
	v_mov_b32_e32 v62, v0
	v_mov_b32_e32 v63, v0
	v_mov_b32_e32 v64, v0
	v_mov_b32_e32 v65, v0
	v_mov_b32_e32 v66, v0
	v_mov_b32_e32 v67, v0
	v_mov_b32_e32 v68, v0
	v_mov_b32_e32 v69, v0
	v_mov_b32_e32 v70, v0
	v_mov_b32_e32 v71, v0
	v_mov_b32_e32 v72, v0
	v_mov_b32_e32 v73, v0
	v_mov_b32_e32 v82, v0
	v_mov_b32_e32 v83, v0
	v_mov_b32_e32 v84, v0
	v_mov_b32_e32 v85, v0
	v_mov_b32_e32 v86, v0
	v_mov_b32_e32 v87, v0
	v_mov_b32_e32 v88, v0
	v_mov_b32_e32 v89, v0
	v_mov_b32_e32 v98, v0
	v_mov_b32_e32 v99, v0
	v_mov_b32_e32 v100, v0
	v_mov_b32_e32 v101, v0
	v_mov_b32_e32 v102, v0
	v_mov_b32_e32 v103, v0
	v_mov_b32_e32 v104, v0
	v_mov_b32_e32 v105, v0
	v_mov_b32_e32 v114, v0
	v_mov_b32_e32 v115, v0
	v_mov_b32_e32 v116, v0
	v_mov_b32_e32 v117, v0
	v_mov_b32_e32 v118, v0
	v_mov_b32_e32 v119, v0
	v_mov_b32_e32 v120, v0
	v_mov_b32_e32 v121, v0
	v_mov_b32_e32 v74, v0
	v_mov_b32_e32 v75, v0
	v_mov_b32_e32 v76, v0
	v_mov_b32_e32 v77, v0
	v_mov_b32_e32 v78, v0
	v_mov_b32_e32 v79, v0
	v_mov_b32_e32 v80, v0
	v_mov_b32_e32 v81, v0
	v_mov_b32_e32 v90, v0
	v_mov_b32_e32 v91, v0
	v_mov_b32_e32 v92, v0
	v_mov_b32_e32 v93, v0
	v_mov_b32_e32 v94, v0
	v_mov_b32_e32 v95, v0
	v_mov_b32_e32 v96, v0
	v_mov_b32_e32 v97, v0
	v_mov_b32_e32 v106, v0
	v_mov_b32_e32 v107, v0
	v_mov_b32_e32 v108, v0
	v_mov_b32_e32 v109, v0
	v_mov_b32_e32 v110, v0
	v_mov_b32_e32 v111, v0
	v_mov_b32_e32 v112, v0
	v_mov_b32_e32 v113, v0
	v_mov_b32_e32 v122, v0
	v_mov_b32_e32 v123, v0
	v_mov_b32_e32 v124, v0
	v_mov_b32_e32 v125, v0
	v_mov_b32_e32 v126, v0
	v_mov_b32_e32 v127, v0
	v_mov_b32_e32 v128, v0
	v_mov_b32_e32 v129, v0
	s_cmp_eq_u32 s36, 1
	s_cbranch_scc1 .LBB0_81
	s_add_u32 s14, s0, 0x100
	s_addc_u32 s15, s1, 0
	s_add_i32 s3, 0, 0x10000
	s_cmpk_eq_i32 s9, 0x7c
	s_cselect_b32 s27, s43, s15
	s_cselect_b32 s26, s42, s14
	v_add_u32_e32 v162, s3, v145
	s_cselect_b32 s23, s79, s8
	s_cselect_b32 s22, s78, s2
	s_add_i32 s4, 0, 0x14000
	ds_read_b128 v[140:143], v162
	ds_read_b128 v[148:151], v162 offset:1024
	ds_read_b128 v[172:175], v162 offset:2048
	ds_read_b128 v[190:193], v162 offset:3072
	v_add_u32_e32 v162, s4, v145
	ds_read_b128 v[194:197], v162
	ds_read_b128 v[198:201], v162 offset:1024
	ds_read_b128 v[202:205], v162 offset:2048
	ds_read_b128 v[206:209], v162 offset:3072
	v_lshl_add_u64 v[162:163], s[0:1], 0, v[136:137]
	s_add_i32 m0, s30, 0xc000
	ds_read_b128 v[210:213], v147
	ds_read_b128 v[214:217], v147 offset:1024
	ds_read_b128 v[218:221], v147 offset:2048
	ds_read_b128 v[222:225], v147 offset:3072
	ds_read_b128 v[226:229], v147 offset:4096
	ds_read_b128 v[230:233], v147 offset:5120
	ds_read_b128 v[234:237], v147 offset:6144
	ds_read_b128 v[238:241], v147 offset:7168
	global_load_lds_dwordx4 v[162:163], off
	s_add_i32 m0, s30, 0xe000
	v_lshl_add_u64 v[162:163], s[0:1], 0, v[138:139]
	global_load_lds_dwordx4 v[162:163], off
	s_waitcnt vmcnt(24)
	s_waitcnt lgkmcnt(0)
	s_barrier
	s_setprio 1
	s_waitcnt lgkmcnt(0)
	v_mfma_f32_16x16x32_bf16 v[126:129], v[140:143], v[210:213], v[126:129]
	v_mfma_f32_16x16x32_bf16 v[122:125], v[172:175], v[210:213], v[122:125]
	v_mfma_f32_16x16x32_bf16 v[110:113], v[140:143], v[218:221], v[110:113]
	v_mfma_f32_16x16x32_bf16 v[106:109], v[172:175], v[218:221], v[106:109]
	v_mfma_f32_16x16x32_bf16 v[94:97], v[140:143], v[226:229], v[94:97]
	v_mfma_f32_16x16x32_bf16 v[90:93], v[172:175], v[226:229], v[90:93]
	v_mfma_f32_16x16x32_bf16 v[78:81], v[140:143], v[234:237], v[78:81]
	v_mfma_f32_16x16x32_bf16 v[74:77], v[172:175], v[234:237], v[74:77]
	v_mfma_f32_16x16x32_bf16 v[126:129], v[148:151], v[214:217], v[126:129]
	v_mfma_f32_16x16x32_bf16 v[122:125], v[190:193], v[214:217], v[122:125]
	v_mfma_f32_16x16x32_bf16 v[110:113], v[148:151], v[222:225], v[110:113]
	v_mfma_f32_16x16x32_bf16 v[106:109], v[190:193], v[222:225], v[106:109]
	v_mfma_f32_16x16x32_bf16 v[94:97], v[148:151], v[230:233], v[94:97]
	v_mfma_f32_16x16x32_bf16 v[90:93], v[190:193], v[230:233], v[90:93]
	v_mfma_f32_16x16x32_bf16 v[78:81], v[148:151], v[238:241], v[78:81]
	v_mfma_f32_16x16x32_bf16 v[74:77], v[190:193], v[238:241], v[74:77]
	s_setprio 0
	s_setprio 1
	v_mfma_f32_16x16x32_bf16 v[118:121], v[194:197], v[210:213], v[118:121]
	v_mfma_f32_16x16x32_bf16 v[114:117], v[202:205], v[210:213], v[114:117]
	v_mfma_f32_16x16x32_bf16 v[102:105], v[194:197], v[218:221], v[102:105]
	v_mfma_f32_16x16x32_bf16 v[98:101], v[202:205], v[218:221], v[98:101]
	v_mfma_f32_16x16x32_bf16 v[86:89], v[194:197], v[226:229], v[86:89]
	v_mfma_f32_16x16x32_bf16 v[82:85], v[202:205], v[226:229], v[82:85]
	v_mfma_f32_16x16x32_bf16 v[70:73], v[194:197], v[234:237], v[70:73]
	v_mfma_f32_16x16x32_bf16 v[66:69], v[202:205], v[234:237], v[66:69]
	v_mfma_f32_16x16x32_bf16 v[118:121], v[198:201], v[214:217], v[118:121]
	v_mfma_f32_16x16x32_bf16 v[114:117], v[206:209], v[214:217], v[114:117]
	v_mfma_f32_16x16x32_bf16 v[102:105], v[198:201], v[222:225], v[102:105]
	v_mfma_f32_16x16x32_bf16 v[98:101], v[206:209], v[222:225], v[98:101]
	v_mfma_f32_16x16x32_bf16 v[86:89], v[198:201], v[230:233], v[86:89]
	v_mfma_f32_16x16x32_bf16 v[82:85], v[206:209], v[230:233], v[82:85]
	v_mfma_f32_16x16x32_bf16 v[70:73], v[198:201], v[238:241], v[70:73]
	v_mfma_f32_16x16x32_bf16 v[66:69], v[206:209], v[238:241], v[66:69]
	s_setprio 0
	s_barrier
	s_add_i32 s0, s3, s11
	v_lshl_add_u64 v[162:163], s[22:23], 0, v[4:5]
	s_mov_b32 m0, s0
	ds_read_b128 v[210:213], v147 offset:16384
	ds_read_b128 v[214:217], v147 offset:17408
	ds_read_b128 v[218:221], v147 offset:18432
	ds_read_b128 v[222:225], v147 offset:19456
	ds_read_b128 v[226:229], v147 offset:20480
	ds_read_b128 v[230:233], v147 offset:21504
	ds_read_b128 v[234:237], v147 offset:22528
	ds_read_b128 v[238:241], v147 offset:23552
	global_load_lds_dwordx4 v[162:163], off
	s_add_i32 m0, s0, 0x2000
	s_add_u32 s0, s22, 0x208000
	v_lshl_add_u64 v[166:167], s[22:23], 0, v[130:131]
	s_addc_u32 s1, s23, 0
	s_add_i32 s3, s4, s11
	global_load_lds_dwordx4 v[166:167], off
	v_lshl_add_u64 v[176:177], s[0:1], 0, v[4:5]
	s_mov_b32 m0, s3
	v_lshl_add_u64 v[180:181], s[26:27], 0, v[132:133]
	global_load_lds_dwordx4 v[176:177], off
	s_add_i32 m0, s3, 0x2000
	v_lshl_add_u64 v[176:177], s[0:1], 0, v[130:131]
	global_load_lds_dwordx4 v[176:177], off
	s_mov_b32 m0, s30
	v_lshl_add_u64 v[176:177], s[26:27], 0, v[134:135]
	global_load_lds_dwordx4 v[176:177], off
	s_mov_b32 m0, s31
	s_nop 0
	global_load_lds_dwordx4 v[180:181], off
	s_waitcnt vmcnt(24)
	s_waitcnt lgkmcnt(0)
	s_barrier
	s_setprio 1
	s_waitcnt lgkmcnt(0)
	v_mfma_f32_16x16x32_bf16 v[62:65], v[140:143], v[210:213], v[62:65]
	v_mfma_f32_16x16x32_bf16 v[58:61], v[172:175], v[210:213], v[58:61]
	v_mfma_f32_16x16x32_bf16 v[46:49], v[140:143], v[218:221], v[46:49]
	v_mfma_f32_16x16x32_bf16 v[42:45], v[172:175], v[218:221], v[42:45]
	v_mfma_f32_16x16x32_bf16 v[30:33], v[140:143], v[226:229], v[30:33]
	v_mfma_f32_16x16x32_bf16 v[26:29], v[172:175], v[226:229], v[26:29]
	v_mfma_f32_16x16x32_bf16 v[14:17], v[140:143], v[234:237], v[14:17]
	v_mfma_f32_16x16x32_bf16 v[10:13], v[172:175], v[234:237], v[10:13]
	v_mfma_f32_16x16x32_bf16 v[62:65], v[148:151], v[214:217], v[62:65]
	v_mfma_f32_16x16x32_bf16 v[58:61], v[190:193], v[214:217], v[58:61]
	v_mfma_f32_16x16x32_bf16 v[46:49], v[148:151], v[222:225], v[46:49]
	v_mfma_f32_16x16x32_bf16 v[42:45], v[190:193], v[222:225], v[42:45]
	v_mfma_f32_16x16x32_bf16 v[30:33], v[148:151], v[230:233], v[30:33]
	v_mfma_f32_16x16x32_bf16 v[26:29], v[190:193], v[230:233], v[26:29]
	v_mfma_f32_16x16x32_bf16 v[14:17], v[148:151], v[238:241], v[14:17]
	v_mfma_f32_16x16x32_bf16 v[10:13], v[190:193], v[238:241], v[10:13]
	s_setprio 0
	s_setprio 1
	v_mfma_f32_16x16x32_bf16 v[54:57], v[194:197], v[210:213], v[54:57]
	v_mfma_f32_16x16x32_bf16 v[50:53], v[202:205], v[210:213], v[50:53]
	v_mfma_f32_16x16x32_bf16 v[38:41], v[194:197], v[218:221], v[38:41]
	v_mfma_f32_16x16x32_bf16 v[34:37], v[202:205], v[218:221], v[34:37]
	v_mfma_f32_16x16x32_bf16 v[22:25], v[194:197], v[226:229], v[22:25]
	v_mfma_f32_16x16x32_bf16 v[18:21], v[202:205], v[226:229], v[18:21]
	v_mfma_f32_16x16x32_bf16 v[6:9], v[194:197], v[234:237], v[6:9]
	v_mfma_f32_16x16x32_bf16 v[0:3], v[202:205], v[234:237], v[0:3]
	v_mfma_f32_16x16x32_bf16 v[54:57], v[198:201], v[214:217], v[54:57]
	v_mfma_f32_16x16x32_bf16 v[50:53], v[206:209], v[214:217], v[50:53]
	v_mfma_f32_16x16x32_bf16 v[38:41], v[198:201], v[222:225], v[38:41]
	v_mfma_f32_16x16x32_bf16 v[34:37], v[206:209], v[222:225], v[34:37]
	v_mfma_f32_16x16x32_bf16 v[22:25], v[198:201], v[230:233], v[22:25]
	v_mfma_f32_16x16x32_bf16 v[18:21], v[206:209], v[230:233], v[18:21]
	v_mfma_f32_16x16x32_bf16 v[6:9], v[198:201], v[238:241], v[6:9]
	v_mfma_f32_16x16x32_bf16 v[0:3], v[206:209], v[238:241], v[0:3]
	s_setprio 0
	s_barrier
	s_branch .Lpeelmid_81
.LBB0_81:
	s_add_u32 s14, s0, 0x100
	s_addc_u32 s15, s1, 0
	s_add_i32 s3, 0, 0x10000
	s_cmpk_eq_i32 s9, 0x7c
	s_cselect_b32 s27, s43, s15
	s_cselect_b32 s26, s42, s14
	v_add_u32_e32 v162, s3, v145
	s_cselect_b32 s23, s79, s8
	s_cselect_b32 s22, s78, s2
	s_add_i32 s4, 0, 0x14000
	ds_read_b128 v[140:143], v162
	ds_read_b128 v[148:151], v162 offset:1024
	ds_read_b128 v[172:175], v162 offset:2048
	ds_read_b128 v[190:193], v162 offset:3072
	v_add_u32_e32 v162, s4, v145
	ds_read_b128 v[194:197], v162
	ds_read_b128 v[198:201], v162 offset:1024
	ds_read_b128 v[202:205], v162 offset:2048
	ds_read_b128 v[206:209], v162 offset:3072
	v_lshl_add_u64 v[162:163], s[0:1], 0, v[136:137]
	s_add_i32 m0, s30, 0xc000
	ds_read_b128 v[210:213], v147
	ds_read_b128 v[214:217], v147 offset:1024
	ds_read_b128 v[218:221], v147 offset:2048
	ds_read_b128 v[222:225], v147 offset:3072
	ds_read_b128 v[226:229], v147 offset:4096
	ds_read_b128 v[230:233], v147 offset:5120
	ds_read_b128 v[234:237], v147 offset:6144
	ds_read_b128 v[238:241], v147 offset:7168
	global_load_lds_dwordx4 v[162:163], off
	s_add_i32 m0, s30, 0xe000
	v_lshl_add_u64 v[162:163], s[0:1], 0, v[138:139]
	global_load_lds_dwordx4 v[162:163], off
	s_waitcnt vmcnt(8)
	s_waitcnt lgkmcnt(0)
	s_barrier
	s_setprio 1
	s_waitcnt lgkmcnt(0)
	v_mfma_f32_16x16x32_bf16 v[126:129], v[140:143], v[210:213], v[126:129]
	v_mfma_f32_16x16x32_bf16 v[122:125], v[172:175], v[210:213], v[122:125]
	v_mfma_f32_16x16x32_bf16 v[110:113], v[140:143], v[218:221], v[110:113]
	v_mfma_f32_16x16x32_bf16 v[106:109], v[172:175], v[218:221], v[106:109]
	v_mfma_f32_16x16x32_bf16 v[94:97], v[140:143], v[226:229], v[94:97]
	v_mfma_f32_16x16x32_bf16 v[90:93], v[172:175], v[226:229], v[90:93]
	v_mfma_f32_16x16x32_bf16 v[78:81], v[140:143], v[234:237], v[78:81]
	v_mfma_f32_16x16x32_bf16 v[74:77], v[172:175], v[234:237], v[74:77]
	v_mfma_f32_16x16x32_bf16 v[126:129], v[148:151], v[214:217], v[126:129]
	v_mfma_f32_16x16x32_bf16 v[122:125], v[190:193], v[214:217], v[122:125]
	v_mfma_f32_16x16x32_bf16 v[110:113], v[148:151], v[222:225], v[110:113]
	v_mfma_f32_16x16x32_bf16 v[106:109], v[190:193], v[222:225], v[106:109]
	v_mfma_f32_16x16x32_bf16 v[94:97], v[148:151], v[230:233], v[94:97]
	v_mfma_f32_16x16x32_bf16 v[90:93], v[190:193], v[230:233], v[90:93]
	v_mfma_f32_16x16x32_bf16 v[78:81], v[148:151], v[238:241], v[78:81]
	v_mfma_f32_16x16x32_bf16 v[74:77], v[190:193], v[238:241], v[74:77]
	s_setprio 0
	s_setprio 1
	v_mfma_f32_16x16x32_bf16 v[118:121], v[194:197], v[210:213], v[118:121]
	v_mfma_f32_16x16x32_bf16 v[114:117], v[202:205], v[210:213], v[114:117]
	v_mfma_f32_16x16x32_bf16 v[102:105], v[194:197], v[218:221], v[102:105]
	v_mfma_f32_16x16x32_bf16 v[98:101], v[202:205], v[218:221], v[98:101]
	v_mfma_f32_16x16x32_bf16 v[86:89], v[194:197], v[226:229], v[86:89]
	v_mfma_f32_16x16x32_bf16 v[82:85], v[202:205], v[226:229], v[82:85]
	v_mfma_f32_16x16x32_bf16 v[70:73], v[194:197], v[234:237], v[70:73]
	v_mfma_f32_16x16x32_bf16 v[66:69], v[202:205], v[234:237], v[66:69]
	v_mfma_f32_16x16x32_bf16 v[118:121], v[198:201], v[214:217], v[118:121]
	v_mfma_f32_16x16x32_bf16 v[114:117], v[206:209], v[214:217], v[114:117]
	v_mfma_f32_16x16x32_bf16 v[102:105], v[198:201], v[222:225], v[102:105]
	v_mfma_f32_16x16x32_bf16 v[98:101], v[206:209], v[222:225], v[98:101]
	v_mfma_f32_16x16x32_bf16 v[86:89], v[198:201], v[230:233], v[86:89]
	v_mfma_f32_16x16x32_bf16 v[82:85], v[206:209], v[230:233], v[82:85]
	v_mfma_f32_16x16x32_bf16 v[70:73], v[198:201], v[238:241], v[70:73]
	v_mfma_f32_16x16x32_bf16 v[66:69], v[206:209], v[238:241], v[66:69]
	s_setprio 0
	s_barrier
	s_add_i32 s0, s3, s11
	v_lshl_add_u64 v[162:163], s[22:23], 0, v[4:5]
	s_mov_b32 m0, s0
	ds_read_b128 v[210:213], v147 offset:16384
	ds_read_b128 v[214:217], v147 offset:17408
	ds_read_b128 v[218:221], v147 offset:18432
	ds_read_b128 v[222:225], v147 offset:19456
	ds_read_b128 v[226:229], v147 offset:20480
	ds_read_b128 v[230:233], v147 offset:21504
	ds_read_b128 v[234:237], v147 offset:22528
	ds_read_b128 v[238:241], v147 offset:23552
	global_load_lds_dwordx4 v[162:163], off
	s_add_i32 m0, s0, 0x2000
	s_add_u32 s0, s22, 0x208000
	v_lshl_add_u64 v[166:167], s[22:23], 0, v[130:131]
	s_addc_u32 s1, s23, 0
	s_add_i32 s3, s4, s11
	global_load_lds_dwordx4 v[166:167], off
	v_lshl_add_u64 v[176:177], s[0:1], 0, v[4:5]
	s_mov_b32 m0, s3
	v_lshl_add_u64 v[180:181], s[26:27], 0, v[132:133]
	global_load_lds_dwordx4 v[176:177], off
	s_add_i32 m0, s3, 0x2000
	v_lshl_add_u64 v[176:177], s[0:1], 0, v[130:131]
	global_load_lds_dwordx4 v[176:177], off
	s_mov_b32 m0, s30
	v_lshl_add_u64 v[176:177], s[26:27], 0, v[134:135]
	global_load_lds_dwordx4 v[176:177], off
	s_mov_b32 m0, s31
	s_nop 0
	global_load_lds_dwordx4 v[180:181], off
	s_waitcnt vmcnt(8)
	s_waitcnt lgkmcnt(0)
	s_barrier
	s_setprio 1
	s_waitcnt lgkmcnt(0)
	v_mfma_f32_16x16x32_bf16 v[62:65], v[140:143], v[210:213], v[62:65]
	v_mfma_f32_16x16x32_bf16 v[58:61], v[172:175], v[210:213], v[58:61]
	v_mfma_f32_16x16x32_bf16 v[46:49], v[140:143], v[218:221], v[46:49]
	v_mfma_f32_16x16x32_bf16 v[42:45], v[172:175], v[218:221], v[42:45]
	v_mfma_f32_16x16x32_bf16 v[30:33], v[140:143], v[226:229], v[30:33]
	v_mfma_f32_16x16x32_bf16 v[26:29], v[172:175], v[226:229], v[26:29]
	v_mfma_f32_16x16x32_bf16 v[14:17], v[140:143], v[234:237], v[14:17]
	v_mfma_f32_16x16x32_bf16 v[10:13], v[172:175], v[234:237], v[10:13]
	v_mfma_f32_16x16x32_bf16 v[62:65], v[148:151], v[214:217], v[62:65]
	v_mfma_f32_16x16x32_bf16 v[58:61], v[190:193], v[214:217], v[58:61]
	v_mfma_f32_16x16x32_bf16 v[46:49], v[148:151], v[222:225], v[46:49]
	v_mfma_f32_16x16x32_bf16 v[42:45], v[190:193], v[222:225], v[42:45]
	v_mfma_f32_16x16x32_bf16 v[30:33], v[148:151], v[230:233], v[30:33]
	v_mfma_f32_16x16x32_bf16 v[26:29], v[190:193], v[230:233], v[26:29]
	v_mfma_f32_16x16x32_bf16 v[14:17], v[148:151], v[238:241], v[14:17]
	v_mfma_f32_16x16x32_bf16 v[10:13], v[190:193], v[238:241], v[10:13]
	s_setprio 0
	s_setprio 1
	v_mfma_f32_16x16x32_bf16 v[54:57], v[194:197], v[210:213], v[54:57]
	v_mfma_f32_16x16x32_bf16 v[50:53], v[202:205], v[210:213], v[50:53]
	v_mfma_f32_16x16x32_bf16 v[38:41], v[194:197], v[218:221], v[38:41]
	v_mfma_f32_16x16x32_bf16 v[34:37], v[202:205], v[218:221], v[34:37]
	v_mfma_f32_16x16x32_bf16 v[22:25], v[194:197], v[226:229], v[22:25]
	v_mfma_f32_16x16x32_bf16 v[18:21], v[202:205], v[226:229], v[18:21]
	v_mfma_f32_16x16x32_bf16 v[6:9], v[194:197], v[234:237], v[6:9]
	v_mfma_f32_16x16x32_bf16 v[0:3], v[202:205], v[234:237], v[0:3]
	v_mfma_f32_16x16x32_bf16 v[54:57], v[198:201], v[214:217], v[54:57]
	v_mfma_f32_16x16x32_bf16 v[50:53], v[206:209], v[214:217], v[50:53]
	v_mfma_f32_16x16x32_bf16 v[38:41], v[198:201], v[222:225], v[38:41]
	v_mfma_f32_16x16x32_bf16 v[34:37], v[206:209], v[222:225], v[34:37]
	v_mfma_f32_16x16x32_bf16 v[22:25], v[198:201], v[230:233], v[22:25]
	v_mfma_f32_16x16x32_bf16 v[18:21], v[206:209], v[230:233], v[18:21]
	v_mfma_f32_16x16x32_bf16 v[6:9], v[198:201], v[238:241], v[6:9]
	v_mfma_f32_16x16x32_bf16 v[0:3], v[206:209], v[238:241], v[0:3]
	s_setprio 0
	s_barrier
.Lpeelmid_81:
	s_add_i32 s3, 0, 0x18000
	v_add_u32_e32 v164, s3, v145
	s_add_i32 s4, 0, 0x1c000
	ds_read_b128 v[140:143], v164
	ds_read_b128 v[148:151], v164 offset:1024
	ds_read_b128 v[172:175], v164 offset:2048
	ds_read_b128 v[190:193], v164 offset:3072
	v_add_u32_e32 v164, s4, v145
	ds_read_b128 v[194:197], v164
	ds_read_b128 v[198:201], v164 offset:1024
	ds_read_b128 v[202:205], v164 offset:2048
	ds_read_b128 v[206:209], v164 offset:3072
	s_add_u32 s0, s26, 0x208000
	s_addc_u32 s1, s27, 0
	s_mov_b32 m0, s34
	v_lshl_add_u64 v[242:243], s[0:1], 0, v[134:135]
	ds_read_b128 v[210:213], v147 offset:32768
	ds_read_b128 v[214:217], v147 offset:33792
	ds_read_b128 v[218:221], v147 offset:34816
	ds_read_b128 v[222:225], v147 offset:35840
	ds_read_b128 v[226:229], v147 offset:36864
	ds_read_b128 v[230:233], v147 offset:37888
	ds_read_b128 v[234:237], v147 offset:38912
	ds_read_b128 v[238:241], v147 offset:39936
	global_load_lds_dwordx4 v[242:243], off
	s_mov_b32 m0, s35
	v_lshl_add_u64 v[242:243], s[0:1], 0, v[132:133]
	global_load_lds_dwordx4 v[242:243], off
	s_waitcnt vmcnt(8)
	s_waitcnt lgkmcnt(0)
	s_barrier
	s_setprio 1
	s_waitcnt lgkmcnt(0)
	v_mfma_f32_16x16x32_bf16 v[126:129], v[140:143], v[210:213], v[126:129]
	v_mfma_f32_16x16x32_bf16 v[122:125], v[172:175], v[210:213], v[122:125]
	v_mfma_f32_16x16x32_bf16 v[110:113], v[140:143], v[218:221], v[110:113]
	v_mfma_f32_16x16x32_bf16 v[106:109], v[172:175], v[218:221], v[106:109]
	v_mfma_f32_16x16x32_bf16 v[94:97], v[140:143], v[226:229], v[94:97]
	v_mfma_f32_16x16x32_bf16 v[90:93], v[172:175], v[226:229], v[90:93]
	v_mfma_f32_16x16x32_bf16 v[78:81], v[140:143], v[234:237], v[78:81]
	v_mfma_f32_16x16x32_bf16 v[74:77], v[172:175], v[234:237], v[74:77]
	v_mfma_f32_16x16x32_bf16 v[126:129], v[148:151], v[214:217], v[126:129]
	v_mfma_f32_16x16x32_bf16 v[122:125], v[190:193], v[214:217], v[122:125]
	v_mfma_f32_16x16x32_bf16 v[110:113], v[148:151], v[222:225], v[110:113]
	v_mfma_f32_16x16x32_bf16 v[106:109], v[190:193], v[222:225], v[106:109]
	v_mfma_f32_16x16x32_bf16 v[94:97], v[148:151], v[230:233], v[94:97]
	v_mfma_f32_16x16x32_bf16 v[90:93], v[190:193], v[230:233], v[90:93]
	v_mfma_f32_16x16x32_bf16 v[78:81], v[148:151], v[238:241], v[78:81]
	v_mfma_f32_16x16x32_bf16 v[74:77], v[190:193], v[238:241], v[74:77]
	s_setprio 0
	s_setprio 1
	v_mfma_f32_16x16x32_bf16 v[118:121], v[194:197], v[210:213], v[118:121]
	v_mfma_f32_16x16x32_bf16 v[114:117], v[202:205], v[210:213], v[114:117]
	v_mfma_f32_16x16x32_bf16 v[102:105], v[194:197], v[218:221], v[102:105]
	v_mfma_f32_16x16x32_bf16 v[98:101], v[202:205], v[218:221], v[98:101]
	v_mfma_f32_16x16x32_bf16 v[86:89], v[194:197], v[226:229], v[86:89]
	v_mfma_f32_16x16x32_bf16 v[82:85], v[202:205], v[226:229], v[82:85]
	v_mfma_f32_16x16x32_bf16 v[70:73], v[194:197], v[234:237], v[70:73]
	v_mfma_f32_16x16x32_bf16 v[66:69], v[202:205], v[234:237], v[66:69]
	v_mfma_f32_16x16x32_bf16 v[118:121], v[198:201], v[214:217], v[118:121]
	v_mfma_f32_16x16x32_bf16 v[114:117], v[206:209], v[214:217], v[114:117]
	v_mfma_f32_16x16x32_bf16 v[102:105], v[198:201], v[222:225], v[102:105]
	v_mfma_f32_16x16x32_bf16 v[98:101], v[206:209], v[222:225], v[98:101]
	v_mfma_f32_16x16x32_bf16 v[86:89], v[198:201], v[230:233], v[86:89]
	v_mfma_f32_16x16x32_bf16 v[82:85], v[206:209], v[230:233], v[82:85]
	v_mfma_f32_16x16x32_bf16 v[70:73], v[198:201], v[238:241], v[70:73]
	v_mfma_f32_16x16x32_bf16 v[66:69], v[206:209], v[238:241], v[66:69]
	s_setprio 0
	s_barrier
	s_add_i32 s0, s3, s11
	v_lshl_add_u64 v[162:163], v[162:163], 0, s[70:71]
	s_mov_b32 m0, s0
	ds_read_b128 v[210:213], v147 offset:49152
	ds_read_b128 v[214:217], v147 offset:50176
	ds_read_b128 v[218:221], v147 offset:51200
	ds_read_b128 v[222:225], v147 offset:52224
	ds_read_b128 v[226:229], v147 offset:53248
	ds_read_b128 v[230:233], v147 offset:54272
	ds_read_b128 v[234:237], v147 offset:55296
	ds_read_b128 v[238:241], v147 offset:56320
	global_load_lds_dwordx4 v[162:163], off
	s_add_i32 m0, s0, 0x2000
	s_add_u32 s0, s22, 0x208080
	v_lshl_add_u64 v[162:163], v[166:167], 0, s[70:71]
	s_addc_u32 s1, s23, 0
	s_add_i32 s3, s4, s11
	global_load_lds_dwordx4 v[162:163], off
	s_mov_b32 m0, s3
	v_lshl_add_u64 v[162:163], s[0:1], 0, v[4:5]
	global_load_lds_dwordx4 v[162:163], off
	s_add_i32 m0, s3, 0x2000
	v_lshl_add_u64 v[162:163], s[0:1], 0, v[130:131]
	global_load_lds_dwordx4 v[162:163], off
	s_mov_b32 m0, s51
	v_lshl_add_u64 v[162:163], v[176:177], 0, s[70:71]
	global_load_lds_dwordx4 v[162:163], off
	s_mov_b32 m0, s52
	v_lshl_add_u64 v[162:163], v[180:181], 0, s[70:71]
	global_load_lds_dwordx4 v[162:163], off
	s_waitcnt vmcnt(8)
	s_waitcnt lgkmcnt(0)
	s_barrier
	s_setprio 1
	s_waitcnt lgkmcnt(0)
	v_mfma_f32_16x16x32_bf16 v[62:65], v[140:143], v[210:213], v[62:65]
	v_mfma_f32_16x16x32_bf16 v[58:61], v[172:175], v[210:213], v[58:61]
	v_mfma_f32_16x16x32_bf16 v[46:49], v[140:143], v[218:221], v[46:49]
	v_mfma_f32_16x16x32_bf16 v[42:45], v[172:175], v[218:221], v[42:45]
	v_mfma_f32_16x16x32_bf16 v[30:33], v[140:143], v[226:229], v[30:33]
	v_mfma_f32_16x16x32_bf16 v[26:29], v[172:175], v[226:229], v[26:29]
	v_mfma_f32_16x16x32_bf16 v[14:17], v[140:143], v[234:237], v[14:17]
	v_mfma_f32_16x16x32_bf16 v[10:13], v[172:175], v[234:237], v[10:13]
	v_mfma_f32_16x16x32_bf16 v[62:65], v[148:151], v[214:217], v[62:65]
	v_mfma_f32_16x16x32_bf16 v[58:61], v[190:193], v[214:217], v[58:61]
	v_mfma_f32_16x16x32_bf16 v[46:49], v[148:151], v[222:225], v[46:49]
	v_mfma_f32_16x16x32_bf16 v[42:45], v[190:193], v[222:225], v[42:45]
	v_mfma_f32_16x16x32_bf16 v[30:33], v[148:151], v[230:233], v[30:33]
	v_mfma_f32_16x16x32_bf16 v[26:29], v[190:193], v[230:233], v[26:29]
	v_mfma_f32_16x16x32_bf16 v[14:17], v[148:151], v[238:241], v[14:17]
	v_mfma_f32_16x16x32_bf16 v[10:13], v[190:193], v[238:241], v[10:13]
	s_setprio 0
	s_setprio 1
	v_mfma_f32_16x16x32_bf16 v[54:57], v[194:197], v[210:213], v[54:57]
	v_mfma_f32_16x16x32_bf16 v[50:53], v[202:205], v[210:213], v[50:53]
	v_mfma_f32_16x16x32_bf16 v[38:41], v[194:197], v[218:221], v[38:41]
	v_mfma_f32_16x16x32_bf16 v[34:37], v[202:205], v[218:221], v[34:37]
	v_mfma_f32_16x16x32_bf16 v[22:25], v[194:197], v[226:229], v[22:25]
	v_mfma_f32_16x16x32_bf16 v[18:21], v[202:205], v[226:229], v[18:21]
	v_mfma_f32_16x16x32_bf16 v[6:9], v[194:197], v[234:237], v[6:9]
	v_mfma_f32_16x16x32_bf16 v[0:3], v[202:205], v[234:237], v[0:3]
	v_mfma_f32_16x16x32_bf16 v[54:57], v[198:201], v[214:217], v[54:57]
	v_mfma_f32_16x16x32_bf16 v[50:53], v[206:209], v[214:217], v[50:53]
	v_mfma_f32_16x16x32_bf16 v[38:41], v[198:201], v[222:225], v[38:41]
	v_mfma_f32_16x16x32_bf16 v[34:37], v[206:209], v[222:225], v[34:37]
	v_mfma_f32_16x16x32_bf16 v[22:25], v[198:201], v[230:233], v[22:25]
	v_mfma_f32_16x16x32_bf16 v[18:21], v[206:209], v[230:233], v[18:21]
	v_mfma_f32_16x16x32_bf16 v[6:9], v[198:201], v[238:241], v[6:9]
	v_mfma_f32_16x16x32_bf16 v[0:3], v[206:209], v[238:241], v[0:3]
	s_setprio 0
	s_barrier
	s_add_i32 s9, s9, 2
	s_add_u32 s2, s2, 0x100
	s_addc_u32 s8, s8, 0
	s_cmpk_gt_u32 s9, 0x7d
	s_mov_b64 s[0:1], s[14:15]
	s_cbranch_scc0 .LBB0_81
	s_and_b64 vcc, exec, s[48:49]
	s_cbranch_vccz .LBB0_84
	s_barrier

.LBB0_123:
	s_ashr_i32 s3, s51, 24
	s_lshl_b32 s2, s51, 8
	s_andn2_b32 s3, s3, 63
	s_add_i32 s2, s3, s2
	s_ashr_i32 s3, s2, 31
	s_lshl_b64 s[2:3], s[2:3], 12
	s_add_u32 s48, s11, s2
	s_addc_u32 s49, s26, s3
	s_and_b64 s[2:3], s[38:39], exec
	s_cselect_b32 s2, s49, s1
	s_cselect_b32 s8, s48, s0
	s_ashr_i32 s47, s46, 31
	s_lshl_b64 s[4:5], s[46:47], 20
	v_readlane_b32 s6, v254, 1
	v_readlane_b32 s7, v254, 2
	s_add_u32 s78, s6, s4
	s_addc_u32 s79, s7, s5
	s_and_b64 s[4:5], s[38:39], exec
	s_cselect_b32 s10, s79, s15
	s_cselect_b32 s24, s78, s14
	s_add_u32 s22, s0, 0x80080
	s_addc_u32 s23, s1, 0
	s_add_u32 s9, s14, 0x100
	v_mov_b32_e32 v0, 0
	s_addc_u32 s25, s15, 0
	s_mov_b32 s28, -2
	v_mov_b32_e32 v1, v0
	v_mov_b32_e32 v2, v0
	v_mov_b32_e32 v3, v0
	v_mov_b32_e32 v6, v0
	v_mov_b32_e32 v7, v0
	v_mov_b32_e32 v8, v0
	v_mov_b32_e32 v9, v0
	v_mov_b32_e32 v10, v0
	v_mov_b32_e32 v11, v0
	v_mov_b32_e32 v12, v0
	v_mov_b32_e32 v13, v0
	v_mov_b32_e32 v14, v0
	v_mov_b32_e32 v15, v0
	v_mov_b32_e32 v16, v0
	v_mov_b32_e32 v17, v0
	v_mov_b32_e32 v18, v0
	v_mov_b32_e32 v19, v0
	v_mov_b32_e32 v20, v0
	v_mov_b32_e32 v21, v0
	v_mov_b32_e32 v22, v0
	v_mov_b32_e32 v23, v0
	v_mov_b32_e32 v24, v0
	v_mov_b32_e32 v25, v0
	v_mov_b32_e32 v26, v0
	v_mov_b32_e32 v27, v0
	v_mov_b32_e32 v28, v0
	v_mov_b32_e32 v29, v0
	v_mov_b32_e32 v30, v0
	v_mov_b32_e32 v31, v0
	v_mov_b32_e32 v32, v0
	v_mov_b32_e32 v33, v0
	v_mov_b32_e32 v58, v0
	v_mov_b32_e32 v59, v0
	v_mov_b32_e32 v60, v0
	v_mov_b32_e32 v61, v0
	v_mov_b32_e32 v62, v0
	v_mov_b32_e32 v63, v0
	v_mov_b32_e32 v64, v0
	v_mov_b32_e32 v65, v0
	v_mov_b32_e32 v74, v0
	v_mov_b32_e32 v75, v0
	v_mov_b32_e32 v76, v0
	v_mov_b32_e32 v77, v0
	v_mov_b32_e32 v78, v0
	v_mov_b32_e32 v79, v0
	v_mov_b32_e32 v80, v0
	v_mov_b32_e32 v81, v0
	v_mov_b32_e32 v82, v0
	v_mov_b32_e32 v83, v0
	v_mov_b32_e32 v84, v0
	v_mov_b32_e32 v85, v0
	v_mov_b32_e32 v86, v0
	v_mov_b32_e32 v87, v0
	v_mov_b32_e32 v88, v0
	v_mov_b32_e32 v89, v0
	v_mov_b32_e32 v90, v0
	v_mov_b32_e32 v91, v0
	v_mov_b32_e32 v92, v0
	v_mov_b32_e32 v93, v0
	v_mov_b32_e32 v94, v0
	v_mov_b32_e32 v95, v0
	v_mov_b32_e32 v96, v0
	v_mov_b32_e32 v97, v0
	v_mov_b32_e32 v34, v0
	v_mov_b32_e32 v35, v0
	v_mov_b32_e32 v36, v0
	v_mov_b32_e32 v37, v0
	v_mov_b32_e32 v38, v0
	v_mov_b32_e32 v39, v0
	v_mov_b32_e32 v40, v0
	v_mov_b32_e32 v41, v0
	v_mov_b32_e32 v42, v0
	v_mov_b32_e32 v43, v0
	v_mov_b32_e32 v44, v0
	v_mov_b32_e32 v45, v0
	v_mov_b32_e32 v46, v0
	v_mov_b32_e32 v47, v0
	v_mov_b32_e32 v48, v0
	v_mov_b32_e32 v49, v0
	v_mov_b32_e32 v50, v0
	v_mov_b32_e32 v51, v0
	v_mov_b32_e32 v52, v0
	v_mov_b32_e32 v53, v0
	v_mov_b32_e32 v54, v0
	v_mov_b32_e32 v55, v0
	v_mov_b32_e32 v56, v0
	v_mov_b32_e32 v57, v0
	v_mov_b32_e32 v66, v0
	v_mov_b32_e32 v67, v0
	v_mov_b32_e32 v68, v0
	v_mov_b32_e32 v69, v0
	v_mov_b32_e32 v70, v0
	v_mov_b32_e32 v71, v0
	v_mov_b32_e32 v72, v0
	v_mov_b32_e32 v73, v0
	v_mov_b32_e32 v98, v0
	v_mov_b32_e32 v99, v0
	v_mov_b32_e32 v100, v0
	v_mov_b32_e32 v101, v0
	v_mov_b32_e32 v102, v0
	v_mov_b32_e32 v103, v0
	v_mov_b32_e32 v104, v0
	v_mov_b32_e32 v105, v0
	v_mov_b32_e32 v106, v0
	v_mov_b32_e32 v107, v0
	v_mov_b32_e32 v108, v0
	v_mov_b32_e32 v109, v0
	v_mov_b32_e32 v110, v0
	v_mov_b32_e32 v111, v0
	v_mov_b32_e32 v112, v0
	v_mov_b32_e32 v113, v0
	v_mov_b32_e32 v114, v0
	v_mov_b32_e32 v115, v0
	v_mov_b32_e32 v116, v0
	v_mov_b32_e32 v117, v0
	v_mov_b32_e32 v118, v0
	v_mov_b32_e32 v119, v0
	v_mov_b32_e32 v120, v0
	v_mov_b32_e32 v121, v0
	v_mov_b32_e32 v122, v0
	v_mov_b32_e32 v123, v0
	v_mov_b32_e32 v124, v0
	v_mov_b32_e32 v125, v0
	v_mov_b32_e32 v126, v0
	v_mov_b32_e32 v127, v0
	v_mov_b32_e32 v128, v0
	v_mov_b32_e32 v129, v0
	s_cmp_eq_u32 s50, 1
	s_cbranch_scc1 .LBB0_124
	s_add_u32 s0, s22, 0xfff80080
	s_addc_u32 s1, s23, -1
	s_add_i32 s3, 0, 0x10000
	s_cmp_eq_u32 s28, 28
	s_cselect_b32 s15, s2, s1
	s_cselect_b32 s14, s8, s0
	v_add_u32_e32 v162, s3, v141
	s_cselect_b32 s1, s10, s25
	s_cselect_b32 s0, s24, s9
	s_add_i32 s6, 0, 0x14000
	ds_read_b128 v[144:147], v162
	ds_read_b128 v[148:151], v162 offset:1024
	ds_read_b128 v[172:175], v162 offset:2048
	ds_read_b128 v[190:193], v162 offset:3072
	v_add_u32_e32 v162, s6, v141
	ds_read_b128 v[194:197], v162
	ds_read_b128 v[198:201], v162 offset:1024
	ds_read_b128 v[202:205], v162 offset:2048
	ds_read_b128 v[206:209], v162 offset:3072
	v_lshl_add_u64 v[162:163], s[22:23], 0, v[136:137]
	s_add_i32 m0, s30, 0xc000
	ds_read_b128 v[210:213], v143
	ds_read_b128 v[214:217], v143 offset:1024
	ds_read_b128 v[218:221], v143 offset:2048
	ds_read_b128 v[222:225], v143 offset:3072
	ds_read_b128 v[226:229], v143 offset:4096
	ds_read_b128 v[230:233], v143 offset:5120
	ds_read_b128 v[234:237], v143 offset:6144
	ds_read_b128 v[238:241], v143 offset:7168
	global_load_lds_dwordx4 v[162:163], off
	s_add_i32 m0, s30, 0xe000
	v_lshl_add_u64 v[162:163], s[22:23], 0, v[138:139]
	global_load_lds_dwordx4 v[162:163], off
	s_waitcnt vmcnt(24)
	s_waitcnt lgkmcnt(0)
	s_barrier
	s_setprio 1
	s_waitcnt lgkmcnt(0)
	v_mfma_f32_16x16x32_bf16 v[126:129], v[144:147], v[210:213], v[126:129]
	v_mfma_f32_16x16x32_bf16 v[122:125], v[172:175], v[210:213], v[122:125]
	v_mfma_f32_16x16x32_bf16 v[118:121], v[144:147], v[218:221], v[118:121]
	v_mfma_f32_16x16x32_bf16 v[114:117], v[172:175], v[218:221], v[114:117]
	v_mfma_f32_16x16x32_bf16 v[110:113], v[144:147], v[226:229], v[110:113]
	v_mfma_f32_16x16x32_bf16 v[106:109], v[172:175], v[226:229], v[106:109]
	v_mfma_f32_16x16x32_bf16 v[102:105], v[144:147], v[234:237], v[102:105]
	v_mfma_f32_16x16x32_bf16 v[98:101], v[172:175], v[234:237], v[98:101]
	v_mfma_f32_16x16x32_bf16 v[126:129], v[148:151], v[214:217], v[126:129]
	v_mfma_f32_16x16x32_bf16 v[122:125], v[190:193], v[214:217], v[122:125]
	v_mfma_f32_16x16x32_bf16 v[118:121], v[148:151], v[222:225], v[118:121]
	v_mfma_f32_16x16x32_bf16 v[114:117], v[190:193], v[222:225], v[114:117]
	v_mfma_f32_16x16x32_bf16 v[110:113], v[148:151], v[230:233], v[110:113]
	v_mfma_f32_16x16x32_bf16 v[106:109], v[190:193], v[230:233], v[106:109]
	v_mfma_f32_16x16x32_bf16 v[102:105], v[148:151], v[238:241], v[102:105]
	v_mfma_f32_16x16x32_bf16 v[98:101], v[190:193], v[238:241], v[98:101]
	s_setprio 0
	s_setprio 1
	v_mfma_f32_16x16x32_bf16 v[70:73], v[194:197], v[210:213], v[70:73]
	v_mfma_f32_16x16x32_bf16 v[66:69], v[202:205], v[210:213], v[66:69]
	v_mfma_f32_16x16x32_bf16 v[54:57], v[194:197], v[218:221], v[54:57]
	v_mfma_f32_16x16x32_bf16 v[50:53], v[202:205], v[218:221], v[50:53]
	v_mfma_f32_16x16x32_bf16 v[46:49], v[194:197], v[226:229], v[46:49]
	v_mfma_f32_16x16x32_bf16 v[42:45], v[202:205], v[226:229], v[42:45]
	v_mfma_f32_16x16x32_bf16 v[38:41], v[194:197], v[234:237], v[38:41]
	v_mfma_f32_16x16x32_bf16 v[34:37], v[202:205], v[234:237], v[34:37]
	v_mfma_f32_16x16x32_bf16 v[70:73], v[198:201], v[214:217], v[70:73]
	v_mfma_f32_16x16x32_bf16 v[66:69], v[206:209], v[214:217], v[66:69]
	v_mfma_f32_16x16x32_bf16 v[54:57], v[198:201], v[222:225], v[54:57]
	v_mfma_f32_16x16x32_bf16 v[50:53], v[206:209], v[222:225], v[50:53]
	v_mfma_f32_16x16x32_bf16 v[46:49], v[198:201], v[230:233], v[46:49]
	v_mfma_f32_16x16x32_bf16 v[42:45], v[206:209], v[230:233], v[42:45]
	v_mfma_f32_16x16x32_bf16 v[38:41], v[198:201], v[238:241], v[38:41]
	v_mfma_f32_16x16x32_bf16 v[34:37], v[206:209], v[238:241], v[34:37]
	s_setprio 0
	s_barrier
	s_add_i32 s3, s3, s27
	v_lshl_add_u64 v[162:163], s[0:1], 0, v[4:5]
	s_mov_b32 m0, s3
	ds_read_b128 v[210:213], v143 offset:16384
	ds_read_b128 v[214:217], v143 offset:17408
	ds_read_b128 v[218:221], v143 offset:18432
	ds_read_b128 v[222:225], v143 offset:19456
	ds_read_b128 v[226:229], v143 offset:20480
	ds_read_b128 v[230:233], v143 offset:21504
	ds_read_b128 v[234:237], v143 offset:22528
	ds_read_b128 v[238:241], v143 offset:23552
	global_load_lds_dwordx4 v[162:163], off
	s_add_i32 m0, s3, 0x2000
	s_add_u32 s4, s0, 0x80000
	v_lshl_add_u64 v[166:167], s[0:1], 0, v[130:131]
	s_addc_u32 s5, s1, 0
	s_add_i32 s3, s6, s27
	global_load_lds_dwordx4 v[166:167], off
	v_lshl_add_u64 v[176:177], s[4:5], 0, v[4:5]
	s_mov_b32 m0, s3
	v_lshl_add_u64 v[180:181], s[14:15], 0, v[132:133]
	global_load_lds_dwordx4 v[176:177], off
	s_add_i32 m0, s3, 0x2000
	v_lshl_add_u64 v[176:177], s[4:5], 0, v[130:131]
	global_load_lds_dwordx4 v[176:177], off
	s_mov_b32 m0, s30
	v_lshl_add_u64 v[176:177], s[14:15], 0, v[134:135]
	global_load_lds_dwordx4 v[176:177], off
	s_mov_b32 m0, s31
	s_nop 0
	global_load_lds_dwordx4 v[180:181], off
	s_waitcnt vmcnt(24)
	s_waitcnt lgkmcnt(0)
	s_barrier
	s_setprio 1
	s_waitcnt lgkmcnt(0)
	v_mfma_f32_16x16x32_bf16 v[94:97], v[144:147], v[210:213], v[94:97]
	v_mfma_f32_16x16x32_bf16 v[90:93], v[172:175], v[210:213], v[90:93]
	v_mfma_f32_16x16x32_bf16 v[86:89], v[144:147], v[218:221], v[86:89]
	v_mfma_f32_16x16x32_bf16 v[82:85], v[172:175], v[218:221], v[82:85]
	v_mfma_f32_16x16x32_bf16 v[78:81], v[144:147], v[226:229], v[78:81]
	v_mfma_f32_16x16x32_bf16 v[74:77], v[172:175], v[226:229], v[74:77]
	v_mfma_f32_16x16x32_bf16 v[62:65], v[144:147], v[234:237], v[62:65]
	v_mfma_f32_16x16x32_bf16 v[58:61], v[172:175], v[234:237], v[58:61]
	v_mfma_f32_16x16x32_bf16 v[94:97], v[148:151], v[214:217], v[94:97]
	v_mfma_f32_16x16x32_bf16 v[90:93], v[190:193], v[214:217], v[90:93]
	v_mfma_f32_16x16x32_bf16 v[86:89], v[148:151], v[222:225], v[86:89]
	v_mfma_f32_16x16x32_bf16 v[82:85], v[190:193], v[222:225], v[82:85]
	v_mfma_f32_16x16x32_bf16 v[78:81], v[148:151], v[230:233], v[78:81]
	v_mfma_f32_16x16x32_bf16 v[74:77], v[190:193], v[230:233], v[74:77]
	v_mfma_f32_16x16x32_bf16 v[62:65], v[148:151], v[238:241], v[62:65]
	v_mfma_f32_16x16x32_bf16 v[58:61], v[190:193], v[238:241], v[58:61]
	s_setprio 0
	s_setprio 1
	v_mfma_f32_16x16x32_bf16 v[30:33], v[194:197], v[210:213], v[30:33]
	v_mfma_f32_16x16x32_bf16 v[26:29], v[202:205], v[210:213], v[26:29]
	v_mfma_f32_16x16x32_bf16 v[22:25], v[194:197], v[218:221], v[22:25]
	v_mfma_f32_16x16x32_bf16 v[18:21], v[202:205], v[218:221], v[18:21]
	v_mfma_f32_16x16x32_bf16 v[14:17], v[194:197], v[226:229], v[14:17]
	v_mfma_f32_16x16x32_bf16 v[10:13], v[202:205], v[226:229], v[10:13]
	v_mfma_f32_16x16x32_bf16 v[6:9], v[194:197], v[234:237], v[6:9]
	v_mfma_f32_16x16x32_bf16 v[0:3], v[202:205], v[234:237], v[0:3]
	v_mfma_f32_16x16x32_bf16 v[30:33], v[198:201], v[214:217], v[30:33]
	v_mfma_f32_16x16x32_bf16 v[26:29], v[206:209], v[214:217], v[26:29]
	v_mfma_f32_16x16x32_bf16 v[22:25], v[198:201], v[222:225], v[22:25]
	v_mfma_f32_16x16x32_bf16 v[18:21], v[206:209], v[222:225], v[18:21]
	v_mfma_f32_16x16x32_bf16 v[14:17], v[198:201], v[230:233], v[14:17]
	v_mfma_f32_16x16x32_bf16 v[10:13], v[206:209], v[230:233], v[10:13]
	v_mfma_f32_16x16x32_bf16 v[6:9], v[198:201], v[238:241], v[6:9]
	v_mfma_f32_16x16x32_bf16 v[0:3], v[206:209], v[238:241], v[0:3]
	s_setprio 0
	s_barrier
	s_branch .Lpeelmid_124
.LBB0_124:
	s_add_u32 s0, s22, 0xfff80080
	s_addc_u32 s1, s23, -1
	s_add_i32 s3, 0, 0x10000
	s_cmp_eq_u32 s28, 28
	s_cselect_b32 s15, s2, s1
	s_cselect_b32 s14, s8, s0
	v_add_u32_e32 v162, s3, v141
	s_cselect_b32 s1, s10, s25
	s_cselect_b32 s0, s24, s9
	s_add_i32 s6, 0, 0x14000
	ds_read_b128 v[144:147], v162
	ds_read_b128 v[148:151], v162 offset:1024
	ds_read_b128 v[172:175], v162 offset:2048
	ds_read_b128 v[190:193], v162 offset:3072
	v_add_u32_e32 v162, s6, v141
	ds_read_b128 v[194:197], v162
	ds_read_b128 v[198:201], v162 offset:1024
	ds_read_b128 v[202:205], v162 offset:2048
	ds_read_b128 v[206:209], v162 offset:3072
	v_lshl_add_u64 v[162:163], s[22:23], 0, v[136:137]
	s_add_i32 m0, s30, 0xc000
	ds_read_b128 v[210:213], v143
	ds_read_b128 v[214:217], v143 offset:1024
	ds_read_b128 v[218:221], v143 offset:2048
	ds_read_b128 v[222:225], v143 offset:3072
	ds_read_b128 v[226:229], v143 offset:4096
	ds_read_b128 v[230:233], v143 offset:5120
	ds_read_b128 v[234:237], v143 offset:6144
	ds_read_b128 v[238:241], v143 offset:7168
	global_load_lds_dwordx4 v[162:163], off
	s_add_i32 m0, s30, 0xe000
	v_lshl_add_u64 v[162:163], s[22:23], 0, v[138:139]
	global_load_lds_dwordx4 v[162:163], off
	s_waitcnt vmcnt(8)
	s_waitcnt lgkmcnt(0)
	s_barrier
	s_setprio 1
	s_waitcnt lgkmcnt(0)
	v_mfma_f32_16x16x32_bf16 v[126:129], v[144:147], v[210:213], v[126:129]
	v_mfma_f32_16x16x32_bf16 v[122:125], v[172:175], v[210:213], v[122:125]
	v_mfma_f32_16x16x32_bf16 v[118:121], v[144:147], v[218:221], v[118:121]
	v_mfma_f32_16x16x32_bf16 v[114:117], v[172:175], v[218:221], v[114:117]
	v_mfma_f32_16x16x32_bf16 v[110:113], v[144:147], v[226:229], v[110:113]
	v_mfma_f32_16x16x32_bf16 v[106:109], v[172:175], v[226:229], v[106:109]
	v_mfma_f32_16x16x32_bf16 v[102:105], v[144:147], v[234:237], v[102:105]
	v_mfma_f32_16x16x32_bf16 v[98:101], v[172:175], v[234:237], v[98:101]
	v_mfma_f32_16x16x32_bf16 v[126:129], v[148:151], v[214:217], v[126:129]
	v_mfma_f32_16x16x32_bf16 v[122:125], v[190:193], v[214:217], v[122:125]
	v_mfma_f32_16x16x32_bf16 v[118:121], v[148:151], v[222:225], v[118:121]
	v_mfma_f32_16x16x32_bf16 v[114:117], v[190:193], v[222:225], v[114:117]
	v_mfma_f32_16x16x32_bf16 v[110:113], v[148:151], v[230:233], v[110:113]
	v_mfma_f32_16x16x32_bf16 v[106:109], v[190:193], v[230:233], v[106:109]
	v_mfma_f32_16x16x32_bf16 v[102:105], v[148:151], v[238:241], v[102:105]
	v_mfma_f32_16x16x32_bf16 v[98:101], v[190:193], v[238:241], v[98:101]
	s_setprio 0
	s_setprio 1
	v_mfma_f32_16x16x32_bf16 v[70:73], v[194:197], v[210:213], v[70:73]
	v_mfma_f32_16x16x32_bf16 v[66:69], v[202:205], v[210:213], v[66:69]
	v_mfma_f32_16x16x32_bf16 v[54:57], v[194:197], v[218:221], v[54:57]
	v_mfma_f32_16x16x32_bf16 v[50:53], v[202:205], v[218:221], v[50:53]
	v_mfma_f32_16x16x32_bf16 v[46:49], v[194:197], v[226:229], v[46:49]
	v_mfma_f32_16x16x32_bf16 v[42:45], v[202:205], v[226:229], v[42:45]
	v_mfma_f32_16x16x32_bf16 v[38:41], v[194:197], v[234:237], v[38:41]
	v_mfma_f32_16x16x32_bf16 v[34:37], v[202:205], v[234:237], v[34:37]
	v_mfma_f32_16x16x32_bf16 v[70:73], v[198:201], v[214:217], v[70:73]
	v_mfma_f32_16x16x32_bf16 v[66:69], v[206:209], v[214:217], v[66:69]
	v_mfma_f32_16x16x32_bf16 v[54:57], v[198:201], v[222:225], v[54:57]
	v_mfma_f32_16x16x32_bf16 v[50:53], v[206:209], v[222:225], v[50:53]
	v_mfma_f32_16x16x32_bf16 v[46:49], v[198:201], v[230:233], v[46:49]
	v_mfma_f32_16x16x32_bf16 v[42:45], v[206:209], v[230:233], v[42:45]
	v_mfma_f32_16x16x32_bf16 v[38:41], v[198:201], v[238:241], v[38:41]
	v_mfma_f32_16x16x32_bf16 v[34:37], v[206:209], v[238:241], v[34:37]
	s_setprio 0
	s_barrier
	s_add_i32 s3, s3, s27
	v_lshl_add_u64 v[162:163], s[0:1], 0, v[4:5]
	s_mov_b32 m0, s3
	ds_read_b128 v[210:213], v143 offset:16384
	ds_read_b128 v[214:217], v143 offset:17408
	ds_read_b128 v[218:221], v143 offset:18432
	ds_read_b128 v[222:225], v143 offset:19456
	ds_read_b128 v[226:229], v143 offset:20480
	ds_read_b128 v[230:233], v143 offset:21504
	ds_read_b128 v[234:237], v143 offset:22528
	ds_read_b128 v[238:241], v143 offset:23552
	global_load_lds_dwordx4 v[162:163], off
	s_add_i32 m0, s3, 0x2000
	s_add_u32 s4, s0, 0x80000
	v_lshl_add_u64 v[166:167], s[0:1], 0, v[130:131]
	s_addc_u32 s5, s1, 0
	s_add_i32 s3, s6, s27
	global_load_lds_dwordx4 v[166:167], off
	v_lshl_add_u64 v[176:177], s[4:5], 0, v[4:5]
	s_mov_b32 m0, s3
	v_lshl_add_u64 v[180:181], s[14:15], 0, v[132:133]
	global_load_lds_dwordx4 v[176:177], off
	s_add_i32 m0, s3, 0x2000
	v_lshl_add_u64 v[176:177], s[4:5], 0, v[130:131]
	global_load_lds_dwordx4 v[176:177], off
	s_mov_b32 m0, s30
	v_lshl_add_u64 v[176:177], s[14:15], 0, v[134:135]
	global_load_lds_dwordx4 v[176:177], off
	s_mov_b32 m0, s31
	s_nop 0
	global_load_lds_dwordx4 v[180:181], off
	s_waitcnt vmcnt(8)
	s_waitcnt lgkmcnt(0)
	s_barrier
	s_setprio 1
	s_waitcnt lgkmcnt(0)
	v_mfma_f32_16x16x32_bf16 v[94:97], v[144:147], v[210:213], v[94:97]
	v_mfma_f32_16x16x32_bf16 v[90:93], v[172:175], v[210:213], v[90:93]
	v_mfma_f32_16x16x32_bf16 v[86:89], v[144:147], v[218:221], v[86:89]
	v_mfma_f32_16x16x32_bf16 v[82:85], v[172:175], v[218:221], v[82:85]
	v_mfma_f32_16x16x32_bf16 v[78:81], v[144:147], v[226:229], v[78:81]
	v_mfma_f32_16x16x32_bf16 v[74:77], v[172:175], v[226:229], v[74:77]
	v_mfma_f32_16x16x32_bf16 v[62:65], v[144:147], v[234:237], v[62:65]
	v_mfma_f32_16x16x32_bf16 v[58:61], v[172:175], v[234:237], v[58:61]
	v_mfma_f32_16x16x32_bf16 v[94:97], v[148:151], v[214:217], v[94:97]
	v_mfma_f32_16x16x32_bf16 v[90:93], v[190:193], v[214:217], v[90:93]
	v_mfma_f32_16x16x32_bf16 v[86:89], v[148:151], v[222:225], v[86:89]
	v_mfma_f32_16x16x32_bf16 v[82:85], v[190:193], v[222:225], v[82:85]
	v_mfma_f32_16x16x32_bf16 v[78:81], v[148:151], v[230:233], v[78:81]
	v_mfma_f32_16x16x32_bf16 v[74:77], v[190:193], v[230:233], v[74:77]
	v_mfma_f32_16x16x32_bf16 v[62:65], v[148:151], v[238:241], v[62:65]
	v_mfma_f32_16x16x32_bf16 v[58:61], v[190:193], v[238:241], v[58:61]
	s_setprio 0
	s_setprio 1
	v_mfma_f32_16x16x32_bf16 v[30:33], v[194:197], v[210:213], v[30:33]
	v_mfma_f32_16x16x32_bf16 v[26:29], v[202:205], v[210:213], v[26:29]
	v_mfma_f32_16x16x32_bf16 v[22:25], v[194:197], v[218:221], v[22:25]
	v_mfma_f32_16x16x32_bf16 v[18:21], v[202:205], v[218:221], v[18:21]
	v_mfma_f32_16x16x32_bf16 v[14:17], v[194:197], v[226:229], v[14:17]
	v_mfma_f32_16x16x32_bf16 v[10:13], v[202:205], v[226:229], v[10:13]
	v_mfma_f32_16x16x32_bf16 v[6:9], v[194:197], v[234:237], v[6:9]
	v_mfma_f32_16x16x32_bf16 v[0:3], v[202:205], v[234:237], v[0:3]
	v_mfma_f32_16x16x32_bf16 v[30:33], v[198:201], v[214:217], v[30:33]
	v_mfma_f32_16x16x32_bf16 v[26:29], v[206:209], v[214:217], v[26:29]
	v_mfma_f32_16x16x32_bf16 v[22:25], v[198:201], v[222:225], v[22:25]
	v_mfma_f32_16x16x32_bf16 v[18:21], v[206:209], v[222:225], v[18:21]
	v_mfma_f32_16x16x32_bf16 v[14:17], v[198:201], v[230:233], v[14:17]
	v_mfma_f32_16x16x32_bf16 v[10:13], v[206:209], v[230:233], v[10:13]
	v_mfma_f32_16x16x32_bf16 v[6:9], v[198:201], v[238:241], v[6:9]
	v_mfma_f32_16x16x32_bf16 v[0:3], v[206:209], v[238:241], v[0:3]
	s_setprio 0
	s_barrier
.Lpeelmid_124:
	s_add_i32 s3, 0, 0x18000
	v_add_u32_e32 v164, s3, v141
	s_add_i32 s6, 0, 0x1c000
	ds_read_b128 v[144:147], v164
	ds_read_b128 v[148:151], v164 offset:1024
	ds_read_b128 v[172:175], v164 offset:2048
	ds_read_b128 v[190:193], v164 offset:3072
	v_add_u32_e32 v164, s6, v141
	ds_read_b128 v[194:197], v164
	ds_read_b128 v[198:201], v164 offset:1024
	ds_read_b128 v[202:205], v164 offset:2048
	ds_read_b128 v[206:209], v164 offset:3072
	s_add_u32 s4, s14, 0x80000
	s_addc_u32 s5, s15, 0
	s_mov_b32 m0, s34
	v_lshl_add_u64 v[242:243], s[4:5], 0, v[134:135]
	ds_read_b128 v[210:213], v143 offset:32768
	ds_read_b128 v[214:217], v143 offset:33792
	ds_read_b128 v[218:221], v143 offset:34816
	ds_read_b128 v[222:225], v143 offset:35840
	ds_read_b128 v[226:229], v143 offset:36864
	ds_read_b128 v[230:233], v143 offset:37888
	ds_read_b128 v[234:237], v143 offset:38912
	ds_read_b128 v[238:241], v143 offset:39936
	global_load_lds_dwordx4 v[242:243], off
	s_mov_b32 m0, s35
	v_lshl_add_u64 v[242:243], s[4:5], 0, v[132:133]
	global_load_lds_dwordx4 v[242:243], off
	s_waitcnt vmcnt(8)
	s_waitcnt lgkmcnt(0)
	s_barrier
	s_setprio 1
	s_waitcnt lgkmcnt(0)
	v_mfma_f32_16x16x32_bf16 v[126:129], v[144:147], v[210:213], v[126:129]
	v_mfma_f32_16x16x32_bf16 v[122:125], v[172:175], v[210:213], v[122:125]
	v_mfma_f32_16x16x32_bf16 v[118:121], v[144:147], v[218:221], v[118:121]
	v_mfma_f32_16x16x32_bf16 v[114:117], v[172:175], v[218:221], v[114:117]
	v_mfma_f32_16x16x32_bf16 v[110:113], v[144:147], v[226:229], v[110:113]
	v_mfma_f32_16x16x32_bf16 v[106:109], v[172:175], v[226:229], v[106:109]
	v_mfma_f32_16x16x32_bf16 v[102:105], v[144:147], v[234:237], v[102:105]
	v_mfma_f32_16x16x32_bf16 v[98:101], v[172:175], v[234:237], v[98:101]
	v_mfma_f32_16x16x32_bf16 v[126:129], v[148:151], v[214:217], v[126:129]
	v_mfma_f32_16x16x32_bf16 v[122:125], v[190:193], v[214:217], v[122:125]
	v_mfma_f32_16x16x32_bf16 v[118:121], v[148:151], v[222:225], v[118:121]
	v_mfma_f32_16x16x32_bf16 v[114:117], v[190:193], v[222:225], v[114:117]
	v_mfma_f32_16x16x32_bf16 v[110:113], v[148:151], v[230:233], v[110:113]
	v_mfma_f32_16x16x32_bf16 v[106:109], v[190:193], v[230:233], v[106:109]
	v_mfma_f32_16x16x32_bf16 v[102:105], v[148:151], v[238:241], v[102:105]
	v_mfma_f32_16x16x32_bf16 v[98:101], v[190:193], v[238:241], v[98:101]
	s_setprio 0
	s_setprio 1
	v_mfma_f32_16x16x32_bf16 v[70:73], v[194:197], v[210:213], v[70:73]
	v_mfma_f32_16x16x32_bf16 v[66:69], v[202:205], v[210:213], v[66:69]
	v_mfma_f32_16x16x32_bf16 v[54:57], v[194:197], v[218:221], v[54:57]
	v_mfma_f32_16x16x32_bf16 v[50:53], v[202:205], v[218:221], v[50:53]
	v_mfma_f32_16x16x32_bf16 v[46:49], v[194:197], v[226:229], v[46:49]
	v_mfma_f32_16x16x32_bf16 v[42:45], v[202:205], v[226:229], v[42:45]
	v_mfma_f32_16x16x32_bf16 v[38:41], v[194:197], v[234:237], v[38:41]
	v_mfma_f32_16x16x32_bf16 v[34:37], v[202:205], v[234:237], v[34:37]
	v_mfma_f32_16x16x32_bf16 v[70:73], v[198:201], v[214:217], v[70:73]
	v_mfma_f32_16x16x32_bf16 v[66:69], v[206:209], v[214:217], v[66:69]
	v_mfma_f32_16x16x32_bf16 v[54:57], v[198:201], v[222:225], v[54:57]
	v_mfma_f32_16x16x32_bf16 v[50:53], v[206:209], v[222:225], v[50:53]
	v_mfma_f32_16x16x32_bf16 v[46:49], v[198:201], v[230:233], v[46:49]
	v_mfma_f32_16x16x32_bf16 v[42:45], v[206:209], v[230:233], v[42:45]
	v_mfma_f32_16x16x32_bf16 v[38:41], v[198:201], v[238:241], v[38:41]
	v_mfma_f32_16x16x32_bf16 v[34:37], v[206:209], v[238:241], v[34:37]
	s_setprio 0
	s_barrier
	s_add_i32 s3, s3, s27
	v_lshl_add_u64 v[162:163], v[162:163], 0, s[70:71]
	s_mov_b32 m0, s3
	ds_read_b128 v[210:213], v143 offset:49152
	ds_read_b128 v[214:217], v143 offset:50176
	ds_read_b128 v[218:221], v143 offset:51200
	ds_read_b128 v[222:225], v143 offset:52224
	ds_read_b128 v[226:229], v143 offset:53248
	ds_read_b128 v[230:233], v143 offset:54272
	ds_read_b128 v[234:237], v143 offset:55296
	ds_read_b128 v[238:241], v143 offset:56320
	global_load_lds_dwordx4 v[162:163], off
	s_add_i32 m0, s3, 0x2000
	s_add_u32 s0, s0, 0x80080
	v_lshl_add_u64 v[162:163], v[166:167], 0, s[70:71]
	s_addc_u32 s1, s1, 0
	s_add_i32 s3, s6, s27
	global_load_lds_dwordx4 v[162:163], off
	s_mov_b32 m0, s3
	v_lshl_add_u64 v[162:163], s[0:1], 0, v[4:5]
	global_load_lds_dwordx4 v[162:163], off
	s_add_i32 m0, s3, 0x2000
	v_lshl_add_u64 v[162:163], s[0:1], 0, v[130:131]
	global_load_lds_dwordx4 v[162:163], off
	s_mov_b32 m0, s36
	v_lshl_add_u64 v[162:163], v[176:177], 0, s[70:71]
	global_load_lds_dwordx4 v[162:163], off
	s_mov_b32 m0, s37
	v_lshl_add_u64 v[162:163], v[180:181], 0, s[70:71]
	global_load_lds_dwordx4 v[162:163], off
	s_waitcnt vmcnt(8)
	s_waitcnt lgkmcnt(0)
	s_barrier
	s_setprio 1
	s_waitcnt lgkmcnt(0)
	v_mfma_f32_16x16x32_bf16 v[94:97], v[144:147], v[210:213], v[94:97]
	v_mfma_f32_16x16x32_bf16 v[90:93], v[172:175], v[210:213], v[90:93]
	v_mfma_f32_16x16x32_bf16 v[86:89], v[144:147], v[218:221], v[86:89]
	v_mfma_f32_16x16x32_bf16 v[82:85], v[172:175], v[218:221], v[82:85]
	v_mfma_f32_16x16x32_bf16 v[78:81], v[144:147], v[226:229], v[78:81]
	v_mfma_f32_16x16x32_bf16 v[74:77], v[172:175], v[226:229], v[74:77]
	v_mfma_f32_16x16x32_bf16 v[62:65], v[144:147], v[234:237], v[62:65]
	v_mfma_f32_16x16x32_bf16 v[58:61], v[172:175], v[234:237], v[58:61]
	v_mfma_f32_16x16x32_bf16 v[94:97], v[148:151], v[214:217], v[94:97]
	v_mfma_f32_16x16x32_bf16 v[90:93], v[190:193], v[214:217], v[90:93]
	v_mfma_f32_16x16x32_bf16 v[86:89], v[148:151], v[222:225], v[86:89]
	v_mfma_f32_16x16x32_bf16 v[82:85], v[190:193], v[222:225], v[82:85]
	v_mfma_f32_16x16x32_bf16 v[78:81], v[148:151], v[230:233], v[78:81]
	v_mfma_f32_16x16x32_bf16 v[74:77], v[190:193], v[230:233], v[74:77]
	v_mfma_f32_16x16x32_bf16 v[62:65], v[148:151], v[238:241], v[62:65]
	v_mfma_f32_16x16x32_bf16 v[58:61], v[190:193], v[238:241], v[58:61]
	s_setprio 0
	s_setprio 1
	v_mfma_f32_16x16x32_bf16 v[30:33], v[194:197], v[210:213], v[30:33]
	v_mfma_f32_16x16x32_bf16 v[26:29], v[202:205], v[210:213], v[26:29]
	v_mfma_f32_16x16x32_bf16 v[22:25], v[194:197], v[218:221], v[22:25]
	v_mfma_f32_16x16x32_bf16 v[18:21], v[202:205], v[218:221], v[18:21]
	v_mfma_f32_16x16x32_bf16 v[14:17], v[194:197], v[226:229], v[14:17]
	v_mfma_f32_16x16x32_bf16 v[10:13], v[202:205], v[226:229], v[10:13]
	v_mfma_f32_16x16x32_bf16 v[6:9], v[194:197], v[234:237], v[6:9]
	v_mfma_f32_16x16x32_bf16 v[0:3], v[202:205], v[234:237], v[0:3]
	v_mfma_f32_16x16x32_bf16 v[30:33], v[198:201], v[214:217], v[30:33]
	v_mfma_f32_16x16x32_bf16 v[26:29], v[206:209], v[214:217], v[26:29]
	v_mfma_f32_16x16x32_bf16 v[22:25], v[198:201], v[222:225], v[22:25]
	v_mfma_f32_16x16x32_bf16 v[18:21], v[206:209], v[222:225], v[18:21]
	v_mfma_f32_16x16x32_bf16 v[14:17], v[198:201], v[230:233], v[14:17]
	v_mfma_f32_16x16x32_bf16 v[10:13], v[206:209], v[230:233], v[10:13]
	v_mfma_f32_16x16x32_bf16 v[6:9], v[198:201], v[238:241], v[6:9]
	v_mfma_f32_16x16x32_bf16 v[0:3], v[206:209], v[238:241], v[0:3]
	s_setprio 0
	s_barrier
	s_add_i32 s28, s28, 2
	s_add_u32 s22, s22, 0x100
	s_addc_u32 s23, s23, 0
	s_add_u32 s9, s9, 0x100
	s_addc_u32 s25, s25, 0
	s_cmp_gt_u32 s28, 29
	s_cbranch_scc0 .LBB0_124
	s_and_b64 vcc, exec, s[42:43]
	s_cbranch_vccz .LBB0_127
	s_barrier

.LBB0_162:
	s_ashr_i32 s49, s48, 31
	s_lshl_b64 s[2:3], s[48:49], 20
	v_readlane_b32 s4, v253, 61
	v_readlane_b32 s5, v253, 62
	s_add_u32 s82, s4, s2
	s_addc_u32 s83, s5, s3
	s_and_b64 s[2:3], s[42:43], exec
	s_cselect_b32 s2, s83, s1
	s_cselect_b32 s8, s82, s0
	s_add_u32 s22, s14, 0x80080
	s_addc_u32 s23, s15, 0
	s_add_u32 s9, s0, 0x100
	v_mov_b32_e32 v0, 0
	s_addc_u32 s10, s1, 0
	s_mov_b32 s24, -2
	v_mov_b32_e32 v1, v0
	v_mov_b32_e32 v2, v0
	v_mov_b32_e32 v3, v0
	v_mov_b32_e32 v6, v0
	s_waitcnt lgkmcnt(0)
	v_mov_b32_e32 v7, v0
	v_mov_b32_e32 v8, v0
	v_mov_b32_e32 v9, v0
	v_mov_b32_e32 v18, v0
	v_mov_b32_e32 v19, v0
	v_mov_b32_e32 v20, v0
	v_mov_b32_e32 v21, v0
	v_mov_b32_e32 v22, v0
	v_mov_b32_e32 v23, v0
	v_mov_b32_e32 v24, v0
	v_mov_b32_e32 v25, v0
	v_mov_b32_e32 v34, v0
	v_mov_b32_e32 v35, v0
	v_mov_b32_e32 v36, v0
	v_mov_b32_e32 v37, v0
	v_mov_b32_e32 v38, v0
	v_mov_b32_e32 v39, v0
	v_mov_b32_e32 v40, v0
	v_mov_b32_e32 v41, v0
	v_mov_b32_e32 v50, v0
	v_mov_b32_e32 v51, v0
	v_mov_b32_e32 v52, v0
	v_mov_b32_e32 v53, v0
	v_mov_b32_e32 v54, v0
	v_mov_b32_e32 v55, v0
	v_mov_b32_e32 v56, v0
	v_mov_b32_e32 v57, v0
	v_mov_b32_e32 v10, v0
	v_mov_b32_e32 v11, v0
	v_mov_b32_e32 v12, v0
	v_mov_b32_e32 v13, v0
	v_mov_b32_e32 v14, v0
	v_mov_b32_e32 v15, v0
	v_mov_b32_e32 v16, v0
	v_mov_b32_e32 v17, v0
	v_mov_b32_e32 v26, v0
	v_mov_b32_e32 v27, v0
	v_mov_b32_e32 v28, v0
	v_mov_b32_e32 v29, v0
	v_mov_b32_e32 v30, v0
	v_mov_b32_e32 v31, v0
	v_mov_b32_e32 v32, v0
	v_mov_b32_e32 v33, v0
	v_mov_b32_e32 v42, v0
	v_mov_b32_e32 v43, v0
	v_mov_b32_e32 v44, v0
	v_mov_b32_e32 v45, v0
	v_mov_b32_e32 v46, v0
	v_mov_b32_e32 v47, v0
	v_mov_b32_e32 v48, v0
	v_mov_b32_e32 v49, v0
	v_mov_b32_e32 v58, v0
	v_mov_b32_e32 v59, v0
	v_mov_b32_e32 v60, v0
	v_mov_b32_e32 v61, v0
	v_mov_b32_e32 v62, v0
	v_mov_b32_e32 v63, v0
	v_mov_b32_e32 v64, v0
	v_mov_b32_e32 v65, v0
	v_mov_b32_e32 v66, v0
	v_mov_b32_e32 v67, v0
	v_mov_b32_e32 v68, v0
	v_mov_b32_e32 v69, v0
	v_mov_b32_e32 v70, v0
	v_mov_b32_e32 v71, v0
	v_mov_b32_e32 v72, v0
	v_mov_b32_e32 v73, v0
	v_mov_b32_e32 v82, v0
	v_mov_b32_e32 v83, v0
	v_mov_b32_e32 v84, v0
	v_mov_b32_e32 v85, v0
	v_mov_b32_e32 v86, v0
	v_mov_b32_e32 v87, v0
	v_mov_b32_e32 v88, v0
	v_mov_b32_e32 v89, v0
	v_mov_b32_e32 v98, v0
	v_mov_b32_e32 v99, v0
	v_mov_b32_e32 v100, v0
	v_mov_b32_e32 v101, v0
	v_mov_b32_e32 v102, v0
	v_mov_b32_e32 v103, v0
	v_mov_b32_e32 v104, v0
	v_mov_b32_e32 v105, v0
	v_mov_b32_e32 v114, v0
	v_mov_b32_e32 v115, v0
	v_mov_b32_e32 v116, v0
	v_mov_b32_e32 v117, v0
	v_mov_b32_e32 v118, v0
	v_mov_b32_e32 v119, v0
	v_mov_b32_e32 v120, v0
	v_mov_b32_e32 v121, v0
	v_mov_b32_e32 v74, v0
	v_mov_b32_e32 v75, v0
	v_mov_b32_e32 v76, v0
	v_mov_b32_e32 v77, v0
	v_mov_b32_e32 v78, v0
	v_mov_b32_e32 v79, v0
	v_mov_b32_e32 v80, v0
	v_mov_b32_e32 v81, v0
	v_mov_b32_e32 v90, v0
	v_mov_b32_e32 v91, v0
	v_mov_b32_e32 v92, v0
	v_mov_b32_e32 v93, v0
	v_mov_b32_e32 v94, v0
	v_mov_b32_e32 v95, v0
	v_mov_b32_e32 v96, v0
	v_mov_b32_e32 v97, v0
	v_mov_b32_e32 v106, v0
	v_mov_b32_e32 v107, v0
	v_mov_b32_e32 v108, v0
	v_mov_b32_e32 v109, v0
	v_mov_b32_e32 v110, v0
	v_mov_b32_e32 v111, v0
	v_mov_b32_e32 v112, v0
	v_mov_b32_e32 v113, v0
	v_mov_b32_e32 v122, v0
	v_mov_b32_e32 v123, v0
	v_mov_b32_e32 v124, v0
	v_mov_b32_e32 v125, v0
	v_mov_b32_e32 v126, v0
	v_mov_b32_e32 v127, v0
	v_mov_b32_e32 v128, v0
	v_mov_b32_e32 v129, v0
	s_cmp_eq_u32 s37, 1
	s_cbranch_scc1 .LBB0_163
	s_add_u32 s0, s22, 0xfff80080
	s_addc_u32 s1, s23, -1
	s_add_i32 s3, 0, 0x10000
	s_cmp_eq_u32 s24, 28
	s_cselect_b32 s15, s79, s1
	s_cselect_b32 s14, s78, s0
	v_add_u32_e32 v162, s3, v145
	s_cselect_b32 s1, s2, s10
	s_cselect_b32 s0, s8, s9
	s_add_i32 s6, 0, 0x14000
	ds_read_b128 v[140:143], v162
	ds_read_b128 v[148:151], v162 offset:1024
	ds_read_b128 v[172:175], v162 offset:2048
	ds_read_b128 v[190:193], v162 offset:3072
	v_add_u32_e32 v162, s6, v145
	ds_read_b128 v[194:197], v162
	ds_read_b128 v[198:201], v162 offset:1024
	ds_read_b128 v[202:205], v162 offset:2048
	ds_read_b128 v[206:209], v162 offset:3072
	v_lshl_add_u64 v[162:163], s[22:23], 0, v[136:137]
	s_add_i32 m0, s26, 0xc000
	ds_read_b128 v[210:213], v147
	ds_read_b128 v[214:217], v147 offset:1024
	ds_read_b128 v[218:221], v147 offset:2048
	ds_read_b128 v[222:225], v147 offset:3072
	ds_read_b128 v[226:229], v147 offset:4096
	ds_read_b128 v[230:233], v147 offset:5120
	ds_read_b128 v[234:237], v147 offset:6144
	ds_read_b128 v[238:241], v147 offset:7168
	global_load_lds_dwordx4 v[162:163], off
	s_add_i32 m0, s26, 0xe000
	v_lshl_add_u64 v[162:163], s[22:23], 0, v[138:139]
	global_load_lds_dwordx4 v[162:163], off
	s_waitcnt vmcnt(24)
	s_waitcnt lgkmcnt(0)
	s_barrier
	s_setprio 1
	s_waitcnt lgkmcnt(0)
	v_mfma_f32_16x16x32_bf16 v[126:129], v[140:143], v[210:213], v[126:129]
	v_mfma_f32_16x16x32_bf16 v[122:125], v[172:175], v[210:213], v[122:125]
	v_mfma_f32_16x16x32_bf16 v[110:113], v[140:143], v[218:221], v[110:113]
	v_mfma_f32_16x16x32_bf16 v[106:109], v[172:175], v[218:221], v[106:109]
	v_mfma_f32_16x16x32_bf16 v[94:97], v[140:143], v[226:229], v[94:97]
	v_mfma_f32_16x16x32_bf16 v[90:93], v[172:175], v[226:229], v[90:93]
	v_mfma_f32_16x16x32_bf16 v[78:81], v[140:143], v[234:237], v[78:81]
	v_mfma_f32_16x16x32_bf16 v[74:77], v[172:175], v[234:237], v[74:77]
	v_mfma_f32_16x16x32_bf16 v[126:129], v[148:151], v[214:217], v[126:129]
	v_mfma_f32_16x16x32_bf16 v[122:125], v[190:193], v[214:217], v[122:125]
	v_mfma_f32_16x16x32_bf16 v[110:113], v[148:151], v[222:225], v[110:113]
	v_mfma_f32_16x16x32_bf16 v[106:109], v[190:193], v[222:225], v[106:109]
	v_mfma_f32_16x16x32_bf16 v[94:97], v[148:151], v[230:233], v[94:97]
	v_mfma_f32_16x16x32_bf16 v[90:93], v[190:193], v[230:233], v[90:93]
	v_mfma_f32_16x16x32_bf16 v[78:81], v[148:151], v[238:241], v[78:81]
	v_mfma_f32_16x16x32_bf16 v[74:77], v[190:193], v[238:241], v[74:77]
	s_setprio 0
	s_setprio 1
	v_mfma_f32_16x16x32_bf16 v[118:121], v[194:197], v[210:213], v[118:121]
	v_mfma_f32_16x16x32_bf16 v[114:117], v[202:205], v[210:213], v[114:117]
	v_mfma_f32_16x16x32_bf16 v[102:105], v[194:197], v[218:221], v[102:105]
	v_mfma_f32_16x16x32_bf16 v[98:101], v[202:205], v[218:221], v[98:101]
	v_mfma_f32_16x16x32_bf16 v[86:89], v[194:197], v[226:229], v[86:89]
	v_mfma_f32_16x16x32_bf16 v[82:85], v[202:205], v[226:229], v[82:85]
	v_mfma_f32_16x16x32_bf16 v[70:73], v[194:197], v[234:237], v[70:73]
	v_mfma_f32_16x16x32_bf16 v[66:69], v[202:205], v[234:237], v[66:69]
	v_mfma_f32_16x16x32_bf16 v[118:121], v[198:201], v[214:217], v[118:121]
	v_mfma_f32_16x16x32_bf16 v[114:117], v[206:209], v[214:217], v[114:117]
	v_mfma_f32_16x16x32_bf16 v[102:105], v[198:201], v[222:225], v[102:105]
	v_mfma_f32_16x16x32_bf16 v[98:101], v[206:209], v[222:225], v[98:101]
	v_mfma_f32_16x16x32_bf16 v[86:89], v[198:201], v[230:233], v[86:89]
	v_mfma_f32_16x16x32_bf16 v[82:85], v[206:209], v[230:233], v[82:85]
	v_mfma_f32_16x16x32_bf16 v[70:73], v[198:201], v[238:241], v[70:73]
	v_mfma_f32_16x16x32_bf16 v[66:69], v[206:209], v[238:241], v[66:69]
	s_setprio 0
	s_barrier
	s_add_i32 s3, s3, s11
	v_lshl_add_u64 v[162:163], s[0:1], 0, v[4:5]
	s_mov_b32 m0, s3
	ds_read_b128 v[210:213], v147 offset:16384
	ds_read_b128 v[214:217], v147 offset:17408
	ds_read_b128 v[218:221], v147 offset:18432
	ds_read_b128 v[222:225], v147 offset:19456
	ds_read_b128 v[226:229], v147 offset:20480
	ds_read_b128 v[230:233], v147 offset:21504
	ds_read_b128 v[234:237], v147 offset:22528
	ds_read_b128 v[238:241], v147 offset:23552
	global_load_lds_dwordx4 v[162:163], off
	s_add_i32 m0, s3, 0x2000
	s_add_u32 s4, s0, 0x80000
	v_lshl_add_u64 v[166:167], s[0:1], 0, v[130:131]
	s_addc_u32 s5, s1, 0
	s_add_i32 s3, s6, s11
	global_load_lds_dwordx4 v[166:167], off
	v_lshl_add_u64 v[176:177], s[4:5], 0, v[4:5]
	s_mov_b32 m0, s3
	v_lshl_add_u64 v[180:181], s[14:15], 0, v[132:133]
	global_load_lds_dwordx4 v[176:177], off
	s_add_i32 m0, s3, 0x2000
	v_lshl_add_u64 v[176:177], s[4:5], 0, v[130:131]
	global_load_lds_dwordx4 v[176:177], off
	s_mov_b32 m0, s26
	v_lshl_add_u64 v[176:177], s[14:15], 0, v[134:135]
	global_load_lds_dwordx4 v[176:177], off
	s_mov_b32 m0, s27
	s_nop 0
	global_load_lds_dwordx4 v[180:181], off
	s_waitcnt vmcnt(24)
	s_waitcnt lgkmcnt(0)
	s_barrier
	s_setprio 1
	s_waitcnt lgkmcnt(0)
	v_mfma_f32_16x16x32_bf16 v[62:65], v[140:143], v[210:213], v[62:65]
	v_mfma_f32_16x16x32_bf16 v[58:61], v[172:175], v[210:213], v[58:61]
	v_mfma_f32_16x16x32_bf16 v[46:49], v[140:143], v[218:221], v[46:49]
	v_mfma_f32_16x16x32_bf16 v[42:45], v[172:175], v[218:221], v[42:45]
	v_mfma_f32_16x16x32_bf16 v[30:33], v[140:143], v[226:229], v[30:33]
	v_mfma_f32_16x16x32_bf16 v[26:29], v[172:175], v[226:229], v[26:29]
	v_mfma_f32_16x16x32_bf16 v[14:17], v[140:143], v[234:237], v[14:17]
	v_mfma_f32_16x16x32_bf16 v[10:13], v[172:175], v[234:237], v[10:13]
	v_mfma_f32_16x16x32_bf16 v[62:65], v[148:151], v[214:217], v[62:65]
	v_mfma_f32_16x16x32_bf16 v[58:61], v[190:193], v[214:217], v[58:61]
	v_mfma_f32_16x16x32_bf16 v[46:49], v[148:151], v[222:225], v[46:49]
	v_mfma_f32_16x16x32_bf16 v[42:45], v[190:193], v[222:225], v[42:45]
	v_mfma_f32_16x16x32_bf16 v[30:33], v[148:151], v[230:233], v[30:33]
	v_mfma_f32_16x16x32_bf16 v[26:29], v[190:193], v[230:233], v[26:29]
	v_mfma_f32_16x16x32_bf16 v[14:17], v[148:151], v[238:241], v[14:17]
	v_mfma_f32_16x16x32_bf16 v[10:13], v[190:193], v[238:241], v[10:13]
	s_setprio 0
	s_setprio 1
	v_mfma_f32_16x16x32_bf16 v[54:57], v[194:197], v[210:213], v[54:57]
	v_mfma_f32_16x16x32_bf16 v[50:53], v[202:205], v[210:213], v[50:53]
	v_mfma_f32_16x16x32_bf16 v[38:41], v[194:197], v[218:221], v[38:41]
	v_mfma_f32_16x16x32_bf16 v[34:37], v[202:205], v[218:221], v[34:37]
	v_mfma_f32_16x16x32_bf16 v[22:25], v[194:197], v[226:229], v[22:25]
	v_mfma_f32_16x16x32_bf16 v[18:21], v[202:205], v[226:229], v[18:21]
	v_mfma_f32_16x16x32_bf16 v[6:9], v[194:197], v[234:237], v[6:9]
	v_mfma_f32_16x16x32_bf16 v[0:3], v[202:205], v[234:237], v[0:3]
	v_mfma_f32_16x16x32_bf16 v[54:57], v[198:201], v[214:217], v[54:57]
	v_mfma_f32_16x16x32_bf16 v[50:53], v[206:209], v[214:217], v[50:53]
	v_mfma_f32_16x16x32_bf16 v[38:41], v[198:201], v[222:225], v[38:41]
	v_mfma_f32_16x16x32_bf16 v[34:37], v[206:209], v[222:225], v[34:37]
	v_mfma_f32_16x16x32_bf16 v[22:25], v[198:201], v[230:233], v[22:25]
	v_mfma_f32_16x16x32_bf16 v[18:21], v[206:209], v[230:233], v[18:21]
	v_mfma_f32_16x16x32_bf16 v[6:9], v[198:201], v[238:241], v[6:9]
	v_mfma_f32_16x16x32_bf16 v[0:3], v[206:209], v[238:241], v[0:3]
	s_setprio 0
	s_barrier
	s_branch .Lpeelmid_163
.LBB0_163:
	s_add_u32 s0, s22, 0xfff80080
	s_addc_u32 s1, s23, -1
	s_add_i32 s3, 0, 0x10000
	s_cmp_eq_u32 s24, 28
	s_cselect_b32 s15, s79, s1
	s_cselect_b32 s14, s78, s0
	v_add_u32_e32 v162, s3, v145
	s_cselect_b32 s1, s2, s10
	s_cselect_b32 s0, s8, s9
	s_add_i32 s6, 0, 0x14000
	ds_read_b128 v[140:143], v162
	ds_read_b128 v[148:151], v162 offset:1024
	ds_read_b128 v[172:175], v162 offset:2048
	ds_read_b128 v[190:193], v162 offset:3072
	v_add_u32_e32 v162, s6, v145
	ds_read_b128 v[194:197], v162
	ds_read_b128 v[198:201], v162 offset:1024
	ds_read_b128 v[202:205], v162 offset:2048
	ds_read_b128 v[206:209], v162 offset:3072
	v_lshl_add_u64 v[162:163], s[22:23], 0, v[136:137]
	s_add_i32 m0, s26, 0xc000
	ds_read_b128 v[210:213], v147
	ds_read_b128 v[214:217], v147 offset:1024
	ds_read_b128 v[218:221], v147 offset:2048
	ds_read_b128 v[222:225], v147 offset:3072
	ds_read_b128 v[226:229], v147 offset:4096
	ds_read_b128 v[230:233], v147 offset:5120
	ds_read_b128 v[234:237], v147 offset:6144
	ds_read_b128 v[238:241], v147 offset:7168
	global_load_lds_dwordx4 v[162:163], off
	s_add_i32 m0, s26, 0xe000
	v_lshl_add_u64 v[162:163], s[22:23], 0, v[138:139]
	global_load_lds_dwordx4 v[162:163], off
	s_waitcnt vmcnt(8)
	s_waitcnt lgkmcnt(0)
	s_barrier
	s_setprio 1
	s_waitcnt lgkmcnt(0)
	v_mfma_f32_16x16x32_bf16 v[126:129], v[140:143], v[210:213], v[126:129]
	v_mfma_f32_16x16x32_bf16 v[122:125], v[172:175], v[210:213], v[122:125]
	v_mfma_f32_16x16x32_bf16 v[110:113], v[140:143], v[218:221], v[110:113]
	v_mfma_f32_16x16x32_bf16 v[106:109], v[172:175], v[218:221], v[106:109]
	v_mfma_f32_16x16x32_bf16 v[94:97], v[140:143], v[226:229], v[94:97]
	v_mfma_f32_16x16x32_bf16 v[90:93], v[172:175], v[226:229], v[90:93]
	v_mfma_f32_16x16x32_bf16 v[78:81], v[140:143], v[234:237], v[78:81]
	v_mfma_f32_16x16x32_bf16 v[74:77], v[172:175], v[234:237], v[74:77]
	v_mfma_f32_16x16x32_bf16 v[126:129], v[148:151], v[214:217], v[126:129]
	v_mfma_f32_16x16x32_bf16 v[122:125], v[190:193], v[214:217], v[122:125]
	v_mfma_f32_16x16x32_bf16 v[110:113], v[148:151], v[222:225], v[110:113]
	v_mfma_f32_16x16x32_bf16 v[106:109], v[190:193], v[222:225], v[106:109]
	v_mfma_f32_16x16x32_bf16 v[94:97], v[148:151], v[230:233], v[94:97]
	v_mfma_f32_16x16x32_bf16 v[90:93], v[190:193], v[230:233], v[90:93]
	v_mfma_f32_16x16x32_bf16 v[78:81], v[148:151], v[238:241], v[78:81]
	v_mfma_f32_16x16x32_bf16 v[74:77], v[190:193], v[238:241], v[74:77]
	s_setprio 0
	s_setprio 1
	v_mfma_f32_16x16x32_bf16 v[118:121], v[194:197], v[210:213], v[118:121]
	v_mfma_f32_16x16x32_bf16 v[114:117], v[202:205], v[210:213], v[114:117]
	v_mfma_f32_16x16x32_bf16 v[102:105], v[194:197], v[218:221], v[102:105]
	v_mfma_f32_16x16x32_bf16 v[98:101], v[202:205], v[218:221], v[98:101]
	v_mfma_f32_16x16x32_bf16 v[86:89], v[194:197], v[226:229], v[86:89]
	v_mfma_f32_16x16x32_bf16 v[82:85], v[202:205], v[226:229], v[82:85]
	v_mfma_f32_16x16x32_bf16 v[70:73], v[194:197], v[234:237], v[70:73]
	v_mfma_f32_16x16x32_bf16 v[66:69], v[202:205], v[234:237], v[66:69]
	v_mfma_f32_16x16x32_bf16 v[118:121], v[198:201], v[214:217], v[118:121]
	v_mfma_f32_16x16x32_bf16 v[114:117], v[206:209], v[214:217], v[114:117]
	v_mfma_f32_16x16x32_bf16 v[102:105], v[198:201], v[222:225], v[102:105]
	v_mfma_f32_16x16x32_bf16 v[98:101], v[206:209], v[222:225], v[98:101]
	v_mfma_f32_16x16x32_bf16 v[86:89], v[198:201], v[230:233], v[86:89]
	v_mfma_f32_16x16x32_bf16 v[82:85], v[206:209], v[230:233], v[82:85]
	v_mfma_f32_16x16x32_bf16 v[70:73], v[198:201], v[238:241], v[70:73]
	v_mfma_f32_16x16x32_bf16 v[66:69], v[206:209], v[238:241], v[66:69]
	s_setprio 0
	s_barrier
	s_add_i32 s3, s3, s11
	v_lshl_add_u64 v[162:163], s[0:1], 0, v[4:5]
	s_mov_b32 m0, s3
	ds_read_b128 v[210:213], v147 offset:16384
	ds_read_b128 v[214:217], v147 offset:17408
	ds_read_b128 v[218:221], v147 offset:18432
	ds_read_b128 v[222:225], v147 offset:19456
	ds_read_b128 v[226:229], v147 offset:20480
	ds_read_b128 v[230:233], v147 offset:21504
	ds_read_b128 v[234:237], v147 offset:22528
	ds_read_b128 v[238:241], v147 offset:23552
	global_load_lds_dwordx4 v[162:163], off
	s_add_i32 m0, s3, 0x2000
	s_add_u32 s4, s0, 0x80000
	v_lshl_add_u64 v[166:167], s[0:1], 0, v[130:131]
	s_addc_u32 s5, s1, 0
	s_add_i32 s3, s6, s11
	global_load_lds_dwordx4 v[166:167], off
	v_lshl_add_u64 v[176:177], s[4:5], 0, v[4:5]
	s_mov_b32 m0, s3
	v_lshl_add_u64 v[180:181], s[14:15], 0, v[132:133]
	global_load_lds_dwordx4 v[176:177], off
	s_add_i32 m0, s3, 0x2000
	v_lshl_add_u64 v[176:177], s[4:5], 0, v[130:131]
	global_load_lds_dwordx4 v[176:177], off
	s_mov_b32 m0, s26
	v_lshl_add_u64 v[176:177], s[14:15], 0, v[134:135]
	global_load_lds_dwordx4 v[176:177], off
	s_mov_b32 m0, s27
	s_nop 0
	global_load_lds_dwordx4 v[180:181], off
	s_waitcnt vmcnt(8)
	s_waitcnt lgkmcnt(0)
	s_barrier
	s_setprio 1
	s_waitcnt lgkmcnt(0)
	v_mfma_f32_16x16x32_bf16 v[62:65], v[140:143], v[210:213], v[62:65]
	v_mfma_f32_16x16x32_bf16 v[58:61], v[172:175], v[210:213], v[58:61]
	v_mfma_f32_16x16x32_bf16 v[46:49], v[140:143], v[218:221], v[46:49]
	v_mfma_f32_16x16x32_bf16 v[42:45], v[172:175], v[218:221], v[42:45]
	v_mfma_f32_16x16x32_bf16 v[30:33], v[140:143], v[226:229], v[30:33]
	v_mfma_f32_16x16x32_bf16 v[26:29], v[172:175], v[226:229], v[26:29]
	v_mfma_f32_16x16x32_bf16 v[14:17], v[140:143], v[234:237], v[14:17]
	v_mfma_f32_16x16x32_bf16 v[10:13], v[172:175], v[234:237], v[10:13]
	v_mfma_f32_16x16x32_bf16 v[62:65], v[148:151], v[214:217], v[62:65]
	v_mfma_f32_16x16x32_bf16 v[58:61], v[190:193], v[214:217], v[58:61]
	v_mfma_f32_16x16x32_bf16 v[46:49], v[148:151], v[222:225], v[46:49]
	v_mfma_f32_16x16x32_bf16 v[42:45], v[190:193], v[222:225], v[42:45]
	v_mfma_f32_16x16x32_bf16 v[30:33], v[148:151], v[230:233], v[30:33]
	v_mfma_f32_16x16x32_bf16 v[26:29], v[190:193], v[230:233], v[26:29]
	v_mfma_f32_16x16x32_bf16 v[14:17], v[148:151], v[238:241], v[14:17]
	v_mfma_f32_16x16x32_bf16 v[10:13], v[190:193], v[238:241], v[10:13]
	s_setprio 0
	s_setprio 1
	v_mfma_f32_16x16x32_bf16 v[54:57], v[194:197], v[210:213], v[54:57]
	v_mfma_f32_16x16x32_bf16 v[50:53], v[202:205], v[210:213], v[50:53]
	v_mfma_f32_16x16x32_bf16 v[38:41], v[194:197], v[218:221], v[38:41]
	v_mfma_f32_16x16x32_bf16 v[34:37], v[202:205], v[218:221], v[34:37]
	v_mfma_f32_16x16x32_bf16 v[22:25], v[194:197], v[226:229], v[22:25]
	v_mfma_f32_16x16x32_bf16 v[18:21], v[202:205], v[226:229], v[18:21]
	v_mfma_f32_16x16x32_bf16 v[6:9], v[194:197], v[234:237], v[6:9]
	v_mfma_f32_16x16x32_bf16 v[0:3], v[202:205], v[234:237], v[0:3]
	v_mfma_f32_16x16x32_bf16 v[54:57], v[198:201], v[214:217], v[54:57]
	v_mfma_f32_16x16x32_bf16 v[50:53], v[206:209], v[214:217], v[50:53]
	v_mfma_f32_16x16x32_bf16 v[38:41], v[198:201], v[222:225], v[38:41]
	v_mfma_f32_16x16x32_bf16 v[34:37], v[206:209], v[222:225], v[34:37]
	v_mfma_f32_16x16x32_bf16 v[22:25], v[198:201], v[230:233], v[22:25]
	v_mfma_f32_16x16x32_bf16 v[18:21], v[206:209], v[230:233], v[18:21]
	v_mfma_f32_16x16x32_bf16 v[6:9], v[198:201], v[238:241], v[6:9]
	v_mfma_f32_16x16x32_bf16 v[0:3], v[206:209], v[238:241], v[0:3]
	s_setprio 0
	s_barrier
.Lpeelmid_163:
	s_add_i32 s3, 0, 0x18000
	v_add_u32_e32 v164, s3, v145
	s_add_i32 s6, 0, 0x1c000
	ds_read_b128 v[140:143], v164
	ds_read_b128 v[148:151], v164 offset:1024
	ds_read_b128 v[172:175], v164 offset:2048
	ds_read_b128 v[190:193], v164 offset:3072
	v_add_u32_e32 v164, s6, v145
	ds_read_b128 v[194:197], v164
	ds_read_b128 v[198:201], v164 offset:1024
	ds_read_b128 v[202:205], v164 offset:2048
	ds_read_b128 v[206:209], v164 offset:3072
	s_add_u32 s4, s14, 0x80000
	s_addc_u32 s5, s15, 0
	s_mov_b32 m0, s30
	v_lshl_add_u64 v[242:243], s[4:5], 0, v[134:135]
	ds_read_b128 v[210:213], v147 offset:32768
	ds_read_b128 v[214:217], v147 offset:33792
	ds_read_b128 v[218:221], v147 offset:34816
	ds_read_b128 v[222:225], v147 offset:35840
	ds_read_b128 v[226:229], v147 offset:36864
	ds_read_b128 v[230:233], v147 offset:37888
	ds_read_b128 v[234:237], v147 offset:38912
	ds_read_b128 v[238:241], v147 offset:39936
	global_load_lds_dwordx4 v[242:243], off
	s_mov_b32 m0, s31
	v_lshl_add_u64 v[242:243], s[4:5], 0, v[132:133]
	global_load_lds_dwordx4 v[242:243], off
	s_waitcnt vmcnt(8)
	s_waitcnt lgkmcnt(0)
	s_barrier
	s_setprio 1
	s_waitcnt lgkmcnt(0)
	v_mfma_f32_16x16x32_bf16 v[126:129], v[140:143], v[210:213], v[126:129]
	v_mfma_f32_16x16x32_bf16 v[122:125], v[172:175], v[210:213], v[122:125]
	v_mfma_f32_16x16x32_bf16 v[110:113], v[140:143], v[218:221], v[110:113]
	v_mfma_f32_16x16x32_bf16 v[106:109], v[172:175], v[218:221], v[106:109]
	v_mfma_f32_16x16x32_bf16 v[94:97], v[140:143], v[226:229], v[94:97]
	v_mfma_f32_16x16x32_bf16 v[90:93], v[172:175], v[226:229], v[90:93]
	v_mfma_f32_16x16x32_bf16 v[78:81], v[140:143], v[234:237], v[78:81]
	v_mfma_f32_16x16x32_bf16 v[74:77], v[172:175], v[234:237], v[74:77]
	v_mfma_f32_16x16x32_bf16 v[126:129], v[148:151], v[214:217], v[126:129]
	v_mfma_f32_16x16x32_bf16 v[122:125], v[190:193], v[214:217], v[122:125]
	v_mfma_f32_16x16x32_bf16 v[110:113], v[148:151], v[222:225], v[110:113]
	v_mfma_f32_16x16x32_bf16 v[106:109], v[190:193], v[222:225], v[106:109]
	v_mfma_f32_16x16x32_bf16 v[94:97], v[148:151], v[230:233], v[94:97]
	v_mfma_f32_16x16x32_bf16 v[90:93], v[190:193], v[230:233], v[90:93]
	v_mfma_f32_16x16x32_bf16 v[78:81], v[148:151], v[238:241], v[78:81]
	v_mfma_f32_16x16x32_bf16 v[74:77], v[190:193], v[238:241], v[74:77]
	s_setprio 0
	s_setprio 1
	v_mfma_f32_16x16x32_bf16 v[118:121], v[194:197], v[210:213], v[118:121]
	v_mfma_f32_16x16x32_bf16 v[114:117], v[202:205], v[210:213], v[114:117]
	v_mfma_f32_16x16x32_bf16 v[102:105], v[194:197], v[218:221], v[102:105]
	v_mfma_f32_16x16x32_bf16 v[98:101], v[202:205], v[218:221], v[98:101]
	v_mfma_f32_16x16x32_bf16 v[86:89], v[194:197], v[226:229], v[86:89]
	v_mfma_f32_16x16x32_bf16 v[82:85], v[202:205], v[226:229], v[82:85]
	v_mfma_f32_16x16x32_bf16 v[70:73], v[194:197], v[234:237], v[70:73]
	v_mfma_f32_16x16x32_bf16 v[66:69], v[202:205], v[234:237], v[66:69]
	v_mfma_f32_16x16x32_bf16 v[118:121], v[198:201], v[214:217], v[118:121]
	v_mfma_f32_16x16x32_bf16 v[114:117], v[206:209], v[214:217], v[114:117]
	v_mfma_f32_16x16x32_bf16 v[102:105], v[198:201], v[222:225], v[102:105]
	v_mfma_f32_16x16x32_bf16 v[98:101], v[206:209], v[222:225], v[98:101]
	v_mfma_f32_16x16x32_bf16 v[86:89], v[198:201], v[230:233], v[86:89]
	v_mfma_f32_16x16x32_bf16 v[82:85], v[206:209], v[230:233], v[82:85]
	v_mfma_f32_16x16x32_bf16 v[70:73], v[198:201], v[238:241], v[70:73]
	v_mfma_f32_16x16x32_bf16 v[66:69], v[206:209], v[238:241], v[66:69]
	s_setprio 0
	s_barrier
	s_add_i32 s3, s3, s11
	v_lshl_add_u64 v[162:163], v[162:163], 0, s[70:71]
	s_mov_b32 m0, s3
	ds_read_b128 v[210:213], v147 offset:49152
	ds_read_b128 v[214:217], v147 offset:50176
	ds_read_b128 v[218:221], v147 offset:51200
	ds_read_b128 v[222:225], v147 offset:52224
	ds_read_b128 v[226:229], v147 offset:53248
	ds_read_b128 v[230:233], v147 offset:54272
	ds_read_b128 v[234:237], v147 offset:55296
	ds_read_b128 v[238:241], v147 offset:56320
	global_load_lds_dwordx4 v[162:163], off
	s_add_i32 m0, s3, 0x2000
	s_add_u32 s0, s0, 0x80080
	v_lshl_add_u64 v[162:163], v[166:167], 0, s[70:71]
	s_addc_u32 s1, s1, 0
	s_add_i32 s3, s6, s11
	global_load_lds_dwordx4 v[162:163], off
	s_mov_b32 m0, s3
	v_lshl_add_u64 v[162:163], s[0:1], 0, v[4:5]
	global_load_lds_dwordx4 v[162:163], off
	s_add_i32 m0, s3, 0x2000
	v_lshl_add_u64 v[162:163], s[0:1], 0, v[130:131]
	global_load_lds_dwordx4 v[162:163], off
	s_mov_b32 m0, s35
	v_lshl_add_u64 v[162:163], v[176:177], 0, s[70:71]
	global_load_lds_dwordx4 v[162:163], off
	s_mov_b32 m0, s36
	v_lshl_add_u64 v[162:163], v[180:181], 0, s[70:71]
	global_load_lds_dwordx4 v[162:163], off
	s_waitcnt vmcnt(8)
	s_waitcnt lgkmcnt(0)
	s_barrier
	s_setprio 1
	s_waitcnt lgkmcnt(0)
	v_mfma_f32_16x16x32_bf16 v[62:65], v[140:143], v[210:213], v[62:65]
	v_mfma_f32_16x16x32_bf16 v[58:61], v[172:175], v[210:213], v[58:61]
	v_mfma_f32_16x16x32_bf16 v[46:49], v[140:143], v[218:221], v[46:49]
	v_mfma_f32_16x16x32_bf16 v[42:45], v[172:175], v[218:221], v[42:45]
	v_mfma_f32_16x16x32_bf16 v[30:33], v[140:143], v[226:229], v[30:33]
	v_mfma_f32_16x16x32_bf16 v[26:29], v[172:175], v[226:229], v[26:29]
	v_mfma_f32_16x16x32_bf16 v[14:17], v[140:143], v[234:237], v[14:17]
	v_mfma_f32_16x16x32_bf16 v[10:13], v[172:175], v[234:237], v[10:13]
	v_mfma_f32_16x16x32_bf16 v[62:65], v[148:151], v[214:217], v[62:65]
	v_mfma_f32_16x16x32_bf16 v[58:61], v[190:193], v[214:217], v[58:61]
	v_mfma_f32_16x16x32_bf16 v[46:49], v[148:151], v[222:225], v[46:49]
	v_mfma_f32_16x16x32_bf16 v[42:45], v[190:193], v[222:225], v[42:45]
	v_mfma_f32_16x16x32_bf16 v[30:33], v[148:151], v[230:233], v[30:33]
	v_mfma_f32_16x16x32_bf16 v[26:29], v[190:193], v[230:233], v[26:29]
	v_mfma_f32_16x16x32_bf16 v[14:17], v[148:151], v[238:241], v[14:17]
	v_mfma_f32_16x16x32_bf16 v[10:13], v[190:193], v[238:241], v[10:13]
	s_setprio 0
	s_setprio 1
	v_mfma_f32_16x16x32_bf16 v[54:57], v[194:197], v[210:213], v[54:57]
	v_mfma_f32_16x16x32_bf16 v[50:53], v[202:205], v[210:213], v[50:53]
	v_mfma_f32_16x16x32_bf16 v[38:41], v[194:197], v[218:221], v[38:41]
	v_mfma_f32_16x16x32_bf16 v[34:37], v[202:205], v[218:221], v[34:37]
	v_mfma_f32_16x16x32_bf16 v[22:25], v[194:197], v[226:229], v[22:25]
	v_mfma_f32_16x16x32_bf16 v[18:21], v[202:205], v[226:229], v[18:21]
	v_mfma_f32_16x16x32_bf16 v[6:9], v[194:197], v[234:237], v[6:9]
	v_mfma_f32_16x16x32_bf16 v[0:3], v[202:205], v[234:237], v[0:3]
	v_mfma_f32_16x16x32_bf16 v[54:57], v[198:201], v[214:217], v[54:57]
	v_mfma_f32_16x16x32_bf16 v[50:53], v[206:209], v[214:217], v[50:53]
	v_mfma_f32_16x16x32_bf16 v[38:41], v[198:201], v[222:225], v[38:41]
	v_mfma_f32_16x16x32_bf16 v[34:37], v[206:209], v[222:225], v[34:37]
	v_mfma_f32_16x16x32_bf16 v[22:25], v[198:201], v[230:233], v[22:25]
	v_mfma_f32_16x16x32_bf16 v[18:21], v[206:209], v[230:233], v[18:21]
	v_mfma_f32_16x16x32_bf16 v[6:9], v[198:201], v[238:241], v[6:9]
	v_mfma_f32_16x16x32_bf16 v[0:3], v[206:209], v[238:241], v[0:3]
	s_setprio 0
	s_barrier
	s_add_i32 s24, s24, 2
	s_add_u32 s22, s22, 0x100
	s_addc_u32 s23, s23, 0
	s_add_u32 s9, s9, 0x100
	s_addc_u32 s10, s10, 0
	s_cmp_gt_u32 s24, 29
	s_cbranch_scc0 .LBB0_163
	s_and_b64 vcc, exec, s[46:47]
	s_cbranch_vccz .LBB0_166
	s_barrier

.LBB0_204:
	s_ashr_i32 s49, s48, 31
	s_lshl_b64 s[2:3], s[48:49], 19
	v_readlane_b32 s4, v253, 17
	v_readlane_b32 s5, v253, 18
	s_add_u32 s84, s4, s2
	s_addc_u32 s85, s5, s3
	s_and_b64 s[2:3], s[42:43], exec
	s_cselect_b32 s2, s85, s15
	s_cselect_b32 s8, s84, s14
	s_add_u32 s22, s0, 0x40080
	s_addc_u32 s23, s1, 0
	s_add_u32 s9, s14, 0x100
	v_mov_b32_e32 v0, 0
	s_addc_u32 s10, s15, 0
	s_mov_b32 s24, -2
	v_mov_b32_e32 v1, v0
	v_mov_b32_e32 v2, v0
	v_mov_b32_e32 v3, v0
	v_mov_b32_e32 v6, v0
	v_mov_b32_e32 v7, v0
	v_mov_b32_e32 v8, v0
	v_mov_b32_e32 v9, v0
	v_mov_b32_e32 v10, v0
	v_mov_b32_e32 v11, v0
	v_mov_b32_e32 v12, v0
	v_mov_b32_e32 v13, v0
	v_mov_b32_e32 v14, v0
	v_mov_b32_e32 v15, v0
	v_mov_b32_e32 v16, v0
	v_mov_b32_e32 v17, v0
	v_mov_b32_e32 v18, v0
	v_mov_b32_e32 v19, v0
	v_mov_b32_e32 v20, v0
	v_mov_b32_e32 v21, v0
	v_mov_b32_e32 v22, v0
	v_mov_b32_e32 v23, v0
	v_mov_b32_e32 v24, v0
	v_mov_b32_e32 v25, v0
	v_mov_b32_e32 v26, v0
	v_mov_b32_e32 v27, v0
	v_mov_b32_e32 v28, v0
	v_mov_b32_e32 v29, v0
	v_mov_b32_e32 v30, v0
	v_mov_b32_e32 v31, v0
	v_mov_b32_e32 v32, v0
	v_mov_b32_e32 v33, v0
	v_mov_b32_e32 v66, v0
	v_mov_b32_e32 v67, v0
	v_mov_b32_e32 v68, v0
	v_mov_b32_e32 v69, v0
	v_mov_b32_e32 v70, v0
	v_mov_b32_e32 v71, v0
	v_mov_b32_e32 v72, v0
	v_mov_b32_e32 v73, v0
	v_mov_b32_e32 v74, v0
	v_mov_b32_e32 v75, v0
	v_mov_b32_e32 v76, v0
	v_mov_b32_e32 v77, v0
	v_mov_b32_e32 v78, v0
	v_mov_b32_e32 v79, v0
	v_mov_b32_e32 v80, v0
	v_mov_b32_e32 v81, v0
	v_mov_b32_e32 v82, v0
	v_mov_b32_e32 v83, v0
	v_mov_b32_e32 v84, v0
	v_mov_b32_e32 v85, v0
	v_mov_b32_e32 v86, v0
	v_mov_b32_e32 v87, v0
	v_mov_b32_e32 v88, v0
	v_mov_b32_e32 v89, v0
	v_mov_b32_e32 v90, v0
	v_mov_b32_e32 v91, v0
	v_mov_b32_e32 v92, v0
	v_mov_b32_e32 v93, v0
	v_mov_b32_e32 v94, v0
	v_mov_b32_e32 v95, v0
	v_mov_b32_e32 v96, v0
	v_mov_b32_e32 v97, v0
	v_mov_b32_e32 v34, v0
	v_mov_b32_e32 v35, v0
	v_mov_b32_e32 v36, v0
	v_mov_b32_e32 v37, v0
	v_mov_b32_e32 v38, v0
	v_mov_b32_e32 v39, v0
	v_mov_b32_e32 v40, v0
	v_mov_b32_e32 v41, v0
	v_mov_b32_e32 v42, v0
	v_mov_b32_e32 v43, v0
	v_mov_b32_e32 v44, v0
	v_mov_b32_e32 v45, v0
	v_mov_b32_e32 v46, v0
	v_mov_b32_e32 v47, v0
	v_mov_b32_e32 v48, v0
	v_mov_b32_e32 v49, v0
	v_mov_b32_e32 v50, v0
	v_mov_b32_e32 v51, v0
	v_mov_b32_e32 v52, v0
	v_mov_b32_e32 v53, v0
	v_mov_b32_e32 v54, v0
	v_mov_b32_e32 v55, v0
	v_mov_b32_e32 v56, v0
	v_mov_b32_e32 v57, v0
	v_mov_b32_e32 v58, v0
	v_mov_b32_e32 v59, v0
	v_mov_b32_e32 v60, v0
	v_mov_b32_e32 v61, v0
	v_mov_b32_e32 v62, v0
	v_mov_b32_e32 v63, v0
	v_mov_b32_e32 v64, v0
	v_mov_b32_e32 v65, v0
	v_mov_b32_e32 v98, v0
	v_mov_b32_e32 v99, v0
	v_mov_b32_e32 v100, v0
	v_mov_b32_e32 v101, v0
	v_mov_b32_e32 v102, v0
	v_mov_b32_e32 v103, v0
	v_mov_b32_e32 v104, v0
	v_mov_b32_e32 v105, v0
	v_mov_b32_e32 v106, v0
	v_mov_b32_e32 v107, v0
	v_mov_b32_e32 v108, v0
	v_mov_b32_e32 v109, v0
	v_mov_b32_e32 v110, v0
	v_mov_b32_e32 v111, v0
	v_mov_b32_e32 v112, v0
	v_mov_b32_e32 v113, v0
	v_mov_b32_e32 v114, v0
	v_mov_b32_e32 v115, v0
	v_mov_b32_e32 v116, v0
	v_mov_b32_e32 v117, v0
	v_mov_b32_e32 v118, v0
	v_mov_b32_e32 v119, v0
	v_mov_b32_e32 v120, v0
	v_mov_b32_e32 v121, v0
	v_mov_b32_e32 v122, v0
	v_mov_b32_e32 v123, v0
	v_mov_b32_e32 v124, v0
	v_mov_b32_e32 v125, v0
	v_mov_b32_e32 v126, v0
	v_mov_b32_e32 v127, v0
	v_mov_b32_e32 v128, v0
	v_mov_b32_e32 v129, v0
	s_cmp_eq_u32 s37, 1
	s_cbranch_scc1 .LBB0_205
	s_add_u32 s0, s22, 0xfffc0080
	s_addc_u32 s1, s23, -1
	s_add_i32 s3, 0, 0x10000
	s_cmp_eq_u32 s24, 12
	s_cselect_b32 s15, s83, s1
	s_cselect_b32 s14, s82, s0
	v_add_u32_e32 v144, s3, v168
	s_cselect_b32 s1, s2, s10
	s_cselect_b32 s0, s8, s9
	s_add_i32 s6, 0, 0x14000
	ds_read_b128 v[140:143], v144
	ds_read_b128 v[174:177], v144 offset:1024
	ds_read_b128 v[190:193], v144 offset:2048
	ds_read_b128 v[194:197], v144 offset:3072
	v_add_u32_e32 v144, s6, v168
	ds_read_b128 v[198:201], v144
	ds_read_b128 v[202:205], v144 offset:1024
	ds_read_b128 v[206:209], v144 offset:2048
	ds_read_b128 v[210:213], v144 offset:3072
	v_lshl_add_u64 v[144:145], s[22:23], 0, v[136:137]
	s_add_i32 m0, s27, 0xc000
	ds_read_b128 v[214:217], v172
	ds_read_b128 v[218:221], v172 offset:1024
	ds_read_b128 v[222:225], v172 offset:2048
	ds_read_b128 v[226:229], v172 offset:3072
	ds_read_b128 v[230:233], v172 offset:4096
	ds_read_b128 v[234:237], v172 offset:5120
	ds_read_b128 v[238:241], v172 offset:6144
	ds_read_b128 v[242:245], v172 offset:7168
	global_load_lds_dwordx4 v[144:145], off
	s_add_i32 m0, s27, 0xe000
	v_lshl_add_u64 v[144:145], s[22:23], 0, v[138:139]
	global_load_lds_dwordx4 v[144:145], off
	s_waitcnt vmcnt(24)
	s_waitcnt lgkmcnt(0)
	s_barrier
	s_setprio 1
	s_waitcnt lgkmcnt(0)
	v_mfma_f32_16x16x32_bf16 v[126:129], v[140:143], v[214:217], v[126:129]
	v_mfma_f32_16x16x32_bf16 v[122:125], v[190:193], v[214:217], v[122:125]
	v_mfma_f32_16x16x32_bf16 v[118:121], v[140:143], v[222:225], v[118:121]
	v_mfma_f32_16x16x32_bf16 v[114:117], v[190:193], v[222:225], v[114:117]
	v_mfma_f32_16x16x32_bf16 v[110:113], v[140:143], v[230:233], v[110:113]
	v_mfma_f32_16x16x32_bf16 v[106:109], v[190:193], v[230:233], v[106:109]
	v_mfma_f32_16x16x32_bf16 v[102:105], v[140:143], v[238:241], v[102:105]
	v_mfma_f32_16x16x32_bf16 v[98:101], v[190:193], v[238:241], v[98:101]
	v_mfma_f32_16x16x32_bf16 v[126:129], v[174:177], v[218:221], v[126:129]
	v_mfma_f32_16x16x32_bf16 v[122:125], v[194:197], v[218:221], v[122:125]
	v_mfma_f32_16x16x32_bf16 v[118:121], v[174:177], v[226:229], v[118:121]
	v_mfma_f32_16x16x32_bf16 v[114:117], v[194:197], v[226:229], v[114:117]
	v_mfma_f32_16x16x32_bf16 v[110:113], v[174:177], v[234:237], v[110:113]
	v_mfma_f32_16x16x32_bf16 v[106:109], v[194:197], v[234:237], v[106:109]
	v_mfma_f32_16x16x32_bf16 v[102:105], v[174:177], v[242:245], v[102:105]
	v_mfma_f32_16x16x32_bf16 v[98:101], v[194:197], v[242:245], v[98:101]
	s_setprio 0
	s_setprio 1
	v_mfma_f32_16x16x32_bf16 v[62:65], v[198:201], v[214:217], v[62:65]
	v_mfma_f32_16x16x32_bf16 v[58:61], v[206:209], v[214:217], v[58:61]
	v_mfma_f32_16x16x32_bf16 v[54:57], v[198:201], v[222:225], v[54:57]
	v_mfma_f32_16x16x32_bf16 v[50:53], v[206:209], v[222:225], v[50:53]
	v_mfma_f32_16x16x32_bf16 v[46:49], v[198:201], v[230:233], v[46:49]
	v_mfma_f32_16x16x32_bf16 v[42:45], v[206:209], v[230:233], v[42:45]
	v_mfma_f32_16x16x32_bf16 v[38:41], v[198:201], v[238:241], v[38:41]
	v_mfma_f32_16x16x32_bf16 v[34:37], v[206:209], v[238:241], v[34:37]
	v_mfma_f32_16x16x32_bf16 v[62:65], v[202:205], v[218:221], v[62:65]
	v_mfma_f32_16x16x32_bf16 v[58:61], v[210:213], v[218:221], v[58:61]
	v_mfma_f32_16x16x32_bf16 v[54:57], v[202:205], v[226:229], v[54:57]
	v_mfma_f32_16x16x32_bf16 v[50:53], v[210:213], v[226:229], v[50:53]
	v_mfma_f32_16x16x32_bf16 v[46:49], v[202:205], v[234:237], v[46:49]
	v_mfma_f32_16x16x32_bf16 v[42:45], v[210:213], v[234:237], v[42:45]
	v_mfma_f32_16x16x32_bf16 v[38:41], v[202:205], v[242:245], v[38:41]
	v_mfma_f32_16x16x32_bf16 v[34:37], v[210:213], v[242:245], v[34:37]
	s_setprio 0
	s_barrier
	s_add_i32 s3, s3, s26
	v_lshl_add_u64 v[144:145], s[0:1], 0, v[4:5]
	s_mov_b32 m0, s3
	ds_read_b128 v[214:217], v172 offset:16384
	ds_read_b128 v[218:221], v172 offset:17408
	ds_read_b128 v[222:225], v172 offset:18432
	ds_read_b128 v[226:229], v172 offset:19456
	ds_read_b128 v[230:233], v172 offset:20480
	ds_read_b128 v[234:237], v172 offset:21504
	ds_read_b128 v[238:241], v172 offset:22528
	ds_read_b128 v[242:245], v172 offset:23552
	global_load_lds_dwordx4 v[144:145], off
	s_add_i32 m0, s3, 0x2000
	s_add_u32 s4, s0, 0x40000
	v_lshl_add_u64 v[246:247], s[0:1], 0, v[134:135]
	s_addc_u32 s5, s1, 0
	s_add_i32 s3, s6, s26
	global_load_lds_dwordx4 v[246:247], off
	v_lshl_add_u64 v[248:249], s[4:5], 0, v[4:5]
	s_mov_b32 m0, s3
	v_lshl_add_u64 v[250:251], s[14:15], 0, v[132:133]
	global_load_lds_dwordx4 v[248:249], off
	s_add_i32 m0, s3, 0x2000
	v_lshl_add_u64 v[248:249], s[4:5], 0, v[134:135]
	global_load_lds_dwordx4 v[248:249], off
	s_mov_b32 m0, s27
	v_lshl_add_u64 v[248:249], s[14:15], 0, v[130:131]
	global_load_lds_dwordx4 v[248:249], off
	s_mov_b32 m0, s30
	s_nop 0
	global_load_lds_dwordx4 v[250:251], off
	s_waitcnt vmcnt(24)
	s_waitcnt lgkmcnt(0)
	s_barrier
	s_setprio 1
	s_waitcnt lgkmcnt(0)
	v_mfma_f32_16x16x32_bf16 v[94:97], v[140:143], v[214:217], v[94:97]
	v_mfma_f32_16x16x32_bf16 v[90:93], v[190:193], v[214:217], v[90:93]
	v_mfma_f32_16x16x32_bf16 v[86:89], v[140:143], v[222:225], v[86:89]
	v_mfma_f32_16x16x32_bf16 v[82:85], v[190:193], v[222:225], v[82:85]
	v_mfma_f32_16x16x32_bf16 v[78:81], v[140:143], v[230:233], v[78:81]
	v_mfma_f32_16x16x32_bf16 v[74:77], v[190:193], v[230:233], v[74:77]
	v_mfma_f32_16x16x32_bf16 v[70:73], v[140:143], v[238:241], v[70:73]
	v_mfma_f32_16x16x32_bf16 v[66:69], v[190:193], v[238:241], v[66:69]
	v_mfma_f32_16x16x32_bf16 v[94:97], v[174:177], v[218:221], v[94:97]
	v_mfma_f32_16x16x32_bf16 v[90:93], v[194:197], v[218:221], v[90:93]
	v_mfma_f32_16x16x32_bf16 v[86:89], v[174:177], v[226:229], v[86:89]
	v_mfma_f32_16x16x32_bf16 v[82:85], v[194:197], v[226:229], v[82:85]
	v_mfma_f32_16x16x32_bf16 v[78:81], v[174:177], v[234:237], v[78:81]
	v_mfma_f32_16x16x32_bf16 v[74:77], v[194:197], v[234:237], v[74:77]
	v_mfma_f32_16x16x32_bf16 v[70:73], v[174:177], v[242:245], v[70:73]
	v_mfma_f32_16x16x32_bf16 v[66:69], v[194:197], v[242:245], v[66:69]
	s_setprio 0
	s_setprio 1
	v_mfma_f32_16x16x32_bf16 v[30:33], v[198:201], v[214:217], v[30:33]
	v_mfma_f32_16x16x32_bf16 v[26:29], v[206:209], v[214:217], v[26:29]
	v_mfma_f32_16x16x32_bf16 v[22:25], v[198:201], v[222:225], v[22:25]
	v_mfma_f32_16x16x32_bf16 v[18:21], v[206:209], v[222:225], v[18:21]
	v_mfma_f32_16x16x32_bf16 v[14:17], v[198:201], v[230:233], v[14:17]
	v_mfma_f32_16x16x32_bf16 v[10:13], v[206:209], v[230:233], v[10:13]
	v_mfma_f32_16x16x32_bf16 v[6:9], v[198:201], v[238:241], v[6:9]
	v_mfma_f32_16x16x32_bf16 v[0:3], v[206:209], v[238:241], v[0:3]
	v_mfma_f32_16x16x32_bf16 v[30:33], v[202:205], v[218:221], v[30:33]
	v_mfma_f32_16x16x32_bf16 v[26:29], v[210:213], v[218:221], v[26:29]
	v_mfma_f32_16x16x32_bf16 v[22:25], v[202:205], v[226:229], v[22:25]
	v_mfma_f32_16x16x32_bf16 v[18:21], v[210:213], v[226:229], v[18:21]
	v_mfma_f32_16x16x32_bf16 v[14:17], v[202:205], v[234:237], v[14:17]
	v_mfma_f32_16x16x32_bf16 v[10:13], v[210:213], v[234:237], v[10:13]
	v_mfma_f32_16x16x32_bf16 v[6:9], v[202:205], v[242:245], v[6:9]
	v_mfma_f32_16x16x32_bf16 v[0:3], v[210:213], v[242:245], v[0:3]
	s_setprio 0
	s_barrier
	s_branch .Lpeelmid_205
.LBB0_205:
	s_add_u32 s0, s22, 0xfffc0080
	s_addc_u32 s1, s23, -1
	s_add_i32 s3, 0, 0x10000
	s_cmp_eq_u32 s24, 12
	s_cselect_b32 s15, s83, s1
	s_cselect_b32 s14, s82, s0
	v_add_u32_e32 v144, s3, v168
	s_cselect_b32 s1, s2, s10
	s_cselect_b32 s0, s8, s9
	s_add_i32 s6, 0, 0x14000
	ds_read_b128 v[140:143], v144
	ds_read_b128 v[174:177], v144 offset:1024
	ds_read_b128 v[190:193], v144 offset:2048
	ds_read_b128 v[194:197], v144 offset:3072
	v_add_u32_e32 v144, s6, v168
	ds_read_b128 v[198:201], v144
	ds_read_b128 v[202:205], v144 offset:1024
	ds_read_b128 v[206:209], v144 offset:2048
	ds_read_b128 v[210:213], v144 offset:3072
	v_lshl_add_u64 v[144:145], s[22:23], 0, v[136:137]
	s_add_i32 m0, s27, 0xc000
	ds_read_b128 v[214:217], v172
	ds_read_b128 v[218:221], v172 offset:1024
	ds_read_b128 v[222:225], v172 offset:2048
	ds_read_b128 v[226:229], v172 offset:3072
	ds_read_b128 v[230:233], v172 offset:4096
	ds_read_b128 v[234:237], v172 offset:5120
	ds_read_b128 v[238:241], v172 offset:6144
	ds_read_b128 v[242:245], v172 offset:7168
	global_load_lds_dwordx4 v[144:145], off
	s_add_i32 m0, s27, 0xe000
	v_lshl_add_u64 v[144:145], s[22:23], 0, v[138:139]
	global_load_lds_dwordx4 v[144:145], off
	s_waitcnt vmcnt(8)
	s_waitcnt lgkmcnt(0)
	s_barrier
	s_setprio 1
	s_waitcnt lgkmcnt(0)
	v_mfma_f32_16x16x32_bf16 v[126:129], v[140:143], v[214:217], v[126:129]
	v_mfma_f32_16x16x32_bf16 v[122:125], v[190:193], v[214:217], v[122:125]
	v_mfma_f32_16x16x32_bf16 v[118:121], v[140:143], v[222:225], v[118:121]
	v_mfma_f32_16x16x32_bf16 v[114:117], v[190:193], v[222:225], v[114:117]
	v_mfma_f32_16x16x32_bf16 v[110:113], v[140:143], v[230:233], v[110:113]
	v_mfma_f32_16x16x32_bf16 v[106:109], v[190:193], v[230:233], v[106:109]
	v_mfma_f32_16x16x32_bf16 v[102:105], v[140:143], v[238:241], v[102:105]
	v_mfma_f32_16x16x32_bf16 v[98:101], v[190:193], v[238:241], v[98:101]
	v_mfma_f32_16x16x32_bf16 v[126:129], v[174:177], v[218:221], v[126:129]
	v_mfma_f32_16x16x32_bf16 v[122:125], v[194:197], v[218:221], v[122:125]
	v_mfma_f32_16x16x32_bf16 v[118:121], v[174:177], v[226:229], v[118:121]
	v_mfma_f32_16x16x32_bf16 v[114:117], v[194:197], v[226:229], v[114:117]
	v_mfma_f32_16x16x32_bf16 v[110:113], v[174:177], v[234:237], v[110:113]
	v_mfma_f32_16x16x32_bf16 v[106:109], v[194:197], v[234:237], v[106:109]
	v_mfma_f32_16x16x32_bf16 v[102:105], v[174:177], v[242:245], v[102:105]
	v_mfma_f32_16x16x32_bf16 v[98:101], v[194:197], v[242:245], v[98:101]
	s_setprio 0
	s_setprio 1
	v_mfma_f32_16x16x32_bf16 v[62:65], v[198:201], v[214:217], v[62:65]
	v_mfma_f32_16x16x32_bf16 v[58:61], v[206:209], v[214:217], v[58:61]
	v_mfma_f32_16x16x32_bf16 v[54:57], v[198:201], v[222:225], v[54:57]
	v_mfma_f32_16x16x32_bf16 v[50:53], v[206:209], v[222:225], v[50:53]
	v_mfma_f32_16x16x32_bf16 v[46:49], v[198:201], v[230:233], v[46:49]
	v_mfma_f32_16x16x32_bf16 v[42:45], v[206:209], v[230:233], v[42:45]
	v_mfma_f32_16x16x32_bf16 v[38:41], v[198:201], v[238:241], v[38:41]
	v_mfma_f32_16x16x32_bf16 v[34:37], v[206:209], v[238:241], v[34:37]
	v_mfma_f32_16x16x32_bf16 v[62:65], v[202:205], v[218:221], v[62:65]
	v_mfma_f32_16x16x32_bf16 v[58:61], v[210:213], v[218:221], v[58:61]
	v_mfma_f32_16x16x32_bf16 v[54:57], v[202:205], v[226:229], v[54:57]
	v_mfma_f32_16x16x32_bf16 v[50:53], v[210:213], v[226:229], v[50:53]
	v_mfma_f32_16x16x32_bf16 v[46:49], v[202:205], v[234:237], v[46:49]
	v_mfma_f32_16x16x32_bf16 v[42:45], v[210:213], v[234:237], v[42:45]
	v_mfma_f32_16x16x32_bf16 v[38:41], v[202:205], v[242:245], v[38:41]
	v_mfma_f32_16x16x32_bf16 v[34:37], v[210:213], v[242:245], v[34:37]
	s_setprio 0
	s_barrier
	s_add_i32 s3, s3, s26
	v_lshl_add_u64 v[144:145], s[0:1], 0, v[4:5]
	s_mov_b32 m0, s3
	ds_read_b128 v[214:217], v172 offset:16384
	ds_read_b128 v[218:221], v172 offset:17408
	ds_read_b128 v[222:225], v172 offset:18432
	ds_read_b128 v[226:229], v172 offset:19456
	ds_read_b128 v[230:233], v172 offset:20480
	ds_read_b128 v[234:237], v172 offset:21504
	ds_read_b128 v[238:241], v172 offset:22528
	ds_read_b128 v[242:245], v172 offset:23552
	global_load_lds_dwordx4 v[144:145], off
	s_add_i32 m0, s3, 0x2000
	s_add_u32 s4, s0, 0x40000
	v_lshl_add_u64 v[246:247], s[0:1], 0, v[134:135]
	s_addc_u32 s5, s1, 0
	s_add_i32 s3, s6, s26
	global_load_lds_dwordx4 v[246:247], off
	v_lshl_add_u64 v[248:249], s[4:5], 0, v[4:5]
	s_mov_b32 m0, s3
	v_lshl_add_u64 v[250:251], s[14:15], 0, v[132:133]
	global_load_lds_dwordx4 v[248:249], off
	s_add_i32 m0, s3, 0x2000
	v_lshl_add_u64 v[248:249], s[4:5], 0, v[134:135]
	global_load_lds_dwordx4 v[248:249], off
	s_mov_b32 m0, s27
	v_lshl_add_u64 v[248:249], s[14:15], 0, v[130:131]
	global_load_lds_dwordx4 v[248:249], off
	s_mov_b32 m0, s30
	s_nop 0
	global_load_lds_dwordx4 v[250:251], off
	s_waitcnt vmcnt(8)
	s_waitcnt lgkmcnt(0)
	s_barrier
	s_setprio 1
	s_waitcnt lgkmcnt(0)
	v_mfma_f32_16x16x32_bf16 v[94:97], v[140:143], v[214:217], v[94:97]
	v_mfma_f32_16x16x32_bf16 v[90:93], v[190:193], v[214:217], v[90:93]
	v_mfma_f32_16x16x32_bf16 v[86:89], v[140:143], v[222:225], v[86:89]
	v_mfma_f32_16x16x32_bf16 v[82:85], v[190:193], v[222:225], v[82:85]
	v_mfma_f32_16x16x32_bf16 v[78:81], v[140:143], v[230:233], v[78:81]
	v_mfma_f32_16x16x32_bf16 v[74:77], v[190:193], v[230:233], v[74:77]
	v_mfma_f32_16x16x32_bf16 v[70:73], v[140:143], v[238:241], v[70:73]
	v_mfma_f32_16x16x32_bf16 v[66:69], v[190:193], v[238:241], v[66:69]
	v_mfma_f32_16x16x32_bf16 v[94:97], v[174:177], v[218:221], v[94:97]
	v_mfma_f32_16x16x32_bf16 v[90:93], v[194:197], v[218:221], v[90:93]
	v_mfma_f32_16x16x32_bf16 v[86:89], v[174:177], v[226:229], v[86:89]
	v_mfma_f32_16x16x32_bf16 v[82:85], v[194:197], v[226:229], v[82:85]
	v_mfma_f32_16x16x32_bf16 v[78:81], v[174:177], v[234:237], v[78:81]
	v_mfma_f32_16x16x32_bf16 v[74:77], v[194:197], v[234:237], v[74:77]
	v_mfma_f32_16x16x32_bf16 v[70:73], v[174:177], v[242:245], v[70:73]
	v_mfma_f32_16x16x32_bf16 v[66:69], v[194:197], v[242:245], v[66:69]
	s_setprio 0
	s_setprio 1
	v_mfma_f32_16x16x32_bf16 v[30:33], v[198:201], v[214:217], v[30:33]
	v_mfma_f32_16x16x32_bf16 v[26:29], v[206:209], v[214:217], v[26:29]
	v_mfma_f32_16x16x32_bf16 v[22:25], v[198:201], v[222:225], v[22:25]
	v_mfma_f32_16x16x32_bf16 v[18:21], v[206:209], v[222:225], v[18:21]
	v_mfma_f32_16x16x32_bf16 v[14:17], v[198:201], v[230:233], v[14:17]
	v_mfma_f32_16x16x32_bf16 v[10:13], v[206:209], v[230:233], v[10:13]
	v_mfma_f32_16x16x32_bf16 v[6:9], v[198:201], v[238:241], v[6:9]
	v_mfma_f32_16x16x32_bf16 v[0:3], v[206:209], v[238:241], v[0:3]
	v_mfma_f32_16x16x32_bf16 v[30:33], v[202:205], v[218:221], v[30:33]
	v_mfma_f32_16x16x32_bf16 v[26:29], v[210:213], v[218:221], v[26:29]
	v_mfma_f32_16x16x32_bf16 v[22:25], v[202:205], v[226:229], v[22:25]
	v_mfma_f32_16x16x32_bf16 v[18:21], v[210:213], v[226:229], v[18:21]
	v_mfma_f32_16x16x32_bf16 v[14:17], v[202:205], v[234:237], v[14:17]
	v_mfma_f32_16x16x32_bf16 v[10:13], v[210:213], v[234:237], v[10:13]
	v_mfma_f32_16x16x32_bf16 v[6:9], v[202:205], v[242:245], v[6:9]
	v_mfma_f32_16x16x32_bf16 v[0:3], v[210:213], v[242:245], v[0:3]
	s_setprio 0
	s_barrier
.Lpeelmid_205:
	s_add_i32 s3, 0, 0x18000
	v_add_u32_e32 v173, s3, v168
	s_add_i32 s6, 0, 0x1c000
	ds_read_b128 v[140:143], v173
	ds_read_b128 v[174:177], v173 offset:1024
	ds_read_b128 v[190:193], v173 offset:2048
	ds_read_b128 v[194:197], v173 offset:3072
	v_add_u32_e32 v173, s6, v168
	ds_read_b128 v[198:201], v173
	ds_read_b128 v[202:205], v173 offset:1024
	ds_read_b128 v[206:209], v173 offset:2048
	ds_read_b128 v[210:213], v173 offset:3072
	s_add_u32 s4, s14, 0x40000
	s_addc_u32 s5, s15, 0
	s_mov_b32 m0, s31
	v_lshl_add_u64 v[180:181], s[4:5], 0, v[130:131]
	ds_read_b128 v[214:217], v172 offset:32768
	ds_read_b128 v[218:221], v172 offset:33792
	ds_read_b128 v[222:225], v172 offset:34816
	ds_read_b128 v[226:229], v172 offset:35840
	ds_read_b128 v[230:233], v172 offset:36864
	ds_read_b128 v[234:237], v172 offset:37888
	ds_read_b128 v[238:241], v172 offset:38912
	ds_read_b128 v[242:245], v172 offset:39936
	global_load_lds_dwordx4 v[180:181], off
	s_mov_b32 m0, s34
	v_lshl_add_u64 v[180:181], s[4:5], 0, v[132:133]
	global_load_lds_dwordx4 v[180:181], off
	s_waitcnt vmcnt(8)
	s_waitcnt lgkmcnt(0)
	s_barrier
	s_setprio 1
	s_waitcnt lgkmcnt(0)
	v_mfma_f32_16x16x32_bf16 v[126:129], v[140:143], v[214:217], v[126:129]
	v_mfma_f32_16x16x32_bf16 v[122:125], v[190:193], v[214:217], v[122:125]
	v_mfma_f32_16x16x32_bf16 v[118:121], v[140:143], v[222:225], v[118:121]
	v_mfma_f32_16x16x32_bf16 v[114:117], v[190:193], v[222:225], v[114:117]
	v_mfma_f32_16x16x32_bf16 v[110:113], v[140:143], v[230:233], v[110:113]
	v_mfma_f32_16x16x32_bf16 v[106:109], v[190:193], v[230:233], v[106:109]
	v_mfma_f32_16x16x32_bf16 v[102:105], v[140:143], v[238:241], v[102:105]
	v_mfma_f32_16x16x32_bf16 v[98:101], v[190:193], v[238:241], v[98:101]
	v_mfma_f32_16x16x32_bf16 v[126:129], v[174:177], v[218:221], v[126:129]
	v_mfma_f32_16x16x32_bf16 v[122:125], v[194:197], v[218:221], v[122:125]
	v_mfma_f32_16x16x32_bf16 v[118:121], v[174:177], v[226:229], v[118:121]
	v_mfma_f32_16x16x32_bf16 v[114:117], v[194:197], v[226:229], v[114:117]
	v_mfma_f32_16x16x32_bf16 v[110:113], v[174:177], v[234:237], v[110:113]
	v_mfma_f32_16x16x32_bf16 v[106:109], v[194:197], v[234:237], v[106:109]
	v_mfma_f32_16x16x32_bf16 v[102:105], v[174:177], v[242:245], v[102:105]
	v_mfma_f32_16x16x32_bf16 v[98:101], v[194:197], v[242:245], v[98:101]
	s_setprio 0
	s_setprio 1
	v_mfma_f32_16x16x32_bf16 v[62:65], v[198:201], v[214:217], v[62:65]
	v_mfma_f32_16x16x32_bf16 v[58:61], v[206:209], v[214:217], v[58:61]
	v_mfma_f32_16x16x32_bf16 v[54:57], v[198:201], v[222:225], v[54:57]
	v_mfma_f32_16x16x32_bf16 v[50:53], v[206:209], v[222:225], v[50:53]
	v_mfma_f32_16x16x32_bf16 v[46:49], v[198:201], v[230:233], v[46:49]
	v_mfma_f32_16x16x32_bf16 v[42:45], v[206:209], v[230:233], v[42:45]
	v_mfma_f32_16x16x32_bf16 v[38:41], v[198:201], v[238:241], v[38:41]
	v_mfma_f32_16x16x32_bf16 v[34:37], v[206:209], v[238:241], v[34:37]
	v_mfma_f32_16x16x32_bf16 v[62:65], v[202:205], v[218:221], v[62:65]
	v_mfma_f32_16x16x32_bf16 v[58:61], v[210:213], v[218:221], v[58:61]
	v_mfma_f32_16x16x32_bf16 v[54:57], v[202:205], v[226:229], v[54:57]
	v_mfma_f32_16x16x32_bf16 v[50:53], v[210:213], v[226:229], v[50:53]
	v_mfma_f32_16x16x32_bf16 v[46:49], v[202:205], v[234:237], v[46:49]
	v_mfma_f32_16x16x32_bf16 v[42:45], v[210:213], v[234:237], v[42:45]
	v_mfma_f32_16x16x32_bf16 v[38:41], v[202:205], v[242:245], v[38:41]
	v_mfma_f32_16x16x32_bf16 v[34:37], v[210:213], v[242:245], v[34:37]
	s_setprio 0
	s_barrier
	s_add_i32 s3, s3, s26
	v_lshl_add_u64 v[144:145], v[144:145], 0, s[70:71]
	s_mov_b32 m0, s3
	ds_read_b128 v[214:217], v172 offset:49152
	ds_read_b128 v[218:221], v172 offset:50176
	ds_read_b128 v[222:225], v172 offset:51200
	ds_read_b128 v[226:229], v172 offset:52224
	ds_read_b128 v[230:233], v172 offset:53248
	ds_read_b128 v[234:237], v172 offset:54272
	ds_read_b128 v[238:241], v172 offset:55296
	ds_read_b128 v[242:245], v172 offset:56320
	global_load_lds_dwordx4 v[144:145], off
	s_add_i32 m0, s3, 0x2000
	s_add_u32 s0, s0, 0x40080
	v_lshl_add_u64 v[144:145], v[246:247], 0, s[70:71]
	s_addc_u32 s1, s1, 0
	s_add_i32 s3, s6, s26
	global_load_lds_dwordx4 v[144:145], off
	s_mov_b32 m0, s3
	v_lshl_add_u64 v[144:145], s[0:1], 0, v[4:5]
	global_load_lds_dwordx4 v[144:145], off
	s_add_i32 m0, s3, 0x2000
	v_lshl_add_u64 v[144:145], s[0:1], 0, v[134:135]
	global_load_lds_dwordx4 v[144:145], off
	s_mov_b32 m0, s35
	v_lshl_add_u64 v[144:145], v[248:249], 0, s[70:71]
	global_load_lds_dwordx4 v[144:145], off
	s_mov_b32 m0, s36
	v_lshl_add_u64 v[144:145], v[250:251], 0, s[70:71]
	global_load_lds_dwordx4 v[144:145], off
	s_waitcnt vmcnt(8)
	s_waitcnt lgkmcnt(0)
	s_barrier
	s_setprio 1
	s_waitcnt lgkmcnt(0)
	v_mfma_f32_16x16x32_bf16 v[94:97], v[140:143], v[214:217], v[94:97]
	v_mfma_f32_16x16x32_bf16 v[90:93], v[190:193], v[214:217], v[90:93]
	v_mfma_f32_16x16x32_bf16 v[86:89], v[140:143], v[222:225], v[86:89]
	v_mfma_f32_16x16x32_bf16 v[82:85], v[190:193], v[222:225], v[82:85]
	v_mfma_f32_16x16x32_bf16 v[78:81], v[140:143], v[230:233], v[78:81]
	v_mfma_f32_16x16x32_bf16 v[74:77], v[190:193], v[230:233], v[74:77]
	v_mfma_f32_16x16x32_bf16 v[70:73], v[140:143], v[238:241], v[70:73]
	v_mfma_f32_16x16x32_bf16 v[66:69], v[190:193], v[238:241], v[66:69]
	v_mfma_f32_16x16x32_bf16 v[94:97], v[174:177], v[218:221], v[94:97]
	v_mfma_f32_16x16x32_bf16 v[90:93], v[194:197], v[218:221], v[90:93]
	v_mfma_f32_16x16x32_bf16 v[86:89], v[174:177], v[226:229], v[86:89]
	v_mfma_f32_16x16x32_bf16 v[82:85], v[194:197], v[226:229], v[82:85]
	v_mfma_f32_16x16x32_bf16 v[78:81], v[174:177], v[234:237], v[78:81]
	v_mfma_f32_16x16x32_bf16 v[74:77], v[194:197], v[234:237], v[74:77]
	v_mfma_f32_16x16x32_bf16 v[70:73], v[174:177], v[242:245], v[70:73]
	v_mfma_f32_16x16x32_bf16 v[66:69], v[194:197], v[242:245], v[66:69]
	s_setprio 0
	s_setprio 1
	v_mfma_f32_16x16x32_bf16 v[30:33], v[198:201], v[214:217], v[30:33]
	v_mfma_f32_16x16x32_bf16 v[26:29], v[206:209], v[214:217], v[26:29]
	v_mfma_f32_16x16x32_bf16 v[22:25], v[198:201], v[222:225], v[22:25]
	v_mfma_f32_16x16x32_bf16 v[18:21], v[206:209], v[222:225], v[18:21]
	v_mfma_f32_16x16x32_bf16 v[14:17], v[198:201], v[230:233], v[14:17]
	v_mfma_f32_16x16x32_bf16 v[10:13], v[206:209], v[230:233], v[10:13]
	v_mfma_f32_16x16x32_bf16 v[6:9], v[198:201], v[238:241], v[6:9]
	v_mfma_f32_16x16x32_bf16 v[0:3], v[206:209], v[238:241], v[0:3]
	v_mfma_f32_16x16x32_bf16 v[30:33], v[202:205], v[218:221], v[30:33]
	v_mfma_f32_16x16x32_bf16 v[26:29], v[210:213], v[218:221], v[26:29]
	v_mfma_f32_16x16x32_bf16 v[22:25], v[202:205], v[226:229], v[22:25]
	v_mfma_f32_16x16x32_bf16 v[18:21], v[210:213], v[226:229], v[18:21]
	v_mfma_f32_16x16x32_bf16 v[14:17], v[202:205], v[234:237], v[14:17]
	v_mfma_f32_16x16x32_bf16 v[10:13], v[210:213], v[234:237], v[10:13]
	v_mfma_f32_16x16x32_bf16 v[6:9], v[202:205], v[242:245], v[6:9]
	v_mfma_f32_16x16x32_bf16 v[0:3], v[210:213], v[242:245], v[0:3]
	s_setprio 0
	s_barrier
	s_add_i32 s24, s24, 2
	s_add_u32 s22, s22, 0x100
	s_addc_u32 s23, s23, 0
	s_add_u32 s9, s9, 0x100
	s_addc_u32 s10, s10, 0
	s_cmp_gt_u32 s24, 13
	s_cbranch_scc0 .LBB0_205
	s_and_b64 vcc, exec, s[46:47]
	s_cbranch_vccz .LBB0_208
	s_barrier

.LBB0_227:
	s_ashr_i32 s47, s46, 31
	s_lshl_b64 s[2:3], s[46:47], 19
	v_readlane_b32 s4, v253, 25
	v_readlane_b32 s5, v253, 26
	s_add_u32 s82, s4, s2
	s_addc_u32 s83, s5, s3
	s_and_b64 s[2:3], s[40:41], exec
	s_cselect_b32 s2, s83, s15
	s_cselect_b32 s8, s82, s14
	s_add_u32 s22, s0, 0x40080
	s_addc_u32 s23, s1, 0
	s_add_u32 s9, s14, 0x100
	v_mov_b32_e32 v0, 0
	s_addc_u32 s10, s15, 0
	s_mov_b32 s24, -2
	v_mov_b32_e32 v1, v0
	v_mov_b32_e32 v2, v0
	v_mov_b32_e32 v3, v0
	v_mov_b32_e32 v6, v0
	v_mov_b32_e32 v7, v0
	v_mov_b32_e32 v8, v0
	v_mov_b32_e32 v9, v0
	v_mov_b32_e32 v10, v0
	v_mov_b32_e32 v11, v0
	v_mov_b32_e32 v12, v0
	v_mov_b32_e32 v13, v0
	v_mov_b32_e32 v14, v0
	v_mov_b32_e32 v15, v0
	v_mov_b32_e32 v16, v0
	v_mov_b32_e32 v17, v0
	v_mov_b32_e32 v18, v0
	v_mov_b32_e32 v19, v0
	v_mov_b32_e32 v20, v0
	v_mov_b32_e32 v21, v0
	v_mov_b32_e32 v22, v0
	v_mov_b32_e32 v23, v0
	v_mov_b32_e32 v24, v0
	v_mov_b32_e32 v25, v0
	v_mov_b32_e32 v26, v0
	v_mov_b32_e32 v27, v0
	v_mov_b32_e32 v28, v0
	v_mov_b32_e32 v29, v0
	v_mov_b32_e32 v30, v0
	v_mov_b32_e32 v31, v0
	v_mov_b32_e32 v32, v0
	v_mov_b32_e32 v33, v0
	v_mov_b32_e32 v62, v0
	v_mov_b32_e32 v63, v0
	v_mov_b32_e32 v64, v0
	v_mov_b32_e32 v65, v0
	v_mov_b32_e32 v70, v0
	v_mov_b32_e32 v71, v0
	v_mov_b32_e32 v72, v0
	v_mov_b32_e32 v73, v0
	v_mov_b32_e32 v74, v0
	v_mov_b32_e32 v75, v0
	v_mov_b32_e32 v76, v0
	v_mov_b32_e32 v77, v0
	v_mov_b32_e32 v78, v0
	v_mov_b32_e32 v79, v0
	v_mov_b32_e32 v80, v0
	v_mov_b32_e32 v81, v0
	v_mov_b32_e32 v82, v0
	v_mov_b32_e32 v83, v0
	v_mov_b32_e32 v84, v0
	v_mov_b32_e32 v85, v0
	v_mov_b32_e32 v86, v0
	v_mov_b32_e32 v87, v0
	v_mov_b32_e32 v88, v0
	v_mov_b32_e32 v89, v0
	v_mov_b32_e32 v90, v0
	v_mov_b32_e32 v91, v0
	v_mov_b32_e32 v92, v0
	v_mov_b32_e32 v93, v0
	v_mov_b32_e32 v94, v0
	v_mov_b32_e32 v95, v0
	v_mov_b32_e32 v96, v0
	v_mov_b32_e32 v97, v0
	v_mov_b32_e32 v34, v0
	v_mov_b32_e32 v35, v0
	v_mov_b32_e32 v36, v0
	v_mov_b32_e32 v37, v0
	v_mov_b32_e32 v38, v0
	v_mov_b32_e32 v39, v0
	v_mov_b32_e32 v40, v0
	v_mov_b32_e32 v41, v0
	v_mov_b32_e32 v42, v0
	v_mov_b32_e32 v43, v0
	v_mov_b32_e32 v44, v0
	v_mov_b32_e32 v45, v0
	v_mov_b32_e32 v46, v0
	v_mov_b32_e32 v47, v0
	v_mov_b32_e32 v48, v0
	v_mov_b32_e32 v49, v0
	v_mov_b32_e32 v50, v0
	v_mov_b32_e32 v51, v0
	v_mov_b32_e32 v52, v0
	v_mov_b32_e32 v53, v0
	v_mov_b32_e32 v54, v0
	v_mov_b32_e32 v55, v0
	v_mov_b32_e32 v56, v0
	v_mov_b32_e32 v57, v0
	v_mov_b32_e32 v58, v0
	v_mov_b32_e32 v59, v0
	v_mov_b32_e32 v60, v0
	v_mov_b32_e32 v61, v0
	v_mov_b32_e32 v66, v0
	v_mov_b32_e32 v67, v0
	v_mov_b32_e32 v68, v0
	v_mov_b32_e32 v69, v0
	v_mov_b32_e32 v98, v0
	v_mov_b32_e32 v99, v0
	v_mov_b32_e32 v100, v0
	v_mov_b32_e32 v101, v0
	v_mov_b32_e32 v102, v0
	v_mov_b32_e32 v103, v0
	v_mov_b32_e32 v104, v0
	v_mov_b32_e32 v105, v0
	v_mov_b32_e32 v106, v0
	v_mov_b32_e32 v107, v0
	v_mov_b32_e32 v108, v0
	v_mov_b32_e32 v109, v0
	v_mov_b32_e32 v110, v0
	v_mov_b32_e32 v111, v0
	v_mov_b32_e32 v112, v0
	v_mov_b32_e32 v113, v0
	v_mov_b32_e32 v114, v0
	v_mov_b32_e32 v115, v0
	v_mov_b32_e32 v116, v0
	v_mov_b32_e32 v117, v0
	v_mov_b32_e32 v118, v0
	v_mov_b32_e32 v119, v0
	v_mov_b32_e32 v120, v0
	v_mov_b32_e32 v121, v0
	v_mov_b32_e32 v122, v0
	v_mov_b32_e32 v123, v0
	v_mov_b32_e32 v124, v0
	v_mov_b32_e32 v125, v0
	v_mov_b32_e32 v126, v0
	v_mov_b32_e32 v127, v0
	v_mov_b32_e32 v128, v0
	v_mov_b32_e32 v129, v0
	s_cmp_eq_u32 s37, 1
	s_cbranch_scc1 .LBB0_228
	s_add_u32 s0, s22, 0xfffc0080
	s_addc_u32 s1, s23, -1
	s_add_i32 s3, 0, 0x10000
	s_cmp_eq_u32 s24, 12
	s_cselect_b32 s15, s49, s1
	s_cselect_b32 s14, s48, s0
	v_add_u32_e32 v162, s3, v149
	s_cselect_b32 s1, s2, s10
	s_cselect_b32 s0, s8, s9
	s_add_i32 s6, 0, 0x14000
	ds_read_b128 v[140:143], v162
	ds_read_b128 v[144:147], v162 offset:1024
	ds_read_b128 v[172:175], v162 offset:2048
	ds_read_b128 v[190:193], v162 offset:3072
	v_add_u32_e32 v162, s6, v149
	ds_read_b128 v[194:197], v162
	ds_read_b128 v[198:201], v162 offset:1024
	ds_read_b128 v[202:205], v162 offset:2048
	ds_read_b128 v[206:209], v162 offset:3072
	v_lshl_add_u64 v[162:163], s[22:23], 0, v[136:137]
	s_add_i32 m0, s27, 0xc000
	ds_read_b128 v[210:213], v151
	ds_read_b128 v[214:217], v151 offset:1024
	ds_read_b128 v[218:221], v151 offset:2048
	ds_read_b128 v[222:225], v151 offset:3072
	ds_read_b128 v[226:229], v151 offset:4096
	ds_read_b128 v[230:233], v151 offset:5120
	ds_read_b128 v[234:237], v151 offset:6144
	ds_read_b128 v[238:241], v151 offset:7168
	global_load_lds_dwordx4 v[162:163], off
	s_add_i32 m0, s27, 0xe000
	v_lshl_add_u64 v[162:163], s[22:23], 0, v[138:139]
	global_load_lds_dwordx4 v[162:163], off
	s_waitcnt vmcnt(24)
	s_waitcnt lgkmcnt(0)
	s_barrier
	s_setprio 1
	s_waitcnt lgkmcnt(0)
	v_mfma_f32_16x16x32_bf16 v[126:129], v[140:143], v[210:213], v[126:129]
	v_mfma_f32_16x16x32_bf16 v[122:125], v[172:175], v[210:213], v[122:125]
	v_mfma_f32_16x16x32_bf16 v[118:121], v[140:143], v[218:221], v[118:121]
	v_mfma_f32_16x16x32_bf16 v[114:117], v[172:175], v[218:221], v[114:117]
	v_mfma_f32_16x16x32_bf16 v[110:113], v[140:143], v[226:229], v[110:113]
	v_mfma_f32_16x16x32_bf16 v[106:109], v[172:175], v[226:229], v[106:109]
	v_mfma_f32_16x16x32_bf16 v[102:105], v[140:143], v[234:237], v[102:105]
	v_mfma_f32_16x16x32_bf16 v[98:101], v[172:175], v[234:237], v[98:101]
	v_mfma_f32_16x16x32_bf16 v[126:129], v[144:147], v[214:217], v[126:129]
	v_mfma_f32_16x16x32_bf16 v[122:125], v[190:193], v[214:217], v[122:125]
	v_mfma_f32_16x16x32_bf16 v[118:121], v[144:147], v[222:225], v[118:121]
	v_mfma_f32_16x16x32_bf16 v[114:117], v[190:193], v[222:225], v[114:117]
	v_mfma_f32_16x16x32_bf16 v[110:113], v[144:147], v[230:233], v[110:113]
	v_mfma_f32_16x16x32_bf16 v[106:109], v[190:193], v[230:233], v[106:109]
	v_mfma_f32_16x16x32_bf16 v[102:105], v[144:147], v[238:241], v[102:105]
	v_mfma_f32_16x16x32_bf16 v[98:101], v[190:193], v[238:241], v[98:101]
	s_setprio 0
	s_setprio 1
	v_mfma_f32_16x16x32_bf16 v[66:69], v[194:197], v[210:213], v[66:69]
	v_mfma_f32_16x16x32_bf16 v[58:61], v[202:205], v[210:213], v[58:61]
	v_mfma_f32_16x16x32_bf16 v[54:57], v[194:197], v[218:221], v[54:57]
	v_mfma_f32_16x16x32_bf16 v[50:53], v[202:205], v[218:221], v[50:53]
	v_mfma_f32_16x16x32_bf16 v[46:49], v[194:197], v[226:229], v[46:49]
	v_mfma_f32_16x16x32_bf16 v[42:45], v[202:205], v[226:229], v[42:45]
	v_mfma_f32_16x16x32_bf16 v[38:41], v[194:197], v[234:237], v[38:41]
	v_mfma_f32_16x16x32_bf16 v[34:37], v[202:205], v[234:237], v[34:37]
	v_mfma_f32_16x16x32_bf16 v[66:69], v[198:201], v[214:217], v[66:69]
	v_mfma_f32_16x16x32_bf16 v[58:61], v[206:209], v[214:217], v[58:61]
	v_mfma_f32_16x16x32_bf16 v[54:57], v[198:201], v[222:225], v[54:57]
	v_mfma_f32_16x16x32_bf16 v[50:53], v[206:209], v[222:225], v[50:53]
	v_mfma_f32_16x16x32_bf16 v[46:49], v[198:201], v[230:233], v[46:49]
	v_mfma_f32_16x16x32_bf16 v[42:45], v[206:209], v[230:233], v[42:45]
	v_mfma_f32_16x16x32_bf16 v[38:41], v[198:201], v[238:241], v[38:41]
	v_mfma_f32_16x16x32_bf16 v[34:37], v[206:209], v[238:241], v[34:37]
	s_setprio 0
	s_barrier
	s_add_i32 s3, s3, s26
	v_lshl_add_u64 v[162:163], s[0:1], 0, v[4:5]
	s_mov_b32 m0, s3
	ds_read_b128 v[210:213], v151 offset:16384
	ds_read_b128 v[214:217], v151 offset:17408
	ds_read_b128 v[218:221], v151 offset:18432
	ds_read_b128 v[222:225], v151 offset:19456
	ds_read_b128 v[226:229], v151 offset:20480
	ds_read_b128 v[230:233], v151 offset:21504
	ds_read_b128 v[234:237], v151 offset:22528
	ds_read_b128 v[238:241], v151 offset:23552
	global_load_lds_dwordx4 v[162:163], off
	s_add_i32 m0, s3, 0x2000
	s_add_u32 s4, s0, 0x40000
	v_lshl_add_u64 v[166:167], s[0:1], 0, v[134:135]
	s_addc_u32 s5, s1, 0
	s_add_i32 s3, s6, s26
	global_load_lds_dwordx4 v[166:167], off
	v_lshl_add_u64 v[176:177], s[4:5], 0, v[4:5]
	s_mov_b32 m0, s3
	v_lshl_add_u64 v[180:181], s[14:15], 0, v[132:133]
	global_load_lds_dwordx4 v[176:177], off
	s_add_i32 m0, s3, 0x2000
	v_lshl_add_u64 v[176:177], s[4:5], 0, v[134:135]
	global_load_lds_dwordx4 v[176:177], off
	s_mov_b32 m0, s27
	v_lshl_add_u64 v[176:177], s[14:15], 0, v[130:131]
	global_load_lds_dwordx4 v[176:177], off
	s_mov_b32 m0, s30
	s_nop 0
	global_load_lds_dwordx4 v[180:181], off
	s_waitcnt vmcnt(24)
	s_waitcnt lgkmcnt(0)
	s_barrier
	s_setprio 1
	s_waitcnt lgkmcnt(0)
	v_mfma_f32_16x16x32_bf16 v[94:97], v[140:143], v[210:213], v[94:97]
	v_mfma_f32_16x16x32_bf16 v[90:93], v[172:175], v[210:213], v[90:93]
	v_mfma_f32_16x16x32_bf16 v[86:89], v[140:143], v[218:221], v[86:89]
	v_mfma_f32_16x16x32_bf16 v[82:85], v[172:175], v[218:221], v[82:85]
	v_mfma_f32_16x16x32_bf16 v[78:81], v[140:143], v[226:229], v[78:81]
	v_mfma_f32_16x16x32_bf16 v[74:77], v[172:175], v[226:229], v[74:77]
	v_mfma_f32_16x16x32_bf16 v[70:73], v[140:143], v[234:237], v[70:73]
	v_mfma_f32_16x16x32_bf16 v[62:65], v[172:175], v[234:237], v[62:65]
	v_mfma_f32_16x16x32_bf16 v[94:97], v[144:147], v[214:217], v[94:97]
	v_mfma_f32_16x16x32_bf16 v[90:93], v[190:193], v[214:217], v[90:93]
	v_mfma_f32_16x16x32_bf16 v[86:89], v[144:147], v[222:225], v[86:89]
	v_mfma_f32_16x16x32_bf16 v[82:85], v[190:193], v[222:225], v[82:85]
	v_mfma_f32_16x16x32_bf16 v[78:81], v[144:147], v[230:233], v[78:81]
	v_mfma_f32_16x16x32_bf16 v[74:77], v[190:193], v[230:233], v[74:77]
	v_mfma_f32_16x16x32_bf16 v[70:73], v[144:147], v[238:241], v[70:73]
	v_mfma_f32_16x16x32_bf16 v[62:65], v[190:193], v[238:241], v[62:65]
	s_setprio 0
	s_setprio 1
	v_mfma_f32_16x16x32_bf16 v[30:33], v[194:197], v[210:213], v[30:33]
	v_mfma_f32_16x16x32_bf16 v[26:29], v[202:205], v[210:213], v[26:29]
	v_mfma_f32_16x16x32_bf16 v[22:25], v[194:197], v[218:221], v[22:25]
	v_mfma_f32_16x16x32_bf16 v[18:21], v[202:205], v[218:221], v[18:21]
	v_mfma_f32_16x16x32_bf16 v[14:17], v[194:197], v[226:229], v[14:17]
	v_mfma_f32_16x16x32_bf16 v[10:13], v[202:205], v[226:229], v[10:13]
	v_mfma_f32_16x16x32_bf16 v[6:9], v[194:197], v[234:237], v[6:9]
	v_mfma_f32_16x16x32_bf16 v[0:3], v[202:205], v[234:237], v[0:3]
	v_mfma_f32_16x16x32_bf16 v[30:33], v[198:201], v[214:217], v[30:33]
	v_mfma_f32_16x16x32_bf16 v[26:29], v[206:209], v[214:217], v[26:29]
	v_mfma_f32_16x16x32_bf16 v[22:25], v[198:201], v[222:225], v[22:25]
	v_mfma_f32_16x16x32_bf16 v[18:21], v[206:209], v[222:225], v[18:21]
	v_mfma_f32_16x16x32_bf16 v[14:17], v[198:201], v[230:233], v[14:17]
	v_mfma_f32_16x16x32_bf16 v[10:13], v[206:209], v[230:233], v[10:13]
	v_mfma_f32_16x16x32_bf16 v[6:9], v[198:201], v[238:241], v[6:9]
	v_mfma_f32_16x16x32_bf16 v[0:3], v[206:209], v[238:241], v[0:3]
	s_setprio 0
	s_barrier
	s_branch .Lpeelmid_228
.LBB0_228:
	s_add_u32 s0, s22, 0xfffc0080
	s_addc_u32 s1, s23, -1
	s_add_i32 s3, 0, 0x10000
	s_cmp_eq_u32 s24, 12
	s_cselect_b32 s15, s49, s1
	s_cselect_b32 s14, s48, s0
	v_add_u32_e32 v162, s3, v149
	s_cselect_b32 s1, s2, s10
	s_cselect_b32 s0, s8, s9
	s_add_i32 s6, 0, 0x14000
	ds_read_b128 v[140:143], v162
	ds_read_b128 v[144:147], v162 offset:1024
	ds_read_b128 v[172:175], v162 offset:2048
	ds_read_b128 v[190:193], v162 offset:3072
	v_add_u32_e32 v162, s6, v149
	ds_read_b128 v[194:197], v162
	ds_read_b128 v[198:201], v162 offset:1024
	ds_read_b128 v[202:205], v162 offset:2048
	ds_read_b128 v[206:209], v162 offset:3072
	v_lshl_add_u64 v[162:163], s[22:23], 0, v[136:137]
	s_add_i32 m0, s27, 0xc000
	ds_read_b128 v[210:213], v151
	ds_read_b128 v[214:217], v151 offset:1024
	ds_read_b128 v[218:221], v151 offset:2048
	ds_read_b128 v[222:225], v151 offset:3072
	ds_read_b128 v[226:229], v151 offset:4096
	ds_read_b128 v[230:233], v151 offset:5120
	ds_read_b128 v[234:237], v151 offset:6144
	ds_read_b128 v[238:241], v151 offset:7168
	global_load_lds_dwordx4 v[162:163], off
	s_add_i32 m0, s27, 0xe000
	v_lshl_add_u64 v[162:163], s[22:23], 0, v[138:139]
	global_load_lds_dwordx4 v[162:163], off
	s_waitcnt vmcnt(8)
	s_waitcnt lgkmcnt(0)
	s_barrier
	s_setprio 1
	s_waitcnt lgkmcnt(0)
	v_mfma_f32_16x16x32_bf16 v[126:129], v[140:143], v[210:213], v[126:129]
	v_mfma_f32_16x16x32_bf16 v[122:125], v[172:175], v[210:213], v[122:125]
	v_mfma_f32_16x16x32_bf16 v[118:121], v[140:143], v[218:221], v[118:121]
	v_mfma_f32_16x16x32_bf16 v[114:117], v[172:175], v[218:221], v[114:117]
	v_mfma_f32_16x16x32_bf16 v[110:113], v[140:143], v[226:229], v[110:113]
	v_mfma_f32_16x16x32_bf16 v[106:109], v[172:175], v[226:229], v[106:109]
	v_mfma_f32_16x16x32_bf16 v[102:105], v[140:143], v[234:237], v[102:105]
	v_mfma_f32_16x16x32_bf16 v[98:101], v[172:175], v[234:237], v[98:101]
	v_mfma_f32_16x16x32_bf16 v[126:129], v[144:147], v[214:217], v[126:129]
	v_mfma_f32_16x16x32_bf16 v[122:125], v[190:193], v[214:217], v[122:125]
	v_mfma_f32_16x16x32_bf16 v[118:121], v[144:147], v[222:225], v[118:121]
	v_mfma_f32_16x16x32_bf16 v[114:117], v[190:193], v[222:225], v[114:117]
	v_mfma_f32_16x16x32_bf16 v[110:113], v[144:147], v[230:233], v[110:113]
	v_mfma_f32_16x16x32_bf16 v[106:109], v[190:193], v[230:233], v[106:109]
	v_mfma_f32_16x16x32_bf16 v[102:105], v[144:147], v[238:241], v[102:105]
	v_mfma_f32_16x16x32_bf16 v[98:101], v[190:193], v[238:241], v[98:101]
	s_setprio 0
	s_setprio 1
	v_mfma_f32_16x16x32_bf16 v[66:69], v[194:197], v[210:213], v[66:69]
	v_mfma_f32_16x16x32_bf16 v[58:61], v[202:205], v[210:213], v[58:61]
	v_mfma_f32_16x16x32_bf16 v[54:57], v[194:197], v[218:221], v[54:57]
	v_mfma_f32_16x16x32_bf16 v[50:53], v[202:205], v[218:221], v[50:53]
	v_mfma_f32_16x16x32_bf16 v[46:49], v[194:197], v[226:229], v[46:49]
	v_mfma_f32_16x16x32_bf16 v[42:45], v[202:205], v[226:229], v[42:45]
	v_mfma_f32_16x16x32_bf16 v[38:41], v[194:197], v[234:237], v[38:41]
	v_mfma_f32_16x16x32_bf16 v[34:37], v[202:205], v[234:237], v[34:37]
	v_mfma_f32_16x16x32_bf16 v[66:69], v[198:201], v[214:217], v[66:69]
	v_mfma_f32_16x16x32_bf16 v[58:61], v[206:209], v[214:217], v[58:61]
	v_mfma_f32_16x16x32_bf16 v[54:57], v[198:201], v[222:225], v[54:57]
	v_mfma_f32_16x16x32_bf16 v[50:53], v[206:209], v[222:225], v[50:53]
	v_mfma_f32_16x16x32_bf16 v[46:49], v[198:201], v[230:233], v[46:49]
	v_mfma_f32_16x16x32_bf16 v[42:45], v[206:209], v[230:233], v[42:45]
	v_mfma_f32_16x16x32_bf16 v[38:41], v[198:201], v[238:241], v[38:41]
	v_mfma_f32_16x16x32_bf16 v[34:37], v[206:209], v[238:241], v[34:37]
	s_setprio 0
	s_barrier
	s_add_i32 s3, s3, s26
	v_lshl_add_u64 v[162:163], s[0:1], 0, v[4:5]
	s_mov_b32 m0, s3
	ds_read_b128 v[210:213], v151 offset:16384
	ds_read_b128 v[214:217], v151 offset:17408
	ds_read_b128 v[218:221], v151 offset:18432
	ds_read_b128 v[222:225], v151 offset:19456
	ds_read_b128 v[226:229], v151 offset:20480
	ds_read_b128 v[230:233], v151 offset:21504
	ds_read_b128 v[234:237], v151 offset:22528
	ds_read_b128 v[238:241], v151 offset:23552
	global_load_lds_dwordx4 v[162:163], off
	s_add_i32 m0, s3, 0x2000
	s_add_u32 s4, s0, 0x40000
	v_lshl_add_u64 v[166:167], s[0:1], 0, v[134:135]
	s_addc_u32 s5, s1, 0
	s_add_i32 s3, s6, s26
	global_load_lds_dwordx4 v[166:167], off
	v_lshl_add_u64 v[176:177], s[4:5], 0, v[4:5]
	s_mov_b32 m0, s3
	v_lshl_add_u64 v[180:181], s[14:15], 0, v[132:133]
	global_load_lds_dwordx4 v[176:177], off
	s_add_i32 m0, s3, 0x2000
	v_lshl_add_u64 v[176:177], s[4:5], 0, v[134:135]
	global_load_lds_dwordx4 v[176:177], off
	s_mov_b32 m0, s27
	v_lshl_add_u64 v[176:177], s[14:15], 0, v[130:131]
	global_load_lds_dwordx4 v[176:177], off
	s_mov_b32 m0, s30
	s_nop 0
	global_load_lds_dwordx4 v[180:181], off
	s_waitcnt vmcnt(8)
	s_waitcnt lgkmcnt(0)
	s_barrier
	s_setprio 1
	s_waitcnt lgkmcnt(0)
	v_mfma_f32_16x16x32_bf16 v[94:97], v[140:143], v[210:213], v[94:97]
	v_mfma_f32_16x16x32_bf16 v[90:93], v[172:175], v[210:213], v[90:93]
	v_mfma_f32_16x16x32_bf16 v[86:89], v[140:143], v[218:221], v[86:89]
	v_mfma_f32_16x16x32_bf16 v[82:85], v[172:175], v[218:221], v[82:85]
	v_mfma_f32_16x16x32_bf16 v[78:81], v[140:143], v[226:229], v[78:81]
	v_mfma_f32_16x16x32_bf16 v[74:77], v[172:175], v[226:229], v[74:77]
	v_mfma_f32_16x16x32_bf16 v[70:73], v[140:143], v[234:237], v[70:73]
	v_mfma_f32_16x16x32_bf16 v[62:65], v[172:175], v[234:237], v[62:65]
	v_mfma_f32_16x16x32_bf16 v[94:97], v[144:147], v[214:217], v[94:97]
	v_mfma_f32_16x16x32_bf16 v[90:93], v[190:193], v[214:217], v[90:93]
	v_mfma_f32_16x16x32_bf16 v[86:89], v[144:147], v[222:225], v[86:89]
	v_mfma_f32_16x16x32_bf16 v[82:85], v[190:193], v[222:225], v[82:85]
	v_mfma_f32_16x16x32_bf16 v[78:81], v[144:147], v[230:233], v[78:81]
	v_mfma_f32_16x16x32_bf16 v[74:77], v[190:193], v[230:233], v[74:77]
	v_mfma_f32_16x16x32_bf16 v[70:73], v[144:147], v[238:241], v[70:73]
	v_mfma_f32_16x16x32_bf16 v[62:65], v[190:193], v[238:241], v[62:65]
	s_setprio 0
	s_setprio 1
	v_mfma_f32_16x16x32_bf16 v[30:33], v[194:197], v[210:213], v[30:33]
	v_mfma_f32_16x16x32_bf16 v[26:29], v[202:205], v[210:213], v[26:29]
	v_mfma_f32_16x16x32_bf16 v[22:25], v[194:197], v[218:221], v[22:25]
	v_mfma_f32_16x16x32_bf16 v[18:21], v[202:205], v[218:221], v[18:21]
	v_mfma_f32_16x16x32_bf16 v[14:17], v[194:197], v[226:229], v[14:17]
	v_mfma_f32_16x16x32_bf16 v[10:13], v[202:205], v[226:229], v[10:13]
	v_mfma_f32_16x16x32_bf16 v[6:9], v[194:197], v[234:237], v[6:9]
	v_mfma_f32_16x16x32_bf16 v[0:3], v[202:205], v[234:237], v[0:3]
	v_mfma_f32_16x16x32_bf16 v[30:33], v[198:201], v[214:217], v[30:33]
	v_mfma_f32_16x16x32_bf16 v[26:29], v[206:209], v[214:217], v[26:29]
	v_mfma_f32_16x16x32_bf16 v[22:25], v[198:201], v[222:225], v[22:25]
	v_mfma_f32_16x16x32_bf16 v[18:21], v[206:209], v[222:225], v[18:21]
	v_mfma_f32_16x16x32_bf16 v[14:17], v[198:201], v[230:233], v[14:17]
	v_mfma_f32_16x16x32_bf16 v[10:13], v[206:209], v[230:233], v[10:13]
	v_mfma_f32_16x16x32_bf16 v[6:9], v[198:201], v[238:241], v[6:9]
	v_mfma_f32_16x16x32_bf16 v[0:3], v[206:209], v[238:241], v[0:3]
	s_setprio 0
	s_barrier
.Lpeelmid_228:
	s_add_i32 s3, 0, 0x18000
	v_add_u32_e32 v164, s3, v149
	s_add_i32 s6, 0, 0x1c000
	ds_read_b128 v[140:143], v164
	ds_read_b128 v[144:147], v164 offset:1024
	ds_read_b128 v[172:175], v164 offset:2048
	ds_read_b128 v[190:193], v164 offset:3072
	v_add_u32_e32 v164, s6, v149
	ds_read_b128 v[194:197], v164
	ds_read_b128 v[198:201], v164 offset:1024
	ds_read_b128 v[202:205], v164 offset:2048
	ds_read_b128 v[206:209], v164 offset:3072
	s_add_u32 s4, s14, 0x40000
	s_addc_u32 s5, s15, 0
	s_mov_b32 m0, s31
	v_lshl_add_u64 v[242:243], s[4:5], 0, v[130:131]
	ds_read_b128 v[210:213], v151 offset:32768
	ds_read_b128 v[214:217], v151 offset:33792
	ds_read_b128 v[218:221], v151 offset:34816
	ds_read_b128 v[222:225], v151 offset:35840
	ds_read_b128 v[226:229], v151 offset:36864
	ds_read_b128 v[230:233], v151 offset:37888
	ds_read_b128 v[234:237], v151 offset:38912
	ds_read_b128 v[238:241], v151 offset:39936
	global_load_lds_dwordx4 v[242:243], off
	s_mov_b32 m0, s34
	v_lshl_add_u64 v[242:243], s[4:5], 0, v[132:133]
	global_load_lds_dwordx4 v[242:243], off
	s_waitcnt vmcnt(8)
	s_waitcnt lgkmcnt(0)
	s_barrier
	s_setprio 1
	s_waitcnt lgkmcnt(0)
	v_mfma_f32_16x16x32_bf16 v[126:129], v[140:143], v[210:213], v[126:129]
	v_mfma_f32_16x16x32_bf16 v[122:125], v[172:175], v[210:213], v[122:125]
	v_mfma_f32_16x16x32_bf16 v[118:121], v[140:143], v[218:221], v[118:121]
	v_mfma_f32_16x16x32_bf16 v[114:117], v[172:175], v[218:221], v[114:117]
	v_mfma_f32_16x16x32_bf16 v[110:113], v[140:143], v[226:229], v[110:113]
	v_mfma_f32_16x16x32_bf16 v[106:109], v[172:175], v[226:229], v[106:109]
	v_mfma_f32_16x16x32_bf16 v[102:105], v[140:143], v[234:237], v[102:105]
	v_mfma_f32_16x16x32_bf16 v[98:101], v[172:175], v[234:237], v[98:101]
	v_mfma_f32_16x16x32_bf16 v[126:129], v[144:147], v[214:217], v[126:129]
	v_mfma_f32_16x16x32_bf16 v[122:125], v[190:193], v[214:217], v[122:125]
	v_mfma_f32_16x16x32_bf16 v[118:121], v[144:147], v[222:225], v[118:121]
	v_mfma_f32_16x16x32_bf16 v[114:117], v[190:193], v[222:225], v[114:117]
	v_mfma_f32_16x16x32_bf16 v[110:113], v[144:147], v[230:233], v[110:113]
	v_mfma_f32_16x16x32_bf16 v[106:109], v[190:193], v[230:233], v[106:109]
	v_mfma_f32_16x16x32_bf16 v[102:105], v[144:147], v[238:241], v[102:105]
	v_mfma_f32_16x16x32_bf16 v[98:101], v[190:193], v[238:241], v[98:101]
	s_setprio 0
	s_setprio 1
	v_mfma_f32_16x16x32_bf16 v[66:69], v[194:197], v[210:213], v[66:69]
	v_mfma_f32_16x16x32_bf16 v[58:61], v[202:205], v[210:213], v[58:61]
	v_mfma_f32_16x16x32_bf16 v[54:57], v[194:197], v[218:221], v[54:57]
	v_mfma_f32_16x16x32_bf16 v[50:53], v[202:205], v[218:221], v[50:53]
	v_mfma_f32_16x16x32_bf16 v[46:49], v[194:197], v[226:229], v[46:49]
	v_mfma_f32_16x16x32_bf16 v[42:45], v[202:205], v[226:229], v[42:45]
	v_mfma_f32_16x16x32_bf16 v[38:41], v[194:197], v[234:237], v[38:41]
	v_mfma_f32_16x16x32_bf16 v[34:37], v[202:205], v[234:237], v[34:37]
	v_mfma_f32_16x16x32_bf16 v[66:69], v[198:201], v[214:217], v[66:69]
	v_mfma_f32_16x16x32_bf16 v[58:61], v[206:209], v[214:217], v[58:61]
	v_mfma_f32_16x16x32_bf16 v[54:57], v[198:201], v[222:225], v[54:57]
	v_mfma_f32_16x16x32_bf16 v[50:53], v[206:209], v[222:225], v[50:53]
	v_mfma_f32_16x16x32_bf16 v[46:49], v[198:201], v[230:233], v[46:49]
	v_mfma_f32_16x16x32_bf16 v[42:45], v[206:209], v[230:233], v[42:45]
	v_mfma_f32_16x16x32_bf16 v[38:41], v[198:201], v[238:241], v[38:41]
	v_mfma_f32_16x16x32_bf16 v[34:37], v[206:209], v[238:241], v[34:37]
	s_setprio 0
	s_barrier
	s_add_i32 s3, s3, s26
	v_lshl_add_u64 v[162:163], v[162:163], 0, s[70:71]
	s_mov_b32 m0, s3
	ds_read_b128 v[210:213], v151 offset:49152
	ds_read_b128 v[214:217], v151 offset:50176
	ds_read_b128 v[218:221], v151 offset:51200
	ds_read_b128 v[222:225], v151 offset:52224
	ds_read_b128 v[226:229], v151 offset:53248
	ds_read_b128 v[230:233], v151 offset:54272
	ds_read_b128 v[234:237], v151 offset:55296
	ds_read_b128 v[238:241], v151 offset:56320
	global_load_lds_dwordx4 v[162:163], off
	s_add_i32 m0, s3, 0x2000
	s_add_u32 s0, s0, 0x40080
	v_lshl_add_u64 v[162:163], v[166:167], 0, s[70:71]
	s_addc_u32 s1, s1, 0
	s_add_i32 s3, s6, s26
	global_load_lds_dwordx4 v[162:163], off
	s_mov_b32 m0, s3
	v_lshl_add_u64 v[162:163], s[0:1], 0, v[4:5]
	global_load_lds_dwordx4 v[162:163], off
	s_add_i32 m0, s3, 0x2000
	v_lshl_add_u64 v[162:163], s[0:1], 0, v[134:135]
	global_load_lds_dwordx4 v[162:163], off
	s_mov_b32 m0, s35
	v_lshl_add_u64 v[162:163], v[176:177], 0, s[70:71]
	global_load_lds_dwordx4 v[162:163], off
	s_mov_b32 m0, s36
	v_lshl_add_u64 v[162:163], v[180:181], 0, s[70:71]
	global_load_lds_dwordx4 v[162:163], off
	s_waitcnt vmcnt(8)
	s_waitcnt lgkmcnt(0)
	s_barrier
	s_setprio 1
	s_waitcnt lgkmcnt(0)
	v_mfma_f32_16x16x32_bf16 v[94:97], v[140:143], v[210:213], v[94:97]
	v_mfma_f32_16x16x32_bf16 v[90:93], v[172:175], v[210:213], v[90:93]
	v_mfma_f32_16x16x32_bf16 v[86:89], v[140:143], v[218:221], v[86:89]
	v_mfma_f32_16x16x32_bf16 v[82:85], v[172:175], v[218:221], v[82:85]
	v_mfma_f32_16x16x32_bf16 v[78:81], v[140:143], v[226:229], v[78:81]
	v_mfma_f32_16x16x32_bf16 v[74:77], v[172:175], v[226:229], v[74:77]
	v_mfma_f32_16x16x32_bf16 v[70:73], v[140:143], v[234:237], v[70:73]
	v_mfma_f32_16x16x32_bf16 v[62:65], v[172:175], v[234:237], v[62:65]
	v_mfma_f32_16x16x32_bf16 v[94:97], v[144:147], v[214:217], v[94:97]
	v_mfma_f32_16x16x32_bf16 v[90:93], v[190:193], v[214:217], v[90:93]
	v_mfma_f32_16x16x32_bf16 v[86:89], v[144:147], v[222:225], v[86:89]
	v_mfma_f32_16x16x32_bf16 v[82:85], v[190:193], v[222:225], v[82:85]
	v_mfma_f32_16x16x32_bf16 v[78:81], v[144:147], v[230:233], v[78:81]
	v_mfma_f32_16x16x32_bf16 v[74:77], v[190:193], v[230:233], v[74:77]
	v_mfma_f32_16x16x32_bf16 v[70:73], v[144:147], v[238:241], v[70:73]
	v_mfma_f32_16x16x32_bf16 v[62:65], v[190:193], v[238:241], v[62:65]
	s_setprio 0
	s_setprio 1
	v_mfma_f32_16x16x32_bf16 v[30:33], v[194:197], v[210:213], v[30:33]
	v_mfma_f32_16x16x32_bf16 v[26:29], v[202:205], v[210:213], v[26:29]
	v_mfma_f32_16x16x32_bf16 v[22:25], v[194:197], v[218:221], v[22:25]
	v_mfma_f32_16x16x32_bf16 v[18:21], v[202:205], v[218:221], v[18:21]
	v_mfma_f32_16x16x32_bf16 v[14:17], v[194:197], v[226:229], v[14:17]
	v_mfma_f32_16x16x32_bf16 v[10:13], v[202:205], v[226:229], v[10:13]
	v_mfma_f32_16x16x32_bf16 v[6:9], v[194:197], v[234:237], v[6:9]
	v_mfma_f32_16x16x32_bf16 v[0:3], v[202:205], v[234:237], v[0:3]
	v_mfma_f32_16x16x32_bf16 v[30:33], v[198:201], v[214:217], v[30:33]
	v_mfma_f32_16x16x32_bf16 v[26:29], v[206:209], v[214:217], v[26:29]
	v_mfma_f32_16x16x32_bf16 v[22:25], v[198:201], v[222:225], v[22:25]
	v_mfma_f32_16x16x32_bf16 v[18:21], v[206:209], v[222:225], v[18:21]
	v_mfma_f32_16x16x32_bf16 v[14:17], v[198:201], v[230:233], v[14:17]
	v_mfma_f32_16x16x32_bf16 v[10:13], v[206:209], v[230:233], v[10:13]
	v_mfma_f32_16x16x32_bf16 v[6:9], v[198:201], v[238:241], v[6:9]
	v_mfma_f32_16x16x32_bf16 v[0:3], v[206:209], v[238:241], v[0:3]
	s_setprio 0
	s_barrier
	s_add_i32 s24, s24, 2
	s_add_u32 s22, s22, 0x100
	s_addc_u32 s23, s23, 0
	s_add_u32 s9, s9, 0x100
	s_addc_u32 s10, s10, 0
	s_cmp_gt_u32 s24, 13
	s_cbranch_scc0 .LBB0_228
	s_and_b64 vcc, exec, s[44:45]
	s_cbranch_vccz .LBB0_231
	s_barrier

.LBB0_251:
	s_ashr_i32 s47, s46, 31
	s_lshl_b64 s[2:3], s[46:47], 20
	v_readlane_b32 s4, v253, 36
	s_add_u32 s82, s4, s2
	v_readlane_b32 s2, v253, 37
	s_addc_u32 s83, s2, s3
	s_and_b64 s[2:3], s[40:41], exec
	s_cselect_b32 s2, s83, s15
	s_cselect_b32 s8, s82, s14
	s_add_u32 s22, s0, 0x80080
	s_addc_u32 s23, s1, 0
	s_add_u32 s9, s14, 0x100
	v_mov_b32_e32 v0, 0
	s_addc_u32 s10, s15, 0
	s_mov_b32 s24, -2
	v_mov_b32_e32 v1, v0
	v_mov_b32_e32 v2, v0
	v_mov_b32_e32 v3, v0
	v_mov_b32_e32 v6, v0
	v_mov_b32_e32 v7, v0
	v_mov_b32_e32 v8, v0
	v_mov_b32_e32 v9, v0
	v_mov_b32_e32 v10, v0
	v_mov_b32_e32 v11, v0
	v_mov_b32_e32 v12, v0
	v_mov_b32_e32 v13, v0
	v_mov_b32_e32 v14, v0
	v_mov_b32_e32 v15, v0
	v_mov_b32_e32 v16, v0
	v_mov_b32_e32 v17, v0
	v_mov_b32_e32 v18, v0
	v_mov_b32_e32 v19, v0
	v_mov_b32_e32 v20, v0
	v_mov_b32_e32 v21, v0
	v_mov_b32_e32 v22, v0
	v_mov_b32_e32 v23, v0
	v_mov_b32_e32 v24, v0
	v_mov_b32_e32 v25, v0
	v_mov_b32_e32 v26, v0
	v_mov_b32_e32 v27, v0
	v_mov_b32_e32 v28, v0
	v_mov_b32_e32 v29, v0
	v_mov_b32_e32 v30, v0
	v_mov_b32_e32 v31, v0
	v_mov_b32_e32 v32, v0
	v_mov_b32_e32 v33, v0
	v_mov_b32_e32 v62, v0
	v_mov_b32_e32 v63, v0
	v_mov_b32_e32 v64, v0
	v_mov_b32_e32 v65, v0
	v_mov_b32_e32 v70, v0
	v_mov_b32_e32 v71, v0
	v_mov_b32_e32 v72, v0
	v_mov_b32_e32 v73, v0
	v_mov_b32_e32 v74, v0
	v_mov_b32_e32 v75, v0
	v_mov_b32_e32 v76, v0
	v_mov_b32_e32 v77, v0
	v_mov_b32_e32 v78, v0
	v_mov_b32_e32 v79, v0
	v_mov_b32_e32 v80, v0
	v_mov_b32_e32 v81, v0
	v_mov_b32_e32 v82, v0
	v_mov_b32_e32 v83, v0
	v_mov_b32_e32 v84, v0
	v_mov_b32_e32 v85, v0
	v_mov_b32_e32 v86, v0
	v_mov_b32_e32 v87, v0
	v_mov_b32_e32 v88, v0
	v_mov_b32_e32 v89, v0
	v_mov_b32_e32 v90, v0
	v_mov_b32_e32 v91, v0
	v_mov_b32_e32 v92, v0
	v_mov_b32_e32 v93, v0
	v_mov_b32_e32 v94, v0
	v_mov_b32_e32 v95, v0
	v_mov_b32_e32 v96, v0
	v_mov_b32_e32 v97, v0
	v_mov_b32_e32 v34, v0
	v_mov_b32_e32 v35, v0
	v_mov_b32_e32 v36, v0
	v_mov_b32_e32 v37, v0
	v_mov_b32_e32 v38, v0
	v_mov_b32_e32 v39, v0
	v_mov_b32_e32 v40, v0
	v_mov_b32_e32 v41, v0
	v_mov_b32_e32 v42, v0
	v_mov_b32_e32 v43, v0
	v_mov_b32_e32 v44, v0
	v_mov_b32_e32 v45, v0
	v_mov_b32_e32 v46, v0
	v_mov_b32_e32 v47, v0
	v_mov_b32_e32 v48, v0
	v_mov_b32_e32 v49, v0
	v_mov_b32_e32 v50, v0
	v_mov_b32_e32 v51, v0
	v_mov_b32_e32 v52, v0
	v_mov_b32_e32 v53, v0
	v_mov_b32_e32 v54, v0
	v_mov_b32_e32 v55, v0
	v_mov_b32_e32 v56, v0
	v_mov_b32_e32 v57, v0
	v_mov_b32_e32 v58, v0
	v_mov_b32_e32 v59, v0
	v_mov_b32_e32 v60, v0
	v_mov_b32_e32 v61, v0
	v_mov_b32_e32 v66, v0
	v_mov_b32_e32 v67, v0
	v_mov_b32_e32 v68, v0
	v_mov_b32_e32 v69, v0
	v_mov_b32_e32 v98, v0
	v_mov_b32_e32 v99, v0
	v_mov_b32_e32 v100, v0
	v_mov_b32_e32 v101, v0
	v_mov_b32_e32 v102, v0
	v_mov_b32_e32 v103, v0
	v_mov_b32_e32 v104, v0
	v_mov_b32_e32 v105, v0
	v_mov_b32_e32 v106, v0
	v_mov_b32_e32 v107, v0
	v_mov_b32_e32 v108, v0
	v_mov_b32_e32 v109, v0
	v_mov_b32_e32 v110, v0
	v_mov_b32_e32 v111, v0
	v_mov_b32_e32 v112, v0
	v_mov_b32_e32 v113, v0
	v_mov_b32_e32 v114, v0
	v_mov_b32_e32 v115, v0
	v_mov_b32_e32 v116, v0
	v_mov_b32_e32 v117, v0
	v_mov_b32_e32 v118, v0
	v_mov_b32_e32 v119, v0
	v_mov_b32_e32 v120, v0
	v_mov_b32_e32 v121, v0
	v_mov_b32_e32 v122, v0
	v_mov_b32_e32 v123, v0
	v_mov_b32_e32 v124, v0
	v_mov_b32_e32 v125, v0
	v_mov_b32_e32 v126, v0
	v_mov_b32_e32 v127, v0
	v_mov_b32_e32 v128, v0
	v_mov_b32_e32 v129, v0
	s_cmp_eq_u32 s37, 1
	s_cbranch_scc1 .LBB0_252
	s_add_u32 s0, s22, 0xfff80080
	s_addc_u32 s1, s23, -1
	s_add_i32 s3, 0, 0x10000
	s_cmp_eq_u32 s24, 28
	s_cselect_b32 s15, s49, s1
	s_cselect_b32 s14, s48, s0
	v_add_u32_e32 v162, s3, v141
	s_cselect_b32 s1, s2, s10
	s_cselect_b32 s0, s8, s9
	s_add_i32 s6, 0, 0x14000
	ds_read_b128 v[144:147], v162
	ds_read_b128 v[148:151], v162 offset:1024
	ds_read_b128 v[172:175], v162 offset:2048
	ds_read_b128 v[190:193], v162 offset:3072
	v_add_u32_e32 v162, s6, v141
	ds_read_b128 v[194:197], v162
	ds_read_b128 v[198:201], v162 offset:1024
	ds_read_b128 v[202:205], v162 offset:2048
	ds_read_b128 v[206:209], v162 offset:3072
	v_lshl_add_u64 v[162:163], s[22:23], 0, v[136:137]
	s_add_i32 m0, s27, 0xc000
	ds_read_b128 v[210:213], v143
	ds_read_b128 v[214:217], v143 offset:1024
	ds_read_b128 v[218:221], v143 offset:2048
	ds_read_b128 v[222:225], v143 offset:3072
	ds_read_b128 v[226:229], v143 offset:4096
	ds_read_b128 v[230:233], v143 offset:5120
	ds_read_b128 v[234:237], v143 offset:6144
	ds_read_b128 v[238:241], v143 offset:7168
	global_load_lds_dwordx4 v[162:163], off
	s_add_i32 m0, s27, 0xe000
	v_lshl_add_u64 v[162:163], s[22:23], 0, v[138:139]
	global_load_lds_dwordx4 v[162:163], off
	s_waitcnt vmcnt(24)
	s_waitcnt lgkmcnt(0)
	s_barrier
	s_setprio 1
	s_waitcnt lgkmcnt(0)
	v_mfma_f32_16x16x32_bf16 v[126:129], v[144:147], v[210:213], v[126:129]
	v_mfma_f32_16x16x32_bf16 v[122:125], v[172:175], v[210:213], v[122:125]
	v_mfma_f32_16x16x32_bf16 v[118:121], v[144:147], v[218:221], v[118:121]
	v_mfma_f32_16x16x32_bf16 v[114:117], v[172:175], v[218:221], v[114:117]
	v_mfma_f32_16x16x32_bf16 v[110:113], v[144:147], v[226:229], v[110:113]
	v_mfma_f32_16x16x32_bf16 v[106:109], v[172:175], v[226:229], v[106:109]
	v_mfma_f32_16x16x32_bf16 v[102:105], v[144:147], v[234:237], v[102:105]
	v_mfma_f32_16x16x32_bf16 v[98:101], v[172:175], v[234:237], v[98:101]
	v_mfma_f32_16x16x32_bf16 v[126:129], v[148:151], v[214:217], v[126:129]
	v_mfma_f32_16x16x32_bf16 v[122:125], v[190:193], v[214:217], v[122:125]
	v_mfma_f32_16x16x32_bf16 v[118:121], v[148:151], v[222:225], v[118:121]
	v_mfma_f32_16x16x32_bf16 v[114:117], v[190:193], v[222:225], v[114:117]
	v_mfma_f32_16x16x32_bf16 v[110:113], v[148:151], v[230:233], v[110:113]
	v_mfma_f32_16x16x32_bf16 v[106:109], v[190:193], v[230:233], v[106:109]
	v_mfma_f32_16x16x32_bf16 v[102:105], v[148:151], v[238:241], v[102:105]
	v_mfma_f32_16x16x32_bf16 v[98:101], v[190:193], v[238:241], v[98:101]
	s_setprio 0
	s_setprio 1
	v_mfma_f32_16x16x32_bf16 v[66:69], v[194:197], v[210:213], v[66:69]
	v_mfma_f32_16x16x32_bf16 v[58:61], v[202:205], v[210:213], v[58:61]
	v_mfma_f32_16x16x32_bf16 v[54:57], v[194:197], v[218:221], v[54:57]
	v_mfma_f32_16x16x32_bf16 v[50:53], v[202:205], v[218:221], v[50:53]
	v_mfma_f32_16x16x32_bf16 v[46:49], v[194:197], v[226:229], v[46:49]
	v_mfma_f32_16x16x32_bf16 v[42:45], v[202:205], v[226:229], v[42:45]
	v_mfma_f32_16x16x32_bf16 v[38:41], v[194:197], v[234:237], v[38:41]
	v_mfma_f32_16x16x32_bf16 v[34:37], v[202:205], v[234:237], v[34:37]
	v_mfma_f32_16x16x32_bf16 v[66:69], v[198:201], v[214:217], v[66:69]
	v_mfma_f32_16x16x32_bf16 v[58:61], v[206:209], v[214:217], v[58:61]
	v_mfma_f32_16x16x32_bf16 v[54:57], v[198:201], v[222:225], v[54:57]
	v_mfma_f32_16x16x32_bf16 v[50:53], v[206:209], v[222:225], v[50:53]
	v_mfma_f32_16x16x32_bf16 v[46:49], v[198:201], v[230:233], v[46:49]
	v_mfma_f32_16x16x32_bf16 v[42:45], v[206:209], v[230:233], v[42:45]
	v_mfma_f32_16x16x32_bf16 v[38:41], v[198:201], v[238:241], v[38:41]
	v_mfma_f32_16x16x32_bf16 v[34:37], v[206:209], v[238:241], v[34:37]
	s_setprio 0
	s_barrier
	s_add_i32 s3, s3, s26
	v_lshl_add_u64 v[162:163], s[0:1], 0, v[4:5]
	s_mov_b32 m0, s3
	ds_read_b128 v[210:213], v143 offset:16384
	ds_read_b128 v[214:217], v143 offset:17408
	ds_read_b128 v[218:221], v143 offset:18432
	ds_read_b128 v[222:225], v143 offset:19456
	ds_read_b128 v[226:229], v143 offset:20480
	ds_read_b128 v[230:233], v143 offset:21504
	ds_read_b128 v[234:237], v143 offset:22528
	ds_read_b128 v[238:241], v143 offset:23552
	global_load_lds_dwordx4 v[162:163], off
	s_add_i32 m0, s3, 0x2000
	s_add_u32 s4, s0, 0x80000
	v_lshl_add_u64 v[166:167], s[0:1], 0, v[130:131]
	s_addc_u32 s5, s1, 0
	s_add_i32 s3, s6, s26
	global_load_lds_dwordx4 v[166:167], off
	v_lshl_add_u64 v[176:177], s[4:5], 0, v[4:5]
	s_mov_b32 m0, s3
	v_lshl_add_u64 v[242:243], s[14:15], 0, v[132:133]
	global_load_lds_dwordx4 v[176:177], off
	s_add_i32 m0, s3, 0x2000
	v_lshl_add_u64 v[176:177], s[4:5], 0, v[130:131]
	global_load_lds_dwordx4 v[176:177], off
	s_mov_b32 m0, s27
	v_lshl_add_u64 v[176:177], s[14:15], 0, v[134:135]
	global_load_lds_dwordx4 v[176:177], off
	s_mov_b32 m0, s30
	s_nop 0
	global_load_lds_dwordx4 v[242:243], off
	s_waitcnt vmcnt(24)
	s_waitcnt lgkmcnt(0)
	s_barrier
	s_setprio 1
	s_waitcnt lgkmcnt(0)
	v_mfma_f32_16x16x32_bf16 v[94:97], v[144:147], v[210:213], v[94:97]
	v_mfma_f32_16x16x32_bf16 v[90:93], v[172:175], v[210:213], v[90:93]
	v_mfma_f32_16x16x32_bf16 v[86:89], v[144:147], v[218:221], v[86:89]
	v_mfma_f32_16x16x32_bf16 v[82:85], v[172:175], v[218:221], v[82:85]
	v_mfma_f32_16x16x32_bf16 v[78:81], v[144:147], v[226:229], v[78:81]
	v_mfma_f32_16x16x32_bf16 v[74:77], v[172:175], v[226:229], v[74:77]
	v_mfma_f32_16x16x32_bf16 v[70:73], v[144:147], v[234:237], v[70:73]
	v_mfma_f32_16x16x32_bf16 v[62:65], v[172:175], v[234:237], v[62:65]
	v_mfma_f32_16x16x32_bf16 v[94:97], v[148:151], v[214:217], v[94:97]
	v_mfma_f32_16x16x32_bf16 v[90:93], v[190:193], v[214:217], v[90:93]
	v_mfma_f32_16x16x32_bf16 v[86:89], v[148:151], v[222:225], v[86:89]
	v_mfma_f32_16x16x32_bf16 v[82:85], v[190:193], v[222:225], v[82:85]
	v_mfma_f32_16x16x32_bf16 v[78:81], v[148:151], v[230:233], v[78:81]
	v_mfma_f32_16x16x32_bf16 v[74:77], v[190:193], v[230:233], v[74:77]
	v_mfma_f32_16x16x32_bf16 v[70:73], v[148:151], v[238:241], v[70:73]
	v_mfma_f32_16x16x32_bf16 v[62:65], v[190:193], v[238:241], v[62:65]
	s_setprio 0
	s_setprio 1
	v_mfma_f32_16x16x32_bf16 v[30:33], v[194:197], v[210:213], v[30:33]
	v_mfma_f32_16x16x32_bf16 v[26:29], v[202:205], v[210:213], v[26:29]
	v_mfma_f32_16x16x32_bf16 v[22:25], v[194:197], v[218:221], v[22:25]
	v_mfma_f32_16x16x32_bf16 v[18:21], v[202:205], v[218:221], v[18:21]
	v_mfma_f32_16x16x32_bf16 v[14:17], v[194:197], v[226:229], v[14:17]
	v_mfma_f32_16x16x32_bf16 v[10:13], v[202:205], v[226:229], v[10:13]
	v_mfma_f32_16x16x32_bf16 v[6:9], v[194:197], v[234:237], v[6:9]
	v_mfma_f32_16x16x32_bf16 v[0:3], v[202:205], v[234:237], v[0:3]
	v_mfma_f32_16x16x32_bf16 v[30:33], v[198:201], v[214:217], v[30:33]
	v_mfma_f32_16x16x32_bf16 v[26:29], v[206:209], v[214:217], v[26:29]
	v_mfma_f32_16x16x32_bf16 v[22:25], v[198:201], v[222:225], v[22:25]
	v_mfma_f32_16x16x32_bf16 v[18:21], v[206:209], v[222:225], v[18:21]
	v_mfma_f32_16x16x32_bf16 v[14:17], v[198:201], v[230:233], v[14:17]
	v_mfma_f32_16x16x32_bf16 v[10:13], v[206:209], v[230:233], v[10:13]
	v_mfma_f32_16x16x32_bf16 v[6:9], v[198:201], v[238:241], v[6:9]
	v_mfma_f32_16x16x32_bf16 v[0:3], v[206:209], v[238:241], v[0:3]
	s_setprio 0
	s_barrier
	s_branch .Lpeelmid_252
.LBB0_252:
	s_add_u32 s0, s22, 0xfff80080
	s_addc_u32 s1, s23, -1
	s_add_i32 s3, 0, 0x10000
	s_cmp_eq_u32 s24, 28
	s_cselect_b32 s15, s49, s1
	s_cselect_b32 s14, s48, s0
	v_add_u32_e32 v162, s3, v141
	s_cselect_b32 s1, s2, s10
	s_cselect_b32 s0, s8, s9
	s_add_i32 s6, 0, 0x14000
	ds_read_b128 v[144:147], v162
	ds_read_b128 v[148:151], v162 offset:1024
	ds_read_b128 v[172:175], v162 offset:2048
	ds_read_b128 v[190:193], v162 offset:3072
	v_add_u32_e32 v162, s6, v141
	ds_read_b128 v[194:197], v162
	ds_read_b128 v[198:201], v162 offset:1024
	ds_read_b128 v[202:205], v162 offset:2048
	ds_read_b128 v[206:209], v162 offset:3072
	v_lshl_add_u64 v[162:163], s[22:23], 0, v[136:137]
	s_add_i32 m0, s27, 0xc000
	ds_read_b128 v[210:213], v143
	ds_read_b128 v[214:217], v143 offset:1024
	ds_read_b128 v[218:221], v143 offset:2048
	ds_read_b128 v[222:225], v143 offset:3072
	ds_read_b128 v[226:229], v143 offset:4096
	ds_read_b128 v[230:233], v143 offset:5120
	ds_read_b128 v[234:237], v143 offset:6144
	ds_read_b128 v[238:241], v143 offset:7168
	global_load_lds_dwordx4 v[162:163], off
	s_add_i32 m0, s27, 0xe000
	v_lshl_add_u64 v[162:163], s[22:23], 0, v[138:139]
	global_load_lds_dwordx4 v[162:163], off
	s_waitcnt vmcnt(8)
	s_waitcnt lgkmcnt(0)
	s_barrier
	s_setprio 1
	s_waitcnt lgkmcnt(0)
	v_mfma_f32_16x16x32_bf16 v[126:129], v[144:147], v[210:213], v[126:129]
	v_mfma_f32_16x16x32_bf16 v[122:125], v[172:175], v[210:213], v[122:125]
	v_mfma_f32_16x16x32_bf16 v[118:121], v[144:147], v[218:221], v[118:121]
	v_mfma_f32_16x16x32_bf16 v[114:117], v[172:175], v[218:221], v[114:117]
	v_mfma_f32_16x16x32_bf16 v[110:113], v[144:147], v[226:229], v[110:113]
	v_mfma_f32_16x16x32_bf16 v[106:109], v[172:175], v[226:229], v[106:109]
	v_mfma_f32_16x16x32_bf16 v[102:105], v[144:147], v[234:237], v[102:105]
	v_mfma_f32_16x16x32_bf16 v[98:101], v[172:175], v[234:237], v[98:101]
	v_mfma_f32_16x16x32_bf16 v[126:129], v[148:151], v[214:217], v[126:129]
	v_mfma_f32_16x16x32_bf16 v[122:125], v[190:193], v[214:217], v[122:125]
	v_mfma_f32_16x16x32_bf16 v[118:121], v[148:151], v[222:225], v[118:121]
	v_mfma_f32_16x16x32_bf16 v[114:117], v[190:193], v[222:225], v[114:117]
	v_mfma_f32_16x16x32_bf16 v[110:113], v[148:151], v[230:233], v[110:113]
	v_mfma_f32_16x16x32_bf16 v[106:109], v[190:193], v[230:233], v[106:109]
	v_mfma_f32_16x16x32_bf16 v[102:105], v[148:151], v[238:241], v[102:105]
	v_mfma_f32_16x16x32_bf16 v[98:101], v[190:193], v[238:241], v[98:101]
	s_setprio 0
	s_setprio 1
	v_mfma_f32_16x16x32_bf16 v[66:69], v[194:197], v[210:213], v[66:69]
	v_mfma_f32_16x16x32_bf16 v[58:61], v[202:205], v[210:213], v[58:61]
	v_mfma_f32_16x16x32_bf16 v[54:57], v[194:197], v[218:221], v[54:57]
	v_mfma_f32_16x16x32_bf16 v[50:53], v[202:205], v[218:221], v[50:53]
	v_mfma_f32_16x16x32_bf16 v[46:49], v[194:197], v[226:229], v[46:49]
	v_mfma_f32_16x16x32_bf16 v[42:45], v[202:205], v[226:229], v[42:45]
	v_mfma_f32_16x16x32_bf16 v[38:41], v[194:197], v[234:237], v[38:41]
	v_mfma_f32_16x16x32_bf16 v[34:37], v[202:205], v[234:237], v[34:37]
	v_mfma_f32_16x16x32_bf16 v[66:69], v[198:201], v[214:217], v[66:69]
	v_mfma_f32_16x16x32_bf16 v[58:61], v[206:209], v[214:217], v[58:61]
	v_mfma_f32_16x16x32_bf16 v[54:57], v[198:201], v[222:225], v[54:57]
	v_mfma_f32_16x16x32_bf16 v[50:53], v[206:209], v[222:225], v[50:53]
	v_mfma_f32_16x16x32_bf16 v[46:49], v[198:201], v[230:233], v[46:49]
	v_mfma_f32_16x16x32_bf16 v[42:45], v[206:209], v[230:233], v[42:45]
	v_mfma_f32_16x16x32_bf16 v[38:41], v[198:201], v[238:241], v[38:41]
	v_mfma_f32_16x16x32_bf16 v[34:37], v[206:209], v[238:241], v[34:37]
	s_setprio 0
	s_barrier
	s_add_i32 s3, s3, s26
	v_lshl_add_u64 v[162:163], s[0:1], 0, v[4:5]
	s_mov_b32 m0, s3
	ds_read_b128 v[210:213], v143 offset:16384
	ds_read_b128 v[214:217], v143 offset:17408
	ds_read_b128 v[218:221], v143 offset:18432
	ds_read_b128 v[222:225], v143 offset:19456
	ds_read_b128 v[226:229], v143 offset:20480
	ds_read_b128 v[230:233], v143 offset:21504
	ds_read_b128 v[234:237], v143 offset:22528
	ds_read_b128 v[238:241], v143 offset:23552
	global_load_lds_dwordx4 v[162:163], off
	s_add_i32 m0, s3, 0x2000
	s_add_u32 s4, s0, 0x80000
	v_lshl_add_u64 v[166:167], s[0:1], 0, v[130:131]
	s_addc_u32 s5, s1, 0
	s_add_i32 s3, s6, s26
	global_load_lds_dwordx4 v[166:167], off
	v_lshl_add_u64 v[176:177], s[4:5], 0, v[4:5]
	s_mov_b32 m0, s3
	v_lshl_add_u64 v[242:243], s[14:15], 0, v[132:133]
	global_load_lds_dwordx4 v[176:177], off
	s_add_i32 m0, s3, 0x2000
	v_lshl_add_u64 v[176:177], s[4:5], 0, v[130:131]
	global_load_lds_dwordx4 v[176:177], off
	s_mov_b32 m0, s27
	v_lshl_add_u64 v[176:177], s[14:15], 0, v[134:135]
	global_load_lds_dwordx4 v[176:177], off
	s_mov_b32 m0, s30
	s_nop 0
	global_load_lds_dwordx4 v[242:243], off
	s_waitcnt vmcnt(8)
	s_waitcnt lgkmcnt(0)
	s_barrier
	s_setprio 1
	s_waitcnt lgkmcnt(0)
	v_mfma_f32_16x16x32_bf16 v[94:97], v[144:147], v[210:213], v[94:97]
	v_mfma_f32_16x16x32_bf16 v[90:93], v[172:175], v[210:213], v[90:93]
	v_mfma_f32_16x16x32_bf16 v[86:89], v[144:147], v[218:221], v[86:89]
	v_mfma_f32_16x16x32_bf16 v[82:85], v[172:175], v[218:221], v[82:85]
	v_mfma_f32_16x16x32_bf16 v[78:81], v[144:147], v[226:229], v[78:81]
	v_mfma_f32_16x16x32_bf16 v[74:77], v[172:175], v[226:229], v[74:77]
	v_mfma_f32_16x16x32_bf16 v[70:73], v[144:147], v[234:237], v[70:73]
	v_mfma_f32_16x16x32_bf16 v[62:65], v[172:175], v[234:237], v[62:65]
	v_mfma_f32_16x16x32_bf16 v[94:97], v[148:151], v[214:217], v[94:97]
	v_mfma_f32_16x16x32_bf16 v[90:93], v[190:193], v[214:217], v[90:93]
	v_mfma_f32_16x16x32_bf16 v[86:89], v[148:151], v[222:225], v[86:89]
	v_mfma_f32_16x16x32_bf16 v[82:85], v[190:193], v[222:225], v[82:85]
	v_mfma_f32_16x16x32_bf16 v[78:81], v[148:151], v[230:233], v[78:81]
	v_mfma_f32_16x16x32_bf16 v[74:77], v[190:193], v[230:233], v[74:77]
	v_mfma_f32_16x16x32_bf16 v[70:73], v[148:151], v[238:241], v[70:73]
	v_mfma_f32_16x16x32_bf16 v[62:65], v[190:193], v[238:241], v[62:65]
	s_setprio 0
	s_setprio 1
	v_mfma_f32_16x16x32_bf16 v[30:33], v[194:197], v[210:213], v[30:33]
	v_mfma_f32_16x16x32_bf16 v[26:29], v[202:205], v[210:213], v[26:29]
	v_mfma_f32_16x16x32_bf16 v[22:25], v[194:197], v[218:221], v[22:25]
	v_mfma_f32_16x16x32_bf16 v[18:21], v[202:205], v[218:221], v[18:21]
	v_mfma_f32_16x16x32_bf16 v[14:17], v[194:197], v[226:229], v[14:17]
	v_mfma_f32_16x16x32_bf16 v[10:13], v[202:205], v[226:229], v[10:13]
	v_mfma_f32_16x16x32_bf16 v[6:9], v[194:197], v[234:237], v[6:9]
	v_mfma_f32_16x16x32_bf16 v[0:3], v[202:205], v[234:237], v[0:3]
	v_mfma_f32_16x16x32_bf16 v[30:33], v[198:201], v[214:217], v[30:33]
	v_mfma_f32_16x16x32_bf16 v[26:29], v[206:209], v[214:217], v[26:29]
	v_mfma_f32_16x16x32_bf16 v[22:25], v[198:201], v[222:225], v[22:25]
	v_mfma_f32_16x16x32_bf16 v[18:21], v[206:209], v[222:225], v[18:21]
	v_mfma_f32_16x16x32_bf16 v[14:17], v[198:201], v[230:233], v[14:17]
	v_mfma_f32_16x16x32_bf16 v[10:13], v[206:209], v[230:233], v[10:13]
	v_mfma_f32_16x16x32_bf16 v[6:9], v[198:201], v[238:241], v[6:9]
	v_mfma_f32_16x16x32_bf16 v[0:3], v[206:209], v[238:241], v[0:3]
	s_setprio 0
	s_barrier
.Lpeelmid_252:
	s_add_i32 s3, 0, 0x18000
	v_add_u32_e32 v164, s3, v141
	s_add_i32 s6, 0, 0x1c000
	ds_read_b128 v[144:147], v164
	ds_read_b128 v[148:151], v164 offset:1024
	ds_read_b128 v[172:175], v164 offset:2048
	ds_read_b128 v[190:193], v164 offset:3072
	v_add_u32_e32 v164, s6, v141
	ds_read_b128 v[194:197], v164
	ds_read_b128 v[198:201], v164 offset:1024
	ds_read_b128 v[202:205], v164 offset:2048
	ds_read_b128 v[206:209], v164 offset:3072
	s_add_u32 s4, s14, 0x80000
	s_addc_u32 s5, s15, 0
	s_mov_b32 m0, s31
	v_lshl_add_u64 v[244:245], s[4:5], 0, v[134:135]
	ds_read_b128 v[210:213], v143 offset:32768
	ds_read_b128 v[214:217], v143 offset:33792
	ds_read_b128 v[218:221], v143 offset:34816
	ds_read_b128 v[222:225], v143 offset:35840
	ds_read_b128 v[226:229], v143 offset:36864
	ds_read_b128 v[230:233], v143 offset:37888
	ds_read_b128 v[234:237], v143 offset:38912
	ds_read_b128 v[238:241], v143 offset:39936
	global_load_lds_dwordx4 v[244:245], off
	s_mov_b32 m0, s34
	v_lshl_add_u64 v[244:245], s[4:5], 0, v[132:133]
	global_load_lds_dwordx4 v[244:245], off
	s_waitcnt vmcnt(8)
	s_waitcnt lgkmcnt(0)
	s_barrier
	s_setprio 1
	s_waitcnt lgkmcnt(0)
	v_mfma_f32_16x16x32_bf16 v[126:129], v[144:147], v[210:213], v[126:129]
	v_mfma_f32_16x16x32_bf16 v[122:125], v[172:175], v[210:213], v[122:125]
	v_mfma_f32_16x16x32_bf16 v[118:121], v[144:147], v[218:221], v[118:121]
	v_mfma_f32_16x16x32_bf16 v[114:117], v[172:175], v[218:221], v[114:117]
	v_mfma_f32_16x16x32_bf16 v[110:113], v[144:147], v[226:229], v[110:113]
	v_mfma_f32_16x16x32_bf16 v[106:109], v[172:175], v[226:229], v[106:109]
	v_mfma_f32_16x16x32_bf16 v[102:105], v[144:147], v[234:237], v[102:105]
	v_mfma_f32_16x16x32_bf16 v[98:101], v[172:175], v[234:237], v[98:101]
	v_mfma_f32_16x16x32_bf16 v[126:129], v[148:151], v[214:217], v[126:129]
	v_mfma_f32_16x16x32_bf16 v[122:125], v[190:193], v[214:217], v[122:125]
	v_mfma_f32_16x16x32_bf16 v[118:121], v[148:151], v[222:225], v[118:121]
	v_mfma_f32_16x16x32_bf16 v[114:117], v[190:193], v[222:225], v[114:117]
	v_mfma_f32_16x16x32_bf16 v[110:113], v[148:151], v[230:233], v[110:113]
	v_mfma_f32_16x16x32_bf16 v[106:109], v[190:193], v[230:233], v[106:109]
	v_mfma_f32_16x16x32_bf16 v[102:105], v[148:151], v[238:241], v[102:105]
	v_mfma_f32_16x16x32_bf16 v[98:101], v[190:193], v[238:241], v[98:101]
	s_setprio 0
	s_setprio 1
	v_mfma_f32_16x16x32_bf16 v[66:69], v[194:197], v[210:213], v[66:69]
	v_mfma_f32_16x16x32_bf16 v[58:61], v[202:205], v[210:213], v[58:61]
	v_mfma_f32_16x16x32_bf16 v[54:57], v[194:197], v[218:221], v[54:57]
	v_mfma_f32_16x16x32_bf16 v[50:53], v[202:205], v[218:221], v[50:53]
	v_mfma_f32_16x16x32_bf16 v[46:49], v[194:197], v[226:229], v[46:49]
	v_mfma_f32_16x16x32_bf16 v[42:45], v[202:205], v[226:229], v[42:45]
	v_mfma_f32_16x16x32_bf16 v[38:41], v[194:197], v[234:237], v[38:41]
	v_mfma_f32_16x16x32_bf16 v[34:37], v[202:205], v[234:237], v[34:37]
	v_mfma_f32_16x16x32_bf16 v[66:69], v[198:201], v[214:217], v[66:69]
	v_mfma_f32_16x16x32_bf16 v[58:61], v[206:209], v[214:217], v[58:61]
	v_mfma_f32_16x16x32_bf16 v[54:57], v[198:201], v[222:225], v[54:57]
	v_mfma_f32_16x16x32_bf16 v[50:53], v[206:209], v[222:225], v[50:53]
	v_mfma_f32_16x16x32_bf16 v[46:49], v[198:201], v[230:233], v[46:49]
	v_mfma_f32_16x16x32_bf16 v[42:45], v[206:209], v[230:233], v[42:45]
	v_mfma_f32_16x16x32_bf16 v[38:41], v[198:201], v[238:241], v[38:41]
	v_mfma_f32_16x16x32_bf16 v[34:37], v[206:209], v[238:241], v[34:37]
	s_setprio 0
	s_barrier
	s_add_i32 s3, s3, s26
	v_lshl_add_u64 v[162:163], v[162:163], 0, s[70:71]
	s_mov_b32 m0, s3
	ds_read_b128 v[210:213], v143 offset:49152
	ds_read_b128 v[214:217], v143 offset:50176
	ds_read_b128 v[218:221], v143 offset:51200
	ds_read_b128 v[222:225], v143 offset:52224
	ds_read_b128 v[226:229], v143 offset:53248
	ds_read_b128 v[230:233], v143 offset:54272
	ds_read_b128 v[234:237], v143 offset:55296
	ds_read_b128 v[238:241], v143 offset:56320
	global_load_lds_dwordx4 v[162:163], off
	s_add_i32 m0, s3, 0x2000
	s_add_u32 s0, s0, 0x80080
	v_lshl_add_u64 v[162:163], v[166:167], 0, s[70:71]
	s_addc_u32 s1, s1, 0
	s_add_i32 s3, s6, s26
	global_load_lds_dwordx4 v[162:163], off
	s_mov_b32 m0, s3
	v_lshl_add_u64 v[162:163], s[0:1], 0, v[4:5]
	global_load_lds_dwordx4 v[162:163], off
	s_add_i32 m0, s3, 0x2000
	v_lshl_add_u64 v[162:163], s[0:1], 0, v[130:131]
	global_load_lds_dwordx4 v[162:163], off
	s_mov_b32 m0, s35
	v_lshl_add_u64 v[162:163], v[176:177], 0, s[70:71]
	global_load_lds_dwordx4 v[162:163], off
	s_mov_b32 m0, s36
	v_lshl_add_u64 v[162:163], v[242:243], 0, s[70:71]
	global_load_lds_dwordx4 v[162:163], off
	s_waitcnt vmcnt(8)
	s_waitcnt lgkmcnt(0)
	s_barrier
	s_setprio 1
	s_waitcnt lgkmcnt(0)
	v_mfma_f32_16x16x32_bf16 v[94:97], v[144:147], v[210:213], v[94:97]
	v_mfma_f32_16x16x32_bf16 v[90:93], v[172:175], v[210:213], v[90:93]
	v_mfma_f32_16x16x32_bf16 v[86:89], v[144:147], v[218:221], v[86:89]
	v_mfma_f32_16x16x32_bf16 v[82:85], v[172:175], v[218:221], v[82:85]
	v_mfma_f32_16x16x32_bf16 v[78:81], v[144:147], v[226:229], v[78:81]
	v_mfma_f32_16x16x32_bf16 v[74:77], v[172:175], v[226:229], v[74:77]
	v_mfma_f32_16x16x32_bf16 v[70:73], v[144:147], v[234:237], v[70:73]
	v_mfma_f32_16x16x32_bf16 v[62:65], v[172:175], v[234:237], v[62:65]
	v_mfma_f32_16x16x32_bf16 v[94:97], v[148:151], v[214:217], v[94:97]
	v_mfma_f32_16x16x32_bf16 v[90:93], v[190:193], v[214:217], v[90:93]
	v_mfma_f32_16x16x32_bf16 v[86:89], v[148:151], v[222:225], v[86:89]
	v_mfma_f32_16x16x32_bf16 v[82:85], v[190:193], v[222:225], v[82:85]
	v_mfma_f32_16x16x32_bf16 v[78:81], v[148:151], v[230:233], v[78:81]
	v_mfma_f32_16x16x32_bf16 v[74:77], v[190:193], v[230:233], v[74:77]
	v_mfma_f32_16x16x32_bf16 v[70:73], v[148:151], v[238:241], v[70:73]
	v_mfma_f32_16x16x32_bf16 v[62:65], v[190:193], v[238:241], v[62:65]
	s_setprio 0
	s_setprio 1
	v_mfma_f32_16x16x32_bf16 v[30:33], v[194:197], v[210:213], v[30:33]
	v_mfma_f32_16x16x32_bf16 v[26:29], v[202:205], v[210:213], v[26:29]
	v_mfma_f32_16x16x32_bf16 v[22:25], v[194:197], v[218:221], v[22:25]
	v_mfma_f32_16x16x32_bf16 v[18:21], v[202:205], v[218:221], v[18:21]
	v_mfma_f32_16x16x32_bf16 v[14:17], v[194:197], v[226:229], v[14:17]
	v_mfma_f32_16x16x32_bf16 v[10:13], v[202:205], v[226:229], v[10:13]
	v_mfma_f32_16x16x32_bf16 v[6:9], v[194:197], v[234:237], v[6:9]
	v_mfma_f32_16x16x32_bf16 v[0:3], v[202:205], v[234:237], v[0:3]
	v_mfma_f32_16x16x32_bf16 v[30:33], v[198:201], v[214:217], v[30:33]
	v_mfma_f32_16x16x32_bf16 v[26:29], v[206:209], v[214:217], v[26:29]
	v_mfma_f32_16x16x32_bf16 v[22:25], v[198:201], v[222:225], v[22:25]
	v_mfma_f32_16x16x32_bf16 v[18:21], v[206:209], v[222:225], v[18:21]
	v_mfma_f32_16x16x32_bf16 v[14:17], v[198:201], v[230:233], v[14:17]
	v_mfma_f32_16x16x32_bf16 v[10:13], v[206:209], v[230:233], v[10:13]
	v_mfma_f32_16x16x32_bf16 v[6:9], v[198:201], v[238:241], v[6:9]
	v_mfma_f32_16x16x32_bf16 v[0:3], v[206:209], v[238:241], v[0:3]
	s_setprio 0
	s_barrier
	s_add_i32 s24, s24, 2
	s_add_u32 s22, s22, 0x100
	s_addc_u32 s23, s23, 0
	s_add_u32 s9, s9, 0x100
	s_addc_u32 s10, s10, 0
	s_cmp_gt_u32 s24, 29
	s_cbranch_scc0 .LBB0_252
	s_and_b64 vcc, exec, s[44:45]
	s_cbranch_vccz .LBB0_255
	s_barrier

.LBB0_851:
	s_ashr_i32 s3, s37, 24
	s_lshl_b32 s2, s37, 8
	s_andn2_b32 s3, s3, 63
	s_add_i32 s2, s3, s2
	s_ashr_i32 s3, s2, 31
	s_lshl_b64 s[2:3], s[2:3], 12
	v_readlane_b32 s4, v252, 6
	v_readlane_b32 s5, v252, 7
	s_add_u32 s76, s4, s2
	s_addc_u32 s77, s5, s3
	s_and_b64 s[2:3], s[38:39], exec
	s_cselect_b32 s2, s77, s15
	s_cselect_b32 s8, s76, s14
	s_ashr_i32 s59, s58, 31
	s_lshl_b64 s[4:5], s[58:59], 20
	v_readlane_b32 s6, v252, 4
	v_readlane_b32 s7, v252, 5
	s_add_u32 s78, s6, s4
	s_addc_u32 s79, s7, s5
	s_and_b64 s[4:5], s[38:39], exec
	s_cselect_b32 s10, s79, s1
	s_cselect_b32 s24, s78, s0
	s_add_u32 s22, s14, 0x80080
	s_addc_u32 s23, s15, 0
	s_add_u32 s9, s0, 0x100
	v_mov_b32_e32 v0, 0
	s_addc_u32 s25, s1, 0
	s_mov_b32 s28, -2
	v_mov_b32_e32 v1, v0
	v_mov_b32_e32 v2, v0
	v_mov_b32_e32 v3, v0
	v_mov_b32_e32 v6, v0
	v_mov_b32_e32 v7, v0
	v_mov_b32_e32 v8, v0
	v_mov_b32_e32 v9, v0
	v_mov_b32_e32 v10, v0
	v_mov_b32_e32 v11, v0
	v_mov_b32_e32 v12, v0
	v_mov_b32_e32 v13, v0
	v_mov_b32_e32 v14, v0
	v_mov_b32_e32 v15, v0
	v_mov_b32_e32 v16, v0
	v_mov_b32_e32 v17, v0
	v_mov_b32_e32 v18, v0
	v_mov_b32_e32 v19, v0
	v_mov_b32_e32 v20, v0
	v_mov_b32_e32 v21, v0
	v_mov_b32_e32 v22, v0
	v_mov_b32_e32 v23, v0
	v_mov_b32_e32 v24, v0
	v_mov_b32_e32 v25, v0
	v_mov_b32_e32 v26, v0
	v_mov_b32_e32 v27, v0
	v_mov_b32_e32 v28, v0
	v_mov_b32_e32 v29, v0
	v_mov_b32_e32 v30, v0
	v_mov_b32_e32 v31, v0
	v_mov_b32_e32 v32, v0
	v_mov_b32_e32 v33, v0
	v_mov_b32_e32 v66, v0
	v_mov_b32_e32 v67, v0
	v_mov_b32_e32 v68, v0
	v_mov_b32_e32 v69, v0
	v_mov_b32_e32 v70, v0
	v_mov_b32_e32 v71, v0
	v_mov_b32_e32 v72, v0
	v_mov_b32_e32 v73, v0
	v_mov_b32_e32 v74, v0
	v_mov_b32_e32 v75, v0
	v_mov_b32_e32 v76, v0
	v_mov_b32_e32 v77, v0
	v_mov_b32_e32 v78, v0
	v_mov_b32_e32 v79, v0
	v_mov_b32_e32 v80, v0
	v_mov_b32_e32 v81, v0
	v_mov_b32_e32 v82, v0
	v_mov_b32_e32 v83, v0
	v_mov_b32_e32 v84, v0
	v_mov_b32_e32 v85, v0
	v_mov_b32_e32 v86, v0
	v_mov_b32_e32 v87, v0
	v_mov_b32_e32 v88, v0
	v_mov_b32_e32 v89, v0
	v_mov_b32_e32 v90, v0
	v_mov_b32_e32 v91, v0
	v_mov_b32_e32 v92, v0
	v_mov_b32_e32 v93, v0
	v_mov_b32_e32 v94, v0
	v_mov_b32_e32 v95, v0
	v_mov_b32_e32 v96, v0
	v_mov_b32_e32 v97, v0
	v_mov_b32_e32 v34, v0
	v_mov_b32_e32 v35, v0
	v_mov_b32_e32 v36, v0
	v_mov_b32_e32 v37, v0
	v_mov_b32_e32 v38, v0
	v_mov_b32_e32 v39, v0
	v_mov_b32_e32 v40, v0
	v_mov_b32_e32 v41, v0
	v_mov_b32_e32 v42, v0
	v_mov_b32_e32 v43, v0
	v_mov_b32_e32 v44, v0
	v_mov_b32_e32 v45, v0
	v_mov_b32_e32 v46, v0
	v_mov_b32_e32 v47, v0
	v_mov_b32_e32 v48, v0
	v_mov_b32_e32 v49, v0
	v_mov_b32_e32 v50, v0
	v_mov_b32_e32 v51, v0
	v_mov_b32_e32 v52, v0
	v_mov_b32_e32 v53, v0
	v_mov_b32_e32 v54, v0
	v_mov_b32_e32 v55, v0
	v_mov_b32_e32 v56, v0
	v_mov_b32_e32 v57, v0
	v_mov_b32_e32 v58, v0
	v_mov_b32_e32 v59, v0
	v_mov_b32_e32 v60, v0
	v_mov_b32_e32 v61, v0
	v_mov_b32_e32 v62, v0
	v_mov_b32_e32 v63, v0
	v_mov_b32_e32 v64, v0
	v_mov_b32_e32 v65, v0
	v_mov_b32_e32 v98, v0
	v_mov_b32_e32 v99, v0
	v_mov_b32_e32 v100, v0
	v_mov_b32_e32 v101, v0
	v_mov_b32_e32 v102, v0
	v_mov_b32_e32 v103, v0
	v_mov_b32_e32 v104, v0
	v_mov_b32_e32 v105, v0
	v_mov_b32_e32 v106, v0
	v_mov_b32_e32 v107, v0
	v_mov_b32_e32 v108, v0
	v_mov_b32_e32 v109, v0
	v_mov_b32_e32 v110, v0
	v_mov_b32_e32 v111, v0
	v_mov_b32_e32 v112, v0
	v_mov_b32_e32 v113, v0
	v_mov_b32_e32 v114, v0
	v_mov_b32_e32 v115, v0
	v_mov_b32_e32 v116, v0
	v_mov_b32_e32 v117, v0
	v_mov_b32_e32 v118, v0
	v_mov_b32_e32 v119, v0
	v_mov_b32_e32 v120, v0
	v_mov_b32_e32 v121, v0
	v_mov_b32_e32 v122, v0
	v_mov_b32_e32 v123, v0
	v_mov_b32_e32 v124, v0
	v_mov_b32_e32 v125, v0
	v_mov_b32_e32 v126, v0
	v_mov_b32_e32 v127, v0
	v_mov_b32_e32 v128, v0
	v_mov_b32_e32 v129, v0
	s_cmp_eq_u32 s36, 1
	s_cbranch_scc1 .LBB0_852
	s_add_u32 s0, s22, 0xfff80080
	s_addc_u32 s1, s23, -1
	s_add_i32 s3, 0, 0x10000
	s_cmp_eq_u32 s28, 28
	s_cselect_b32 s15, s2, s1
	s_cselect_b32 s14, s8, s0
	v_add_u32_e32 v167, s3, v163
	s_cselect_b32 s1, s10, s25
	s_cselect_b32 s0, s24, s9
	s_add_i32 s6, 0, 0x14000
	ds_read_b128 v[140:143], v167
	ds_read_b128 v[144:147], v167 offset:1024
	ds_read_b128 v[148:151], v167 offset:2048
	ds_read_b128 v[172:175], v167 offset:3072
	v_add_u32_e32 v167, s6, v163
	ds_read_b128 v[190:193], v167
	ds_read_b128 v[194:197], v167 offset:1024
	ds_read_b128 v[198:201], v167 offset:2048
	ds_read_b128 v[202:205], v167 offset:3072
	v_lshl_add_u64 v[176:177], s[22:23], 0, v[136:137]
	s_add_i32 m0, s26, 0xc000
	ds_read_b128 v[206:209], v166
	ds_read_b128 v[210:213], v166 offset:1024
	ds_read_b128 v[214:217], v166 offset:2048
	ds_read_b128 v[218:221], v166 offset:3072
	ds_read_b128 v[222:225], v166 offset:4096
	ds_read_b128 v[226:229], v166 offset:5120
	ds_read_b128 v[230:233], v166 offset:6144
	ds_read_b128 v[234:237], v166 offset:7168
	global_load_lds_dwordx4 v[176:177], off
	s_add_i32 m0, s26, 0xe000
	v_lshl_add_u64 v[176:177], s[22:23], 0, v[138:139]
	global_load_lds_dwordx4 v[176:177], off
	s_waitcnt vmcnt(24)
	s_waitcnt lgkmcnt(0)
	s_barrier
	s_setprio 1
	s_waitcnt lgkmcnt(0)
	v_mfma_f32_16x16x32_bf16 v[126:129], v[140:143], v[206:209], v[126:129]
	v_mfma_f32_16x16x32_bf16 v[122:125], v[148:151], v[206:209], v[122:125]
	v_mfma_f32_16x16x32_bf16 v[118:121], v[140:143], v[214:217], v[118:121]
	v_mfma_f32_16x16x32_bf16 v[114:117], v[148:151], v[214:217], v[114:117]
	v_mfma_f32_16x16x32_bf16 v[110:113], v[140:143], v[222:225], v[110:113]
	v_mfma_f32_16x16x32_bf16 v[106:109], v[148:151], v[222:225], v[106:109]
	v_mfma_f32_16x16x32_bf16 v[102:105], v[140:143], v[230:233], v[102:105]
	v_mfma_f32_16x16x32_bf16 v[98:101], v[148:151], v[230:233], v[98:101]
	v_mfma_f32_16x16x32_bf16 v[126:129], v[144:147], v[210:213], v[126:129]
	v_mfma_f32_16x16x32_bf16 v[122:125], v[172:175], v[210:213], v[122:125]
	v_mfma_f32_16x16x32_bf16 v[118:121], v[144:147], v[218:221], v[118:121]
	v_mfma_f32_16x16x32_bf16 v[114:117], v[172:175], v[218:221], v[114:117]
	v_mfma_f32_16x16x32_bf16 v[110:113], v[144:147], v[226:229], v[110:113]
	v_mfma_f32_16x16x32_bf16 v[106:109], v[172:175], v[226:229], v[106:109]
	v_mfma_f32_16x16x32_bf16 v[102:105], v[144:147], v[234:237], v[102:105]
	v_mfma_f32_16x16x32_bf16 v[98:101], v[172:175], v[234:237], v[98:101]
	s_setprio 0
	s_setprio 1
	v_mfma_f32_16x16x32_bf16 v[62:65], v[190:193], v[206:209], v[62:65]
	v_mfma_f32_16x16x32_bf16 v[58:61], v[198:201], v[206:209], v[58:61]
	v_mfma_f32_16x16x32_bf16 v[54:57], v[190:193], v[214:217], v[54:57]
	v_mfma_f32_16x16x32_bf16 v[50:53], v[198:201], v[214:217], v[50:53]
	v_mfma_f32_16x16x32_bf16 v[46:49], v[190:193], v[222:225], v[46:49]
	v_mfma_f32_16x16x32_bf16 v[42:45], v[198:201], v[222:225], v[42:45]
	v_mfma_f32_16x16x32_bf16 v[38:41], v[190:193], v[230:233], v[38:41]
	v_mfma_f32_16x16x32_bf16 v[34:37], v[198:201], v[230:233], v[34:37]
	v_mfma_f32_16x16x32_bf16 v[62:65], v[194:197], v[210:213], v[62:65]
	v_mfma_f32_16x16x32_bf16 v[58:61], v[202:205], v[210:213], v[58:61]
	v_mfma_f32_16x16x32_bf16 v[54:57], v[194:197], v[218:221], v[54:57]
	v_mfma_f32_16x16x32_bf16 v[50:53], v[202:205], v[218:221], v[50:53]
	v_mfma_f32_16x16x32_bf16 v[46:49], v[194:197], v[226:229], v[46:49]
	v_mfma_f32_16x16x32_bf16 v[42:45], v[202:205], v[226:229], v[42:45]
	v_mfma_f32_16x16x32_bf16 v[38:41], v[194:197], v[234:237], v[38:41]
	v_mfma_f32_16x16x32_bf16 v[34:37], v[202:205], v[234:237], v[34:37]
	s_setprio 0
	s_barrier
	s_add_i32 s3, s3, s11
	v_lshl_add_u64 v[176:177], s[0:1], 0, v[4:5]
	s_mov_b32 m0, s3
	ds_read_b128 v[206:209], v166 offset:16384
	ds_read_b128 v[210:213], v166 offset:17408
	ds_read_b128 v[214:217], v166 offset:18432
	ds_read_b128 v[218:221], v166 offset:19456
	ds_read_b128 v[222:225], v166 offset:20480
	ds_read_b128 v[226:229], v166 offset:21504
	ds_read_b128 v[230:233], v166 offset:22528
	ds_read_b128 v[234:237], v166 offset:23552
	global_load_lds_dwordx4 v[176:177], off
	s_add_i32 m0, s3, 0x2000
	s_add_u32 s4, s0, 0x80000
	v_lshl_add_u64 v[238:239], s[0:1], 0, v[134:135]
	s_addc_u32 s5, s1, 0
	s_add_i32 s3, s6, s11
	global_load_lds_dwordx4 v[238:239], off
	v_lshl_add_u64 v[240:241], s[4:5], 0, v[4:5]
	s_mov_b32 m0, s3
	v_lshl_add_u64 v[242:243], s[14:15], 0, v[132:133]
	global_load_lds_dwordx4 v[240:241], off
	s_add_i32 m0, s3, 0x2000
	v_lshl_add_u64 v[240:241], s[4:5], 0, v[134:135]
	global_load_lds_dwordx4 v[240:241], off
	s_mov_b32 m0, s26
	v_lshl_add_u64 v[240:241], s[14:15], 0, v[130:131]
	global_load_lds_dwordx4 v[240:241], off
	s_mov_b32 m0, s27
	s_nop 0
	global_load_lds_dwordx4 v[242:243], off
	s_waitcnt vmcnt(24)
	s_waitcnt lgkmcnt(0)
	s_barrier
	s_setprio 1
	s_waitcnt lgkmcnt(0)
	v_mfma_f32_16x16x32_bf16 v[94:97], v[140:143], v[206:209], v[94:97]
	v_mfma_f32_16x16x32_bf16 v[90:93], v[148:151], v[206:209], v[90:93]
	v_mfma_f32_16x16x32_bf16 v[86:89], v[140:143], v[214:217], v[86:89]
	v_mfma_f32_16x16x32_bf16 v[82:85], v[148:151], v[214:217], v[82:85]
	v_mfma_f32_16x16x32_bf16 v[78:81], v[140:143], v[222:225], v[78:81]
	v_mfma_f32_16x16x32_bf16 v[74:77], v[148:151], v[222:225], v[74:77]
	v_mfma_f32_16x16x32_bf16 v[70:73], v[140:143], v[230:233], v[70:73]
	v_mfma_f32_16x16x32_bf16 v[66:69], v[148:151], v[230:233], v[66:69]
	v_mfma_f32_16x16x32_bf16 v[94:97], v[144:147], v[210:213], v[94:97]
	v_mfma_f32_16x16x32_bf16 v[90:93], v[172:175], v[210:213], v[90:93]
	v_mfma_f32_16x16x32_bf16 v[86:89], v[144:147], v[218:221], v[86:89]
	v_mfma_f32_16x16x32_bf16 v[82:85], v[172:175], v[218:221], v[82:85]
	v_mfma_f32_16x16x32_bf16 v[78:81], v[144:147], v[226:229], v[78:81]
	v_mfma_f32_16x16x32_bf16 v[74:77], v[172:175], v[226:229], v[74:77]
	v_mfma_f32_16x16x32_bf16 v[70:73], v[144:147], v[234:237], v[70:73]
	v_mfma_f32_16x16x32_bf16 v[66:69], v[172:175], v[234:237], v[66:69]
	s_setprio 0
	s_setprio 1
	v_mfma_f32_16x16x32_bf16 v[30:33], v[190:193], v[206:209], v[30:33]
	v_mfma_f32_16x16x32_bf16 v[26:29], v[198:201], v[206:209], v[26:29]
	v_mfma_f32_16x16x32_bf16 v[22:25], v[190:193], v[214:217], v[22:25]
	v_mfma_f32_16x16x32_bf16 v[18:21], v[198:201], v[214:217], v[18:21]
	v_mfma_f32_16x16x32_bf16 v[14:17], v[190:193], v[222:225], v[14:17]
	v_mfma_f32_16x16x32_bf16 v[10:13], v[198:201], v[222:225], v[10:13]
	v_mfma_f32_16x16x32_bf16 v[6:9], v[190:193], v[230:233], v[6:9]
	v_mfma_f32_16x16x32_bf16 v[0:3], v[198:201], v[230:233], v[0:3]
	v_mfma_f32_16x16x32_bf16 v[30:33], v[194:197], v[210:213], v[30:33]
	v_mfma_f32_16x16x32_bf16 v[26:29], v[202:205], v[210:213], v[26:29]
	v_mfma_f32_16x16x32_bf16 v[22:25], v[194:197], v[218:221], v[22:25]
	v_mfma_f32_16x16x32_bf16 v[18:21], v[202:205], v[218:221], v[18:21]
	v_mfma_f32_16x16x32_bf16 v[14:17], v[194:197], v[226:229], v[14:17]
	v_mfma_f32_16x16x32_bf16 v[10:13], v[202:205], v[226:229], v[10:13]
	v_mfma_f32_16x16x32_bf16 v[6:9], v[194:197], v[234:237], v[6:9]
	v_mfma_f32_16x16x32_bf16 v[0:3], v[202:205], v[234:237], v[0:3]
	s_setprio 0
	s_barrier
	s_branch .Lpeelmid_852
.LBB0_852:
	s_add_u32 s0, s22, 0xfff80080
	s_addc_u32 s1, s23, -1
	s_add_i32 s3, 0, 0x10000
	s_cmp_eq_u32 s28, 28
	s_cselect_b32 s15, s2, s1
	s_cselect_b32 s14, s8, s0
	v_add_u32_e32 v167, s3, v163
	s_cselect_b32 s1, s10, s25
	s_cselect_b32 s0, s24, s9
	s_add_i32 s6, 0, 0x14000
	ds_read_b128 v[140:143], v167
	ds_read_b128 v[144:147], v167 offset:1024
	ds_read_b128 v[148:151], v167 offset:2048
	ds_read_b128 v[172:175], v167 offset:3072
	v_add_u32_e32 v167, s6, v163
	ds_read_b128 v[190:193], v167
	ds_read_b128 v[194:197], v167 offset:1024
	ds_read_b128 v[198:201], v167 offset:2048
	ds_read_b128 v[202:205], v167 offset:3072
	v_lshl_add_u64 v[176:177], s[22:23], 0, v[136:137]
	s_add_i32 m0, s26, 0xc000
	ds_read_b128 v[206:209], v166
	ds_read_b128 v[210:213], v166 offset:1024
	ds_read_b128 v[214:217], v166 offset:2048
	ds_read_b128 v[218:221], v166 offset:3072
	ds_read_b128 v[222:225], v166 offset:4096
	ds_read_b128 v[226:229], v166 offset:5120
	ds_read_b128 v[230:233], v166 offset:6144
	ds_read_b128 v[234:237], v166 offset:7168
	global_load_lds_dwordx4 v[176:177], off
	s_add_i32 m0, s26, 0xe000
	v_lshl_add_u64 v[176:177], s[22:23], 0, v[138:139]
	global_load_lds_dwordx4 v[176:177], off
	s_waitcnt vmcnt(8)
	s_waitcnt lgkmcnt(0)
	s_barrier
	s_setprio 1
	s_waitcnt lgkmcnt(0)
	v_mfma_f32_16x16x32_bf16 v[126:129], v[140:143], v[206:209], v[126:129]
	v_mfma_f32_16x16x32_bf16 v[122:125], v[148:151], v[206:209], v[122:125]
	v_mfma_f32_16x16x32_bf16 v[118:121], v[140:143], v[214:217], v[118:121]
	v_mfma_f32_16x16x32_bf16 v[114:117], v[148:151], v[214:217], v[114:117]
	v_mfma_f32_16x16x32_bf16 v[110:113], v[140:143], v[222:225], v[110:113]
	v_mfma_f32_16x16x32_bf16 v[106:109], v[148:151], v[222:225], v[106:109]
	v_mfma_f32_16x16x32_bf16 v[102:105], v[140:143], v[230:233], v[102:105]
	v_mfma_f32_16x16x32_bf16 v[98:101], v[148:151], v[230:233], v[98:101]
	v_mfma_f32_16x16x32_bf16 v[126:129], v[144:147], v[210:213], v[126:129]
	v_mfma_f32_16x16x32_bf16 v[122:125], v[172:175], v[210:213], v[122:125]
	v_mfma_f32_16x16x32_bf16 v[118:121], v[144:147], v[218:221], v[118:121]
	v_mfma_f32_16x16x32_bf16 v[114:117], v[172:175], v[218:221], v[114:117]
	v_mfma_f32_16x16x32_bf16 v[110:113], v[144:147], v[226:229], v[110:113]
	v_mfma_f32_16x16x32_bf16 v[106:109], v[172:175], v[226:229], v[106:109]
	v_mfma_f32_16x16x32_bf16 v[102:105], v[144:147], v[234:237], v[102:105]
	v_mfma_f32_16x16x32_bf16 v[98:101], v[172:175], v[234:237], v[98:101]
	s_setprio 0
	s_setprio 1
	v_mfma_f32_16x16x32_bf16 v[62:65], v[190:193], v[206:209], v[62:65]
	v_mfma_f32_16x16x32_bf16 v[58:61], v[198:201], v[206:209], v[58:61]
	v_mfma_f32_16x16x32_bf16 v[54:57], v[190:193], v[214:217], v[54:57]
	v_mfma_f32_16x16x32_bf16 v[50:53], v[198:201], v[214:217], v[50:53]
	v_mfma_f32_16x16x32_bf16 v[46:49], v[190:193], v[222:225], v[46:49]
	v_mfma_f32_16x16x32_bf16 v[42:45], v[198:201], v[222:225], v[42:45]
	v_mfma_f32_16x16x32_bf16 v[38:41], v[190:193], v[230:233], v[38:41]
	v_mfma_f32_16x16x32_bf16 v[34:37], v[198:201], v[230:233], v[34:37]
	v_mfma_f32_16x16x32_bf16 v[62:65], v[194:197], v[210:213], v[62:65]
	v_mfma_f32_16x16x32_bf16 v[58:61], v[202:205], v[210:213], v[58:61]
	v_mfma_f32_16x16x32_bf16 v[54:57], v[194:197], v[218:221], v[54:57]
	v_mfma_f32_16x16x32_bf16 v[50:53], v[202:205], v[218:221], v[50:53]
	v_mfma_f32_16x16x32_bf16 v[46:49], v[194:197], v[226:229], v[46:49]
	v_mfma_f32_16x16x32_bf16 v[42:45], v[202:205], v[226:229], v[42:45]
	v_mfma_f32_16x16x32_bf16 v[38:41], v[194:197], v[234:237], v[38:41]
	v_mfma_f32_16x16x32_bf16 v[34:37], v[202:205], v[234:237], v[34:37]
	s_setprio 0
	s_barrier
	s_add_i32 s3, s3, s11
	v_lshl_add_u64 v[176:177], s[0:1], 0, v[4:5]
	s_mov_b32 m0, s3
	ds_read_b128 v[206:209], v166 offset:16384
	ds_read_b128 v[210:213], v166 offset:17408
	ds_read_b128 v[214:217], v166 offset:18432
	ds_read_b128 v[218:221], v166 offset:19456
	ds_read_b128 v[222:225], v166 offset:20480
	ds_read_b128 v[226:229], v166 offset:21504
	ds_read_b128 v[230:233], v166 offset:22528
	ds_read_b128 v[234:237], v166 offset:23552
	global_load_lds_dwordx4 v[176:177], off
	s_add_i32 m0, s3, 0x2000
	s_add_u32 s4, s0, 0x80000
	v_lshl_add_u64 v[238:239], s[0:1], 0, v[134:135]
	s_addc_u32 s5, s1, 0
	s_add_i32 s3, s6, s11
	global_load_lds_dwordx4 v[238:239], off
	v_lshl_add_u64 v[240:241], s[4:5], 0, v[4:5]
	s_mov_b32 m0, s3
	v_lshl_add_u64 v[242:243], s[14:15], 0, v[132:133]
	global_load_lds_dwordx4 v[240:241], off
	s_add_i32 m0, s3, 0x2000
	v_lshl_add_u64 v[240:241], s[4:5], 0, v[134:135]
	global_load_lds_dwordx4 v[240:241], off
	s_mov_b32 m0, s26
	v_lshl_add_u64 v[240:241], s[14:15], 0, v[130:131]
	global_load_lds_dwordx4 v[240:241], off
	s_mov_b32 m0, s27
	s_nop 0
	global_load_lds_dwordx4 v[242:243], off
	s_waitcnt vmcnt(8)
	s_waitcnt lgkmcnt(0)
	s_barrier
	s_setprio 1
	s_waitcnt lgkmcnt(0)
	v_mfma_f32_16x16x32_bf16 v[94:97], v[140:143], v[206:209], v[94:97]
	v_mfma_f32_16x16x32_bf16 v[90:93], v[148:151], v[206:209], v[90:93]
	v_mfma_f32_16x16x32_bf16 v[86:89], v[140:143], v[214:217], v[86:89]
	v_mfma_f32_16x16x32_bf16 v[82:85], v[148:151], v[214:217], v[82:85]
	v_mfma_f32_16x16x32_bf16 v[78:81], v[140:143], v[222:225], v[78:81]
	v_mfma_f32_16x16x32_bf16 v[74:77], v[148:151], v[222:225], v[74:77]
	v_mfma_f32_16x16x32_bf16 v[70:73], v[140:143], v[230:233], v[70:73]
	v_mfma_f32_16x16x32_bf16 v[66:69], v[148:151], v[230:233], v[66:69]
	v_mfma_f32_16x16x32_bf16 v[94:97], v[144:147], v[210:213], v[94:97]
	v_mfma_f32_16x16x32_bf16 v[90:93], v[172:175], v[210:213], v[90:93]
	v_mfma_f32_16x16x32_bf16 v[86:89], v[144:147], v[218:221], v[86:89]
	v_mfma_f32_16x16x32_bf16 v[82:85], v[172:175], v[218:221], v[82:85]
	v_mfma_f32_16x16x32_bf16 v[78:81], v[144:147], v[226:229], v[78:81]
	v_mfma_f32_16x16x32_bf16 v[74:77], v[172:175], v[226:229], v[74:77]
	v_mfma_f32_16x16x32_bf16 v[70:73], v[144:147], v[234:237], v[70:73]
	v_mfma_f32_16x16x32_bf16 v[66:69], v[172:175], v[234:237], v[66:69]
	s_setprio 0
	s_setprio 1
	v_mfma_f32_16x16x32_bf16 v[30:33], v[190:193], v[206:209], v[30:33]
	v_mfma_f32_16x16x32_bf16 v[26:29], v[198:201], v[206:209], v[26:29]
	v_mfma_f32_16x16x32_bf16 v[22:25], v[190:193], v[214:217], v[22:25]
	v_mfma_f32_16x16x32_bf16 v[18:21], v[198:201], v[214:217], v[18:21]
	v_mfma_f32_16x16x32_bf16 v[14:17], v[190:193], v[222:225], v[14:17]
	v_mfma_f32_16x16x32_bf16 v[10:13], v[198:201], v[222:225], v[10:13]
	v_mfma_f32_16x16x32_bf16 v[6:9], v[190:193], v[230:233], v[6:9]
	v_mfma_f32_16x16x32_bf16 v[0:3], v[198:201], v[230:233], v[0:3]
	v_mfma_f32_16x16x32_bf16 v[30:33], v[194:197], v[210:213], v[30:33]
	v_mfma_f32_16x16x32_bf16 v[26:29], v[202:205], v[210:213], v[26:29]
	v_mfma_f32_16x16x32_bf16 v[22:25], v[194:197], v[218:221], v[22:25]
	v_mfma_f32_16x16x32_bf16 v[18:21], v[202:205], v[218:221], v[18:21]
	v_mfma_f32_16x16x32_bf16 v[14:17], v[194:197], v[226:229], v[14:17]
	v_mfma_f32_16x16x32_bf16 v[10:13], v[202:205], v[226:229], v[10:13]
	v_mfma_f32_16x16x32_bf16 v[6:9], v[194:197], v[234:237], v[6:9]
	v_mfma_f32_16x16x32_bf16 v[0:3], v[202:205], v[234:237], v[0:3]
	s_setprio 0
	s_barrier
.Lpeelmid_852:
	s_add_i32 s3, 0, 0x18000
	v_add_u32_e32 v167, s3, v163
	s_add_i32 s6, 0, 0x1c000
	ds_read_b128 v[140:143], v167
	ds_read_b128 v[144:147], v167 offset:1024
	ds_read_b128 v[148:151], v167 offset:2048
	ds_read_b128 v[172:175], v167 offset:3072
	v_add_u32_e32 v167, s6, v163
	ds_read_b128 v[190:193], v167
	ds_read_b128 v[194:197], v167 offset:1024
	ds_read_b128 v[198:201], v167 offset:2048
	ds_read_b128 v[202:205], v167 offset:3072
	s_add_u32 s4, s14, 0x80000
	s_addc_u32 s5, s15, 0
	s_mov_b32 m0, s30
	v_lshl_add_u64 v[244:245], s[4:5], 0, v[130:131]
	ds_read_b128 v[206:209], v166 offset:32768
	ds_read_b128 v[210:213], v166 offset:33792
	ds_read_b128 v[214:217], v166 offset:34816
	ds_read_b128 v[218:221], v166 offset:35840
	ds_read_b128 v[222:225], v166 offset:36864
	ds_read_b128 v[226:229], v166 offset:37888
	ds_read_b128 v[230:233], v166 offset:38912
	ds_read_b128 v[234:237], v166 offset:39936
	global_load_lds_dwordx4 v[244:245], off
	s_mov_b32 m0, s31
	v_lshl_add_u64 v[244:245], s[4:5], 0, v[132:133]
	global_load_lds_dwordx4 v[244:245], off
	s_waitcnt vmcnt(8)
	s_waitcnt lgkmcnt(0)
	s_barrier
	s_setprio 1
	s_waitcnt lgkmcnt(0)
	v_mfma_f32_16x16x32_bf16 v[126:129], v[140:143], v[206:209], v[126:129]
	v_mfma_f32_16x16x32_bf16 v[122:125], v[148:151], v[206:209], v[122:125]
	v_mfma_f32_16x16x32_bf16 v[118:121], v[140:143], v[214:217], v[118:121]
	v_mfma_f32_16x16x32_bf16 v[114:117], v[148:151], v[214:217], v[114:117]
	v_mfma_f32_16x16x32_bf16 v[110:113], v[140:143], v[222:225], v[110:113]
	v_mfma_f32_16x16x32_bf16 v[106:109], v[148:151], v[222:225], v[106:109]
	v_mfma_f32_16x16x32_bf16 v[102:105], v[140:143], v[230:233], v[102:105]
	v_mfma_f32_16x16x32_bf16 v[98:101], v[148:151], v[230:233], v[98:101]
	v_mfma_f32_16x16x32_bf16 v[126:129], v[144:147], v[210:213], v[126:129]
	v_mfma_f32_16x16x32_bf16 v[122:125], v[172:175], v[210:213], v[122:125]
	v_mfma_f32_16x16x32_bf16 v[118:121], v[144:147], v[218:221], v[118:121]
	v_mfma_f32_16x16x32_bf16 v[114:117], v[172:175], v[218:221], v[114:117]
	v_mfma_f32_16x16x32_bf16 v[110:113], v[144:147], v[226:229], v[110:113]
	v_mfma_f32_16x16x32_bf16 v[106:109], v[172:175], v[226:229], v[106:109]
	v_mfma_f32_16x16x32_bf16 v[102:105], v[144:147], v[234:237], v[102:105]
	v_mfma_f32_16x16x32_bf16 v[98:101], v[172:175], v[234:237], v[98:101]
	s_setprio 0
	s_setprio 1
	v_mfma_f32_16x16x32_bf16 v[62:65], v[190:193], v[206:209], v[62:65]
	v_mfma_f32_16x16x32_bf16 v[58:61], v[198:201], v[206:209], v[58:61]
	v_mfma_f32_16x16x32_bf16 v[54:57], v[190:193], v[214:217], v[54:57]
	v_mfma_f32_16x16x32_bf16 v[50:53], v[198:201], v[214:217], v[50:53]
	v_mfma_f32_16x16x32_bf16 v[46:49], v[190:193], v[222:225], v[46:49]
	v_mfma_f32_16x16x32_bf16 v[42:45], v[198:201], v[222:225], v[42:45]
	v_mfma_f32_16x16x32_bf16 v[38:41], v[190:193], v[230:233], v[38:41]
	v_mfma_f32_16x16x32_bf16 v[34:37], v[198:201], v[230:233], v[34:37]
	v_mfma_f32_16x16x32_bf16 v[62:65], v[194:197], v[210:213], v[62:65]
	v_mfma_f32_16x16x32_bf16 v[58:61], v[202:205], v[210:213], v[58:61]
	v_mfma_f32_16x16x32_bf16 v[54:57], v[194:197], v[218:221], v[54:57]
	v_mfma_f32_16x16x32_bf16 v[50:53], v[202:205], v[218:221], v[50:53]
	v_mfma_f32_16x16x32_bf16 v[46:49], v[194:197], v[226:229], v[46:49]
	v_mfma_f32_16x16x32_bf16 v[42:45], v[202:205], v[226:229], v[42:45]
	v_mfma_f32_16x16x32_bf16 v[38:41], v[194:197], v[234:237], v[38:41]
	v_mfma_f32_16x16x32_bf16 v[34:37], v[202:205], v[234:237], v[34:37]
	s_setprio 0
	s_barrier
	s_add_i32 s3, s3, s11
	v_lshl_add_u64 v[176:177], v[176:177], 0, s[70:71]
	s_mov_b32 m0, s3
	ds_read_b128 v[206:209], v166 offset:49152
	ds_read_b128 v[210:213], v166 offset:50176
	ds_read_b128 v[214:217], v166 offset:51200
	ds_read_b128 v[218:221], v166 offset:52224
	ds_read_b128 v[222:225], v166 offset:53248
	ds_read_b128 v[226:229], v166 offset:54272
	ds_read_b128 v[230:233], v166 offset:55296
	ds_read_b128 v[234:237], v166 offset:56320
	global_load_lds_dwordx4 v[176:177], off
	s_add_i32 m0, s3, 0x2000
	s_add_u32 s0, s0, 0x80080
	v_lshl_add_u64 v[176:177], v[238:239], 0, s[70:71]
	s_addc_u32 s1, s1, 0
	s_add_i32 s3, s6, s11
	global_load_lds_dwordx4 v[176:177], off
	s_mov_b32 m0, s3
	v_lshl_add_u64 v[176:177], s[0:1], 0, v[4:5]
	global_load_lds_dwordx4 v[176:177], off
	s_add_i32 m0, s3, 0x2000
	v_lshl_add_u64 v[176:177], s[0:1], 0, v[134:135]
	global_load_lds_dwordx4 v[176:177], off
	s_mov_b32 m0, s34
	v_lshl_add_u64 v[176:177], v[240:241], 0, s[70:71]
	global_load_lds_dwordx4 v[176:177], off
	s_mov_b32 m0, s35
	v_lshl_add_u64 v[176:177], v[242:243], 0, s[70:71]
	global_load_lds_dwordx4 v[176:177], off
	s_waitcnt vmcnt(8)
	s_waitcnt lgkmcnt(0)
	s_barrier
	s_setprio 1
	s_waitcnt lgkmcnt(0)
	v_mfma_f32_16x16x32_bf16 v[94:97], v[140:143], v[206:209], v[94:97]
	v_mfma_f32_16x16x32_bf16 v[90:93], v[148:151], v[206:209], v[90:93]
	v_mfma_f32_16x16x32_bf16 v[86:89], v[140:143], v[214:217], v[86:89]
	v_mfma_f32_16x16x32_bf16 v[82:85], v[148:151], v[214:217], v[82:85]
	v_mfma_f32_16x16x32_bf16 v[78:81], v[140:143], v[222:225], v[78:81]
	v_mfma_f32_16x16x32_bf16 v[74:77], v[148:151], v[222:225], v[74:77]
	v_mfma_f32_16x16x32_bf16 v[70:73], v[140:143], v[230:233], v[70:73]
	v_mfma_f32_16x16x32_bf16 v[66:69], v[148:151], v[230:233], v[66:69]
	v_mfma_f32_16x16x32_bf16 v[94:97], v[144:147], v[210:213], v[94:97]
	v_mfma_f32_16x16x32_bf16 v[90:93], v[172:175], v[210:213], v[90:93]
	v_mfma_f32_16x16x32_bf16 v[86:89], v[144:147], v[218:221], v[86:89]
	v_mfma_f32_16x16x32_bf16 v[82:85], v[172:175], v[218:221], v[82:85]
	v_mfma_f32_16x16x32_bf16 v[78:81], v[144:147], v[226:229], v[78:81]
	v_mfma_f32_16x16x32_bf16 v[74:77], v[172:175], v[226:229], v[74:77]
	v_mfma_f32_16x16x32_bf16 v[70:73], v[144:147], v[234:237], v[70:73]
	v_mfma_f32_16x16x32_bf16 v[66:69], v[172:175], v[234:237], v[66:69]
	s_setprio 0
	s_setprio 1
	v_mfma_f32_16x16x32_bf16 v[30:33], v[190:193], v[206:209], v[30:33]
	v_mfma_f32_16x16x32_bf16 v[26:29], v[198:201], v[206:209], v[26:29]
	v_mfma_f32_16x16x32_bf16 v[22:25], v[190:193], v[214:217], v[22:25]
	v_mfma_f32_16x16x32_bf16 v[18:21], v[198:201], v[214:217], v[18:21]
	v_mfma_f32_16x16x32_bf16 v[14:17], v[190:193], v[222:225], v[14:17]
	v_mfma_f32_16x16x32_bf16 v[10:13], v[198:201], v[222:225], v[10:13]
	v_mfma_f32_16x16x32_bf16 v[6:9], v[190:193], v[230:233], v[6:9]
	v_mfma_f32_16x16x32_bf16 v[0:3], v[198:201], v[230:233], v[0:3]
	v_mfma_f32_16x16x32_bf16 v[30:33], v[194:197], v[210:213], v[30:33]
	v_mfma_f32_16x16x32_bf16 v[26:29], v[202:205], v[210:213], v[26:29]
	v_mfma_f32_16x16x32_bf16 v[22:25], v[194:197], v[218:221], v[22:25]
	v_mfma_f32_16x16x32_bf16 v[18:21], v[202:205], v[218:221], v[18:21]
	v_mfma_f32_16x16x32_bf16 v[14:17], v[194:197], v[226:229], v[14:17]
	v_mfma_f32_16x16x32_bf16 v[10:13], v[202:205], v[226:229], v[10:13]
	v_mfma_f32_16x16x32_bf16 v[6:9], v[194:197], v[234:237], v[6:9]
	v_mfma_f32_16x16x32_bf16 v[0:3], v[202:205], v[234:237], v[0:3]
	s_setprio 0
	s_barrier
	s_add_i32 s28, s28, 2
	s_add_u32 s22, s22, 0x100
	s_addc_u32 s23, s23, 0
	s_add_u32 s9, s9, 0x100
	s_addc_u32 s25, s25, 0
	s_cmp_gt_u32 s28, 29
	s_cbranch_scc0 .LBB0_852
	s_and_b64 vcc, exec, s[48:49]
	s_cbranch_vccz .LBB0_855
	s_barrier
